# K-loops: trailing s_barrier moved directly after each MFMA burst (ALU/setprio after it), setprio 1 before the pre-burst barrier, duplicate waits removed (all 64 bursts)
# speedup vs baseline: 1.0129x; 1.0129x over previous
.LBB0_124:
	s_ashr_i32 s79, s78, 31
	s_lshl_b64 s[10:11], s[78:79], 19
	s_add_u32 s80, s54, s10
	v_cmp_lt_i64_e32 vcc, s[72:73], v[178:179]
	s_addc_u32 s81, s55, s11
	s_and_b64 s[10:11], vcc, exec
	s_cselect_b32 s1, s81, s87
	s_cselect_b32 s10, s80, s86
	s_ashr_i32 s77, s76, 31
	s_lshl_b64 s[36:37], s[76:77], 19
	s_add_u32 s72, s66, s36
	s_addc_u32 s73, s59, s37
	s_and_b64 s[36:37], vcc, exec
	s_cselect_b32 s11, s73, s83
	s_cselect_b32 s25, s72, s82
	s_add_u32 s86, s86, 0x40080
	s_addc_u32 s87, s87, 0
	s_add_u32 s33, s82, 0x100
	s_addc_u32 s36, s83, 0
	s_mov_b32 s37, -2
	s_add_u32 s27, s86, 0xfffc0080
	s_addc_u32 s56, s87, -1
	s_add_i32 s57, 0, 0x10000
	v_add_u32_e32 v76, s57, v217
	ds_read_b128 v[64:67], v76
	ds_read_b128 v[68:71], v76 offset:1024
	ds_read_b128 v[72:75], v76 offset:2048
	ds_read_b128 v[76:79], v76 offset:3072
	s_cmp_eq_u32 s37, 12
	s_cselect_b32 vcc_hi, s1, s56
	s_cselect_b32 vcc_lo, s10, s27
	s_cselect_b32 s83, s11, s36
	s_cselect_b32 s82, s25, s33
	v_lshl_add_u64 v[168:169], s[86:87], 0, v[164:165]
	s_add_i32 m0, s75, 0xc000
	ds_read_b128 v[80:83], v220
	ds_read_b128 v[84:87], v220 offset:1024
	ds_read_b128 v[88:91], v220 offset:2048
	ds_read_b128 v[92:95], v220 offset:3072
	ds_read_b128 v[188:191], v220 offset:4096
	ds_read_b128 v[192:195], v220 offset:5120
	ds_read_b128 v[196:199], v220 offset:6144
	ds_read_b128 v[200:203], v220 offset:7168
	global_load_lds_dwordx4 v[168:169], off
	v_lshl_add_u64 v[168:169], s[86:87], 0, v[166:167]
	s_add_i32 m0, s75, 0xe000
	s_nop 0
	global_load_lds_dwordx4 v[168:169], off
	s_waitcnt lgkmcnt(8)
	s_setprio 1
	s_barrier
	s_waitcnt lgkmcnt(0)
	v_mfma_f32_16x16x32_bf16 v[146:149], v[64:67], v[80:83], 0
	v_mfma_f32_16x16x32_bf16 v[116:119], v[72:75], v[80:83], 0
	v_mfma_f32_16x16x32_bf16 v[158:161], v[64:67], v[88:91], 0
	v_mfma_f32_16x16x32_bf16 v[124:127], v[72:75], v[88:91], 0
	v_mfma_f32_16x16x32_bf16 v[154:157], v[64:67], v[188:191], 0
	v_mfma_f32_16x16x32_bf16 v[112:115], v[72:75], v[188:191], 0
	v_mfma_f32_16x16x32_bf16 v[150:153], v[64:67], v[196:199], 0
	v_mfma_f32_16x16x32_bf16 v[120:123], v[72:75], v[196:199], 0
	v_mfma_f32_16x16x32_bf16 v[146:149], v[68:71], v[84:87], v[146:149]
	v_mfma_f32_16x16x32_bf16 v[116:119], v[76:79], v[84:87], v[116:119]
	v_mfma_f32_16x16x32_bf16 v[158:161], v[68:71], v[92:95], v[158:161]
	v_mfma_f32_16x16x32_bf16 v[124:127], v[76:79], v[92:95], v[124:127]
	v_mfma_f32_16x16x32_bf16 v[154:157], v[68:71], v[192:195], v[154:157]
	v_mfma_f32_16x16x32_bf16 v[112:115], v[76:79], v[192:195], v[112:115]
	v_mfma_f32_16x16x32_bf16 v[150:153], v[68:71], v[200:203], v[150:153]
	v_mfma_f32_16x16x32_bf16 v[120:123], v[76:79], v[200:203], v[120:123]
	s_barrier
	s_setprio 0
	s_add_i32 s27, 0, 0x14000
	v_add_u32_e32 v168, s27, v217
	s_add_i32 s56, s57, s74
	ds_read_b128 v[204:207], v168
	ds_read_b128 v[222:225], v168 offset:1024
	ds_read_b128 v[228:231], v168 offset:2048
	ds_read_b128 v[232:235], v168 offset:3072
	v_lshl_add_u64 v[168:169], s[82:83], 0, v[144:145]
	s_mov_b32 m0, s56
	v_lshl_add_u64 v[176:177], s[82:83], 0, v[162:163]
	global_load_lds_dwordx4 v[168:169], off
	s_add_i32 m0, s56, 0x2000
	s_nop 0
	global_load_lds_dwordx4 v[176:177], off
	s_setprio 1
	s_barrier
	s_waitcnt lgkmcnt(0)
	v_mfma_f32_16x16x32_bf16 v[140:143], v[204:207], v[80:83], 0
	v_mfma_f32_16x16x32_bf16 v[80:83], v[228:231], v[80:83], 0
	v_mfma_f32_16x16x32_bf16 v[140:143], v[222:225], v[84:87], v[140:143]
	v_mfma_f32_16x16x32_bf16 v[80:83], v[232:235], v[84:87], v[80:83]
	v_mfma_f32_16x16x32_bf16 v[84:87], v[204:207], v[88:91], 0
	v_mfma_f32_16x16x32_bf16 v[88:91], v[228:231], v[88:91], 0
	v_mfma_f32_16x16x32_bf16 v[100:103], v[228:231], v[188:191], 0
	v_mfma_f32_16x16x32_bf16 v[104:107], v[204:207], v[196:199], 0
	v_mfma_f32_16x16x32_bf16 v[96:99], v[228:231], v[196:199], 0
	v_mfma_f32_16x16x32_bf16 v[84:87], v[222:225], v[92:95], v[84:87]
	v_mfma_f32_16x16x32_bf16 v[88:91], v[232:235], v[92:95], v[88:91]
	v_mfma_f32_16x16x32_bf16 v[92:95], v[204:207], v[188:191], 0
	v_mfma_f32_16x16x32_bf16 v[100:103], v[232:235], v[192:195], v[100:103]
	v_mfma_f32_16x16x32_bf16 v[128:131], v[222:225], v[200:203], v[104:107]
	v_mfma_f32_16x16x32_bf16 v[96:99], v[232:235], v[200:203], v[96:99]
	v_mfma_f32_16x16x32_bf16 v[92:95], v[222:225], v[192:195], v[92:95]
	s_barrier
	s_setprio 0
	s_mov_b32 m0, s75
	v_lshl_add_u64 v[240:241], vcc, 0, v[144:145]
	ds_read_b128 v[104:107], v220 offset:16384
	ds_read_b128 v[108:111], v220 offset:17408
	ds_read_b128 v[132:135], v220 offset:18432
	ds_read_b128 v[136:139], v220 offset:19456
	ds_read_b128 v[188:191], v220 offset:20480
	ds_read_b128 v[192:195], v220 offset:21504
	ds_read_b128 v[196:199], v220 offset:22528
	ds_read_b128 v[200:203], v220 offset:23552
	global_load_lds_dwordx4 v[240:241], off
	v_lshl_add_u64 v[242:243], vcc, 0, v[162:163]
	s_mov_b32 m0, s85
	s_nop 0
	global_load_lds_dwordx4 v[242:243], off
	s_setprio 1
	s_barrier
	s_waitcnt lgkmcnt(0)
	v_mfma_f32_16x16x32_bf16 v[48:51], v[64:67], v[104:107], 0
	v_mfma_f32_16x16x32_bf16 v[20:23], v[72:75], v[104:107], 0
	v_mfma_f32_16x16x32_bf16 v[60:63], v[64:67], v[132:135], 0
	v_mfma_f32_16x16x32_bf16 v[28:31], v[72:75], v[132:135], 0
	v_mfma_f32_16x16x32_bf16 v[56:59], v[64:67], v[188:191], 0
	v_mfma_f32_16x16x32_bf16 v[16:19], v[72:75], v[188:191], 0
	v_mfma_f32_16x16x32_bf16 v[52:55], v[64:67], v[196:199], 0
	v_mfma_f32_16x16x32_bf16 v[24:27], v[72:75], v[196:199], 0
	v_mfma_f32_16x16x32_bf16 v[48:51], v[68:71], v[108:111], v[48:51]
	v_mfma_f32_16x16x32_bf16 v[20:23], v[76:79], v[108:111], v[20:23]
	v_mfma_f32_16x16x32_bf16 v[60:63], v[68:71], v[136:139], v[60:63]
	v_mfma_f32_16x16x32_bf16 v[28:31], v[76:79], v[136:139], v[28:31]
	v_mfma_f32_16x16x32_bf16 v[56:59], v[68:71], v[192:195], v[56:59]
	v_mfma_f32_16x16x32_bf16 v[16:19], v[76:79], v[192:195], v[16:19]
	v_mfma_f32_16x16x32_bf16 v[52:55], v[68:71], v[200:203], v[52:55]
	v_mfma_f32_16x16x32_bf16 v[24:27], v[76:79], v[200:203], v[24:27]
	s_barrier
	s_setprio 0
	s_add_u32 s56, s82, 0x40000
	s_addc_u32 s57, s83, 0
	s_add_i32 s27, s27, s74
	v_lshl_add_u64 v[64:65], s[56:57], 0, v[144:145]
	s_mov_b32 m0, s27
	s_nop 0
	global_load_lds_dwordx4 v[64:65], off
	v_lshl_add_u64 v[64:65], s[56:57], 0, v[162:163]
	s_add_i32 m0, s27, 0x2000
	s_nop 0
	global_load_lds_dwordx4 v[64:65], off
	s_waitcnt vmcnt(6)
	s_setprio 1
	s_barrier
	v_mfma_f32_16x16x32_bf16 v[44:47], v[204:207], v[104:107], 0
	v_mfma_f32_16x16x32_bf16 v[12:15], v[228:231], v[104:107], 0
	v_mfma_f32_16x16x32_bf16 v[40:43], v[204:207], v[132:135], 0
	v_mfma_f32_16x16x32_bf16 v[8:11], v[228:231], v[132:135], 0
	v_mfma_f32_16x16x32_bf16 v[36:39], v[204:207], v[188:191], 0
	v_mfma_f32_16x16x32_bf16 v[4:7], v[228:231], v[188:191], 0
	v_mfma_f32_16x16x32_bf16 v[32:35], v[204:207], v[196:199], 0
	v_mfma_f32_16x16x32_bf16 v[0:3], v[228:231], v[196:199], 0
	v_mfma_f32_16x16x32_bf16 v[44:47], v[222:225], v[108:111], v[44:47]
	v_mfma_f32_16x16x32_bf16 v[12:15], v[232:235], v[108:111], v[12:15]
	v_mfma_f32_16x16x32_bf16 v[40:43], v[222:225], v[136:139], v[40:43]
	v_mfma_f32_16x16x32_bf16 v[8:11], v[232:235], v[136:139], v[8:11]
	v_mfma_f32_16x16x32_bf16 v[36:39], v[222:225], v[192:195], v[36:39]
	v_mfma_f32_16x16x32_bf16 v[4:7], v[232:235], v[192:195], v[4:7]
	v_mfma_f32_16x16x32_bf16 v[32:35], v[222:225], v[200:203], v[32:35]
	v_mfma_f32_16x16x32_bf16 v[0:3], v[232:235], v[200:203], v[0:3]
	s_barrier
	s_setprio 0
	s_add_i32 s27, 0, 0x18000
	v_add_u32_e32 v76, s27, v217
	ds_read_b128 v[64:67], v76
	ds_read_b128 v[68:71], v76 offset:1024
	ds_read_b128 v[72:75], v76 offset:2048
	ds_read_b128 v[76:79], v76 offset:3072
	s_add_u32 s56, vcc_lo, 0x40000
	s_addc_u32 s57, vcc_hi, 0
	s_mov_b32 m0, s98
	v_lshl_add_u64 v[136:137], s[56:57], 0, v[144:145]
	ds_read_b128 v[104:107], v220 offset:32768
	ds_read_b128 v[108:111], v220 offset:33792
	ds_read_b128 v[132:135], v220 offset:34816
	ds_read_b128 v[188:191], v220 offset:35840
	ds_read_b128 v[192:195], v220 offset:36864
	ds_read_b128 v[196:199], v220 offset:37888
	ds_read_b128 v[200:203], v220 offset:38912
	ds_read_b128 v[204:207], v220 offset:39936
	global_load_lds_dwordx4 v[136:137], off
	v_lshl_add_u64 v[136:137], s[56:57], 0, v[162:163]
	s_mov_b32 m0, s29
	s_nop 0
	global_load_lds_dwordx4 v[136:137], off
	s_waitcnt lgkmcnt(8)
	s_setprio 1
	s_barrier
	s_waitcnt lgkmcnt(0)
	v_mfma_f32_16x16x32_bf16 v[136:139], v[64:67], v[104:107], v[146:149]
	v_mfma_f32_16x16x32_bf16 v[146:149], v[68:71], v[108:111], v[136:139]
	v_mfma_f32_16x16x32_bf16 v[136:139], v[64:67], v[132:135], v[158:161]
	v_mfma_f32_16x16x32_bf16 v[158:161], v[68:71], v[188:191], v[136:139]
	v_mfma_f32_16x16x32_bf16 v[136:139], v[64:67], v[192:195], v[154:157]
	v_mfma_f32_16x16x32_bf16 v[116:119], v[72:75], v[104:107], v[116:119]
	v_mfma_f32_16x16x32_bf16 v[124:127], v[72:75], v[132:135], v[124:127]
	v_mfma_f32_16x16x32_bf16 v[154:157], v[68:71], v[196:199], v[136:139]
	v_mfma_f32_16x16x32_bf16 v[112:115], v[72:75], v[192:195], v[112:115]
	v_mfma_f32_16x16x32_bf16 v[136:139], v[64:67], v[200:203], v[150:153]
	v_mfma_f32_16x16x32_bf16 v[120:123], v[72:75], v[200:203], v[120:123]
	v_mfma_f32_16x16x32_bf16 v[116:119], v[76:79], v[108:111], v[116:119]
	v_mfma_f32_16x16x32_bf16 v[124:127], v[76:79], v[188:191], v[124:127]
	v_mfma_f32_16x16x32_bf16 v[112:115], v[76:79], v[196:199], v[112:115]
	v_mfma_f32_16x16x32_bf16 v[150:153], v[68:71], v[204:207], v[136:139]
	v_mfma_f32_16x16x32_bf16 v[120:123], v[76:79], v[204:207], v[120:123]
	s_barrier
	s_setprio 0
	s_add_i32 s58, 0, 0x1c000
	v_add_u32_e32 v136, s58, v217
	s_add_i32 s27, s27, s74
	ds_read_b128 v[222:225], v136
	ds_read_b128 v[228:231], v136 offset:1024
	ds_read_b128 v[232:235], v136 offset:2048
	ds_read_b128 v[236:239], v136 offset:3072
	v_lshl_add_u64 v[136:137], v[168:169], 0, s[18:19]
	s_mov_b32 m0, s27
	s_nop 0
	global_load_lds_dwordx4 v[136:137], off
	v_lshl_add_u64 v[136:137], v[176:177], 0, s[18:19]
	s_add_i32 m0, s27, 0x2000
	s_nop 0
	global_load_lds_dwordx4 v[136:137], off
	s_setprio 1
	s_barrier
	s_waitcnt lgkmcnt(0)
	v_mfma_f32_16x16x32_bf16 v[136:139], v[222:225], v[104:107], v[140:143]
	v_mfma_f32_16x16x32_bf16 v[80:83], v[232:235], v[104:107], v[80:83]
	v_mfma_f32_16x16x32_bf16 v[140:143], v[228:231], v[108:111], v[136:139]
	v_mfma_f32_16x16x32_bf16 v[108:111], v[236:239], v[108:111], v[80:83]
	v_mfma_f32_16x16x32_bf16 v[80:83], v[222:225], v[132:135], v[84:87]
	v_mfma_f32_16x16x32_bf16 v[136:139], v[228:231], v[188:191], v[80:83]
	v_mfma_f32_16x16x32_bf16 v[80:83], v[232:235], v[132:135], v[88:91]
	v_mfma_f32_16x16x32_bf16 v[104:107], v[236:239], v[188:191], v[80:83]
	v_mfma_f32_16x16x32_bf16 v[80:83], v[222:225], v[192:195], v[92:95]
	v_mfma_f32_16x16x32_bf16 v[132:135], v[228:231], v[196:199], v[80:83]
	v_mfma_f32_16x16x32_bf16 v[80:83], v[232:235], v[192:195], v[100:103]
	v_mfma_f32_16x16x32_bf16 v[100:103], v[236:239], v[196:199], v[80:83]
	v_mfma_f32_16x16x32_bf16 v[80:83], v[222:225], v[200:203], v[128:131]
	v_mfma_f32_16x16x32_bf16 v[128:131], v[228:231], v[204:207], v[80:83]
	v_mfma_f32_16x16x32_bf16 v[80:83], v[232:235], v[200:203], v[96:99]
	v_mfma_f32_16x16x32_bf16 v[96:99], v[236:239], v[204:207], v[80:83]
	s_barrier
	s_setprio 0
	s_mov_b32 m0, s31
	v_lshl_add_u64 v[168:169], v[240:241], 0, s[18:19]
	s_nop 2
	ds_read_b128 v[80:83], v220 offset:49152
	ds_read_b128 v[84:87], v220 offset:50176
	ds_read_b128 v[88:91], v220 offset:51200
	ds_read_b128 v[92:95], v220 offset:52224
	ds_read_b128 v[188:191], v220 offset:53248
	ds_read_b128 v[192:195], v220 offset:54272
	ds_read_b128 v[196:199], v220 offset:55296
	ds_read_b128 v[200:203], v220 offset:56320
	global_load_lds_dwordx4 v[168:169], off
	v_lshl_add_u64 v[168:169], v[242:243], 0, s[18:19]
	s_mov_b32 m0, s34
	s_nop 0
	global_load_lds_dwordx4 v[168:169], off
	s_setprio 1
	s_barrier
	s_waitcnt lgkmcnt(0)
	v_mfma_f32_16x16x32_bf16 v[48:51], v[64:67], v[80:83], v[48:51]
	v_mfma_f32_16x16x32_bf16 v[20:23], v[72:75], v[80:83], v[20:23]
	v_mfma_f32_16x16x32_bf16 v[60:63], v[64:67], v[88:91], v[60:63]
	v_mfma_f32_16x16x32_bf16 v[28:31], v[72:75], v[88:91], v[28:31]
	v_mfma_f32_16x16x32_bf16 v[56:59], v[64:67], v[188:191], v[56:59]
	v_mfma_f32_16x16x32_bf16 v[16:19], v[72:75], v[188:191], v[16:19]
	v_mfma_f32_16x16x32_bf16 v[52:55], v[64:67], v[196:199], v[52:55]
	v_mfma_f32_16x16x32_bf16 v[24:27], v[72:75], v[196:199], v[24:27]
	v_mfma_f32_16x16x32_bf16 v[48:51], v[68:71], v[84:87], v[48:51]
	v_mfma_f32_16x16x32_bf16 v[20:23], v[76:79], v[84:87], v[20:23]
	v_mfma_f32_16x16x32_bf16 v[60:63], v[68:71], v[92:95], v[60:63]
	v_mfma_f32_16x16x32_bf16 v[28:31], v[76:79], v[92:95], v[28:31]
	v_mfma_f32_16x16x32_bf16 v[56:59], v[68:71], v[192:195], v[56:59]
	v_mfma_f32_16x16x32_bf16 v[16:19], v[76:79], v[192:195], v[16:19]
	v_mfma_f32_16x16x32_bf16 v[52:55], v[68:71], v[200:203], v[52:55]
	v_mfma_f32_16x16x32_bf16 v[24:27], v[76:79], v[200:203], v[24:27]
	s_barrier
	s_setprio 0
	s_add_u32 s56, s82, 0x40080
	s_addc_u32 s57, s83, 0
	s_add_i32 s27, s58, s74
	v_lshl_add_u64 v[64:65], s[56:57], 0, v[144:145]
	s_mov_b32 m0, s27
	s_nop 0
	global_load_lds_dwordx4 v[64:65], off
	v_lshl_add_u64 v[64:65], s[56:57], 0, v[162:163]
	s_add_i32 m0, s27, 0x2000
	s_nop 0
	global_load_lds_dwordx4 v[64:65], off
	s_waitcnt vmcnt(6)
	s_setprio 1
	s_barrier
	v_mfma_f32_16x16x32_bf16 v[44:47], v[222:225], v[80:83], v[44:47]
	v_mfma_f32_16x16x32_bf16 v[12:15], v[232:235], v[80:83], v[12:15]
	v_mfma_f32_16x16x32_bf16 v[40:43], v[222:225], v[88:91], v[40:43]
	v_mfma_f32_16x16x32_bf16 v[8:11], v[232:235], v[88:91], v[8:11]
	v_mfma_f32_16x16x32_bf16 v[36:39], v[222:225], v[188:191], v[36:39]
	v_mfma_f32_16x16x32_bf16 v[4:7], v[232:235], v[188:191], v[4:7]
	v_mfma_f32_16x16x32_bf16 v[32:35], v[222:225], v[196:199], v[32:35]
	v_mfma_f32_16x16x32_bf16 v[0:3], v[232:235], v[196:199], v[0:3]
	v_mfma_f32_16x16x32_bf16 v[44:47], v[228:231], v[84:87], v[44:47]
	v_mfma_f32_16x16x32_bf16 v[12:15], v[236:239], v[84:87], v[12:15]
	v_mfma_f32_16x16x32_bf16 v[40:43], v[228:231], v[92:95], v[40:43]
	v_mfma_f32_16x16x32_bf16 v[8:11], v[236:239], v[92:95], v[8:11]
	v_mfma_f32_16x16x32_bf16 v[36:39], v[228:231], v[192:195], v[36:39]
	v_mfma_f32_16x16x32_bf16 v[4:7], v[236:239], v[192:195], v[4:7]
	v_mfma_f32_16x16x32_bf16 v[32:35], v[228:231], v[200:203], v[32:35]
	v_mfma_f32_16x16x32_bf16 v[0:3], v[236:239], v[200:203], v[0:3]
	s_barrier
	s_setprio 0
	s_add_i32 s37, s37, 2
	s_add_u32 s86, s86, 0x100
	s_addc_u32 s87, s87, 0
	s_add_u32 s33, s33, 0x100
	s_addc_u32 s36, s36, 0
	s_cmp_gt_u32 s37, 13
.LBB0_125:
	s_add_u32 s27, s86, 0xfffc0080
	s_addc_u32 s56, s87, -1
	s_add_i32 s57, 0, 0x10000
	v_add_u32_e32 v76, s57, v217
	ds_read_b128 v[64:67], v76
	ds_read_b128 v[68:71], v76 offset:1024
	ds_read_b128 v[72:75], v76 offset:2048
	ds_read_b128 v[76:79], v76 offset:3072
	s_cmp_eq_u32 s37, 12
	s_cselect_b32 vcc_hi, s1, s56
	s_cselect_b32 vcc_lo, s10, s27
	s_cselect_b32 s83, s11, s36
	s_cselect_b32 s82, s25, s33
	v_lshl_add_u64 v[168:169], s[86:87], 0, v[164:165]
	s_add_i32 m0, s75, 0xc000
	ds_read_b128 v[80:83], v220
	ds_read_b128 v[84:87], v220 offset:1024
	ds_read_b128 v[88:91], v220 offset:2048
	ds_read_b128 v[92:95], v220 offset:3072
	ds_read_b128 v[188:191], v220 offset:4096
	ds_read_b128 v[192:195], v220 offset:5120
	ds_read_b128 v[196:199], v220 offset:6144
	ds_read_b128 v[200:203], v220 offset:7168
	global_load_lds_dwordx4 v[168:169], off
	v_lshl_add_u64 v[168:169], s[86:87], 0, v[166:167]
	s_add_i32 m0, s75, 0xe000
	s_nop 0
	global_load_lds_dwordx4 v[168:169], off
	s_waitcnt lgkmcnt(8)
	s_setprio 1
	s_barrier
	s_waitcnt lgkmcnt(0)
	v_mfma_f32_16x16x32_bf16 v[146:149], v[64:67], v[80:83], v[146:149]
	v_mfma_f32_16x16x32_bf16 v[116:119], v[72:75], v[80:83], v[116:119]
	v_mfma_f32_16x16x32_bf16 v[158:161], v[64:67], v[88:91], v[158:161]
	v_mfma_f32_16x16x32_bf16 v[124:127], v[72:75], v[88:91], v[124:127]
	v_mfma_f32_16x16x32_bf16 v[154:157], v[64:67], v[188:191], v[154:157]
	v_mfma_f32_16x16x32_bf16 v[112:115], v[72:75], v[188:191], v[112:115]
	v_mfma_f32_16x16x32_bf16 v[150:153], v[64:67], v[196:199], v[150:153]
	v_mfma_f32_16x16x32_bf16 v[120:123], v[72:75], v[196:199], v[120:123]
	v_mfma_f32_16x16x32_bf16 v[146:149], v[68:71], v[84:87], v[146:149]
	v_mfma_f32_16x16x32_bf16 v[116:119], v[76:79], v[84:87], v[116:119]
	v_mfma_f32_16x16x32_bf16 v[158:161], v[68:71], v[92:95], v[158:161]
	v_mfma_f32_16x16x32_bf16 v[124:127], v[76:79], v[92:95], v[124:127]
	v_mfma_f32_16x16x32_bf16 v[154:157], v[68:71], v[192:195], v[154:157]
	v_mfma_f32_16x16x32_bf16 v[112:115], v[76:79], v[192:195], v[112:115]
	v_mfma_f32_16x16x32_bf16 v[150:153], v[68:71], v[200:203], v[150:153]
	v_mfma_f32_16x16x32_bf16 v[120:123], v[76:79], v[200:203], v[120:123]
	s_barrier
	s_setprio 0
	s_add_i32 s27, 0, 0x14000
	v_add_u32_e32 v168, s27, v217
	s_add_i32 s56, s57, s74
	ds_read_b128 v[204:207], v168
	ds_read_b128 v[222:225], v168 offset:1024
	ds_read_b128 v[228:231], v168 offset:2048
	ds_read_b128 v[232:235], v168 offset:3072
	v_lshl_add_u64 v[168:169], s[82:83], 0, v[144:145]
	s_mov_b32 m0, s56
	v_lshl_add_u64 v[176:177], s[82:83], 0, v[162:163]
	global_load_lds_dwordx4 v[168:169], off
	s_add_i32 m0, s56, 0x2000
	s_nop 0
	global_load_lds_dwordx4 v[176:177], off
	s_setprio 1
	s_barrier
	s_waitcnt lgkmcnt(0)
	v_mfma_f32_16x16x32_bf16 v[140:143], v[204:207], v[80:83], v[140:143]
	v_mfma_f32_16x16x32_bf16 v[80:83], v[228:231], v[80:83], v[108:111]
	v_mfma_f32_16x16x32_bf16 v[140:143], v[222:225], v[84:87], v[140:143]
	v_mfma_f32_16x16x32_bf16 v[80:83], v[232:235], v[84:87], v[80:83]
	v_mfma_f32_16x16x32_bf16 v[84:87], v[204:207], v[88:91], v[136:139]
	v_mfma_f32_16x16x32_bf16 v[88:91], v[228:231], v[88:91], v[104:107]
	v_mfma_f32_16x16x32_bf16 v[100:103], v[228:231], v[188:191], v[100:103]
	v_mfma_f32_16x16x32_bf16 v[104:107], v[204:207], v[196:199], v[128:131]
	v_mfma_f32_16x16x32_bf16 v[96:99], v[228:231], v[196:199], v[96:99]
	v_mfma_f32_16x16x32_bf16 v[84:87], v[222:225], v[92:95], v[84:87]
	v_mfma_f32_16x16x32_bf16 v[88:91], v[232:235], v[92:95], v[88:91]
	v_mfma_f32_16x16x32_bf16 v[92:95], v[204:207], v[188:191], v[132:135]
	v_mfma_f32_16x16x32_bf16 v[100:103], v[232:235], v[192:195], v[100:103]
	v_mfma_f32_16x16x32_bf16 v[128:131], v[222:225], v[200:203], v[104:107]
	v_mfma_f32_16x16x32_bf16 v[96:99], v[232:235], v[200:203], v[96:99]
	v_mfma_f32_16x16x32_bf16 v[92:95], v[222:225], v[192:195], v[92:95]
	s_barrier
	s_setprio 0
	s_mov_b32 m0, s75
	v_lshl_add_u64 v[240:241], vcc, 0, v[144:145]
	ds_read_b128 v[104:107], v220 offset:16384
	ds_read_b128 v[108:111], v220 offset:17408
	ds_read_b128 v[132:135], v220 offset:18432
	ds_read_b128 v[136:139], v220 offset:19456
	ds_read_b128 v[188:191], v220 offset:20480
	ds_read_b128 v[192:195], v220 offset:21504
	ds_read_b128 v[196:199], v220 offset:22528
	ds_read_b128 v[200:203], v220 offset:23552
	global_load_lds_dwordx4 v[240:241], off
	v_lshl_add_u64 v[242:243], vcc, 0, v[162:163]
	s_mov_b32 m0, s85
	s_nop 0
	global_load_lds_dwordx4 v[242:243], off
	s_setprio 1
	s_barrier
	s_waitcnt lgkmcnt(0)
	v_mfma_f32_16x16x32_bf16 v[48:51], v[64:67], v[104:107], v[48:51]
	v_mfma_f32_16x16x32_bf16 v[20:23], v[72:75], v[104:107], v[20:23]
	v_mfma_f32_16x16x32_bf16 v[60:63], v[64:67], v[132:135], v[60:63]
	v_mfma_f32_16x16x32_bf16 v[28:31], v[72:75], v[132:135], v[28:31]
	v_mfma_f32_16x16x32_bf16 v[56:59], v[64:67], v[188:191], v[56:59]
	v_mfma_f32_16x16x32_bf16 v[16:19], v[72:75], v[188:191], v[16:19]
	v_mfma_f32_16x16x32_bf16 v[52:55], v[64:67], v[196:199], v[52:55]
	v_mfma_f32_16x16x32_bf16 v[24:27], v[72:75], v[196:199], v[24:27]
	v_mfma_f32_16x16x32_bf16 v[48:51], v[68:71], v[108:111], v[48:51]
	v_mfma_f32_16x16x32_bf16 v[20:23], v[76:79], v[108:111], v[20:23]
	v_mfma_f32_16x16x32_bf16 v[60:63], v[68:71], v[136:139], v[60:63]
	v_mfma_f32_16x16x32_bf16 v[28:31], v[76:79], v[136:139], v[28:31]
	v_mfma_f32_16x16x32_bf16 v[56:59], v[68:71], v[192:195], v[56:59]
	v_mfma_f32_16x16x32_bf16 v[16:19], v[76:79], v[192:195], v[16:19]
	v_mfma_f32_16x16x32_bf16 v[52:55], v[68:71], v[200:203], v[52:55]
	v_mfma_f32_16x16x32_bf16 v[24:27], v[76:79], v[200:203], v[24:27]
	s_barrier
	s_setprio 0
	s_add_u32 s56, s82, 0x40000
	s_addc_u32 s57, s83, 0
	s_add_i32 s27, s27, s74
	v_lshl_add_u64 v[64:65], s[56:57], 0, v[144:145]
	s_mov_b32 m0, s27
	s_nop 0
	global_load_lds_dwordx4 v[64:65], off
	v_lshl_add_u64 v[64:65], s[56:57], 0, v[162:163]
	s_add_i32 m0, s27, 0x2000
	s_nop 0
	global_load_lds_dwordx4 v[64:65], off
	s_waitcnt vmcnt(6)
	s_setprio 1
	s_barrier
	v_mfma_f32_16x16x32_bf16 v[44:47], v[204:207], v[104:107], v[44:47]
	v_mfma_f32_16x16x32_bf16 v[12:15], v[228:231], v[104:107], v[12:15]
	v_mfma_f32_16x16x32_bf16 v[40:43], v[204:207], v[132:135], v[40:43]
	v_mfma_f32_16x16x32_bf16 v[8:11], v[228:231], v[132:135], v[8:11]
	v_mfma_f32_16x16x32_bf16 v[36:39], v[204:207], v[188:191], v[36:39]
	v_mfma_f32_16x16x32_bf16 v[4:7], v[228:231], v[188:191], v[4:7]
	v_mfma_f32_16x16x32_bf16 v[32:35], v[204:207], v[196:199], v[32:35]
	v_mfma_f32_16x16x32_bf16 v[0:3], v[228:231], v[196:199], v[0:3]
	v_mfma_f32_16x16x32_bf16 v[44:47], v[222:225], v[108:111], v[44:47]
	v_mfma_f32_16x16x32_bf16 v[12:15], v[232:235], v[108:111], v[12:15]
	v_mfma_f32_16x16x32_bf16 v[40:43], v[222:225], v[136:139], v[40:43]
	v_mfma_f32_16x16x32_bf16 v[8:11], v[232:235], v[136:139], v[8:11]
	v_mfma_f32_16x16x32_bf16 v[36:39], v[222:225], v[192:195], v[36:39]
	v_mfma_f32_16x16x32_bf16 v[4:7], v[232:235], v[192:195], v[4:7]
	v_mfma_f32_16x16x32_bf16 v[32:35], v[222:225], v[200:203], v[32:35]
	v_mfma_f32_16x16x32_bf16 v[0:3], v[232:235], v[200:203], v[0:3]
	s_barrier
	s_setprio 0
	s_add_i32 s27, 0, 0x18000
	v_add_u32_e32 v76, s27, v217
	ds_read_b128 v[64:67], v76
	ds_read_b128 v[68:71], v76 offset:1024
	ds_read_b128 v[72:75], v76 offset:2048
	ds_read_b128 v[76:79], v76 offset:3072
	s_add_u32 s56, vcc_lo, 0x40000
	s_addc_u32 s57, vcc_hi, 0
	s_mov_b32 m0, s98
	v_lshl_add_u64 v[136:137], s[56:57], 0, v[144:145]
	ds_read_b128 v[104:107], v220 offset:32768
	ds_read_b128 v[108:111], v220 offset:33792
	ds_read_b128 v[132:135], v220 offset:34816
	ds_read_b128 v[188:191], v220 offset:35840
	ds_read_b128 v[192:195], v220 offset:36864
	ds_read_b128 v[196:199], v220 offset:37888
	ds_read_b128 v[200:203], v220 offset:38912
	ds_read_b128 v[204:207], v220 offset:39936
	global_load_lds_dwordx4 v[136:137], off
	v_lshl_add_u64 v[136:137], s[56:57], 0, v[162:163]
	s_mov_b32 m0, s29
	s_nop 0
	global_load_lds_dwordx4 v[136:137], off
	s_waitcnt lgkmcnt(8)
	s_setprio 1
	s_barrier
	s_waitcnt lgkmcnt(0)
	v_mfma_f32_16x16x32_bf16 v[136:139], v[64:67], v[104:107], v[146:149]
	v_mfma_f32_16x16x32_bf16 v[146:149], v[68:71], v[108:111], v[136:139]
	v_mfma_f32_16x16x32_bf16 v[136:139], v[64:67], v[132:135], v[158:161]
	v_mfma_f32_16x16x32_bf16 v[158:161], v[68:71], v[188:191], v[136:139]
	v_mfma_f32_16x16x32_bf16 v[136:139], v[64:67], v[192:195], v[154:157]
	v_mfma_f32_16x16x32_bf16 v[116:119], v[72:75], v[104:107], v[116:119]
	v_mfma_f32_16x16x32_bf16 v[124:127], v[72:75], v[132:135], v[124:127]
	v_mfma_f32_16x16x32_bf16 v[154:157], v[68:71], v[196:199], v[136:139]
	v_mfma_f32_16x16x32_bf16 v[112:115], v[72:75], v[192:195], v[112:115]
	v_mfma_f32_16x16x32_bf16 v[136:139], v[64:67], v[200:203], v[150:153]
	v_mfma_f32_16x16x32_bf16 v[120:123], v[72:75], v[200:203], v[120:123]
	v_mfma_f32_16x16x32_bf16 v[116:119], v[76:79], v[108:111], v[116:119]
	v_mfma_f32_16x16x32_bf16 v[124:127], v[76:79], v[188:191], v[124:127]
	v_mfma_f32_16x16x32_bf16 v[112:115], v[76:79], v[196:199], v[112:115]
	v_mfma_f32_16x16x32_bf16 v[150:153], v[68:71], v[204:207], v[136:139]
	v_mfma_f32_16x16x32_bf16 v[120:123], v[76:79], v[204:207], v[120:123]
	s_barrier
	s_setprio 0
	s_add_i32 s58, 0, 0x1c000
	v_add_u32_e32 v136, s58, v217
	s_add_i32 s27, s27, s74
	ds_read_b128 v[222:225], v136
	ds_read_b128 v[228:231], v136 offset:1024
	ds_read_b128 v[232:235], v136 offset:2048
	ds_read_b128 v[236:239], v136 offset:3072
	v_lshl_add_u64 v[136:137], v[168:169], 0, s[18:19]
	s_mov_b32 m0, s27
	s_nop 0
	global_load_lds_dwordx4 v[136:137], off
	v_lshl_add_u64 v[136:137], v[176:177], 0, s[18:19]
	s_add_i32 m0, s27, 0x2000
	s_nop 0
	global_load_lds_dwordx4 v[136:137], off
	s_setprio 1
	s_barrier
	s_waitcnt lgkmcnt(0)
	v_mfma_f32_16x16x32_bf16 v[136:139], v[222:225], v[104:107], v[140:143]
	v_mfma_f32_16x16x32_bf16 v[80:83], v[232:235], v[104:107], v[80:83]
	v_mfma_f32_16x16x32_bf16 v[140:143], v[228:231], v[108:111], v[136:139]
	v_mfma_f32_16x16x32_bf16 v[108:111], v[236:239], v[108:111], v[80:83]
	v_mfma_f32_16x16x32_bf16 v[80:83], v[222:225], v[132:135], v[84:87]
	v_mfma_f32_16x16x32_bf16 v[136:139], v[228:231], v[188:191], v[80:83]
	v_mfma_f32_16x16x32_bf16 v[80:83], v[232:235], v[132:135], v[88:91]
	v_mfma_f32_16x16x32_bf16 v[104:107], v[236:239], v[188:191], v[80:83]
	v_mfma_f32_16x16x32_bf16 v[80:83], v[222:225], v[192:195], v[92:95]
	v_mfma_f32_16x16x32_bf16 v[132:135], v[228:231], v[196:199], v[80:83]
	v_mfma_f32_16x16x32_bf16 v[80:83], v[232:235], v[192:195], v[100:103]
	v_mfma_f32_16x16x32_bf16 v[100:103], v[236:239], v[196:199], v[80:83]
	v_mfma_f32_16x16x32_bf16 v[80:83], v[222:225], v[200:203], v[128:131]
	v_mfma_f32_16x16x32_bf16 v[128:131], v[228:231], v[204:207], v[80:83]
	v_mfma_f32_16x16x32_bf16 v[80:83], v[232:235], v[200:203], v[96:99]
	v_mfma_f32_16x16x32_bf16 v[96:99], v[236:239], v[204:207], v[80:83]
	s_barrier
	s_setprio 0
	s_mov_b32 m0, s31
	v_lshl_add_u64 v[168:169], v[240:241], 0, s[18:19]
	s_nop 2
	ds_read_b128 v[80:83], v220 offset:49152
	ds_read_b128 v[84:87], v220 offset:50176
	ds_read_b128 v[88:91], v220 offset:51200
	ds_read_b128 v[92:95], v220 offset:52224
	ds_read_b128 v[188:191], v220 offset:53248
	ds_read_b128 v[192:195], v220 offset:54272
	ds_read_b128 v[196:199], v220 offset:55296
	ds_read_b128 v[200:203], v220 offset:56320
	global_load_lds_dwordx4 v[168:169], off
	v_lshl_add_u64 v[168:169], v[242:243], 0, s[18:19]
	s_mov_b32 m0, s34
	s_nop 0
	global_load_lds_dwordx4 v[168:169], off
	s_setprio 1
	s_barrier
	s_waitcnt lgkmcnt(0)
	v_mfma_f32_16x16x32_bf16 v[48:51], v[64:67], v[80:83], v[48:51]
	v_mfma_f32_16x16x32_bf16 v[20:23], v[72:75], v[80:83], v[20:23]
	v_mfma_f32_16x16x32_bf16 v[60:63], v[64:67], v[88:91], v[60:63]
	v_mfma_f32_16x16x32_bf16 v[28:31], v[72:75], v[88:91], v[28:31]
	v_mfma_f32_16x16x32_bf16 v[56:59], v[64:67], v[188:191], v[56:59]
	v_mfma_f32_16x16x32_bf16 v[16:19], v[72:75], v[188:191], v[16:19]
	v_mfma_f32_16x16x32_bf16 v[52:55], v[64:67], v[196:199], v[52:55]
	v_mfma_f32_16x16x32_bf16 v[24:27], v[72:75], v[196:199], v[24:27]
	v_mfma_f32_16x16x32_bf16 v[48:51], v[68:71], v[84:87], v[48:51]
	v_mfma_f32_16x16x32_bf16 v[20:23], v[76:79], v[84:87], v[20:23]
	v_mfma_f32_16x16x32_bf16 v[60:63], v[68:71], v[92:95], v[60:63]
	v_mfma_f32_16x16x32_bf16 v[28:31], v[76:79], v[92:95], v[28:31]
	v_mfma_f32_16x16x32_bf16 v[56:59], v[68:71], v[192:195], v[56:59]
	v_mfma_f32_16x16x32_bf16 v[16:19], v[76:79], v[192:195], v[16:19]
	v_mfma_f32_16x16x32_bf16 v[52:55], v[68:71], v[200:203], v[52:55]
	v_mfma_f32_16x16x32_bf16 v[24:27], v[76:79], v[200:203], v[24:27]
	s_barrier
	s_setprio 0
	s_add_u32 s56, s82, 0x40080
	s_addc_u32 s57, s83, 0
	s_add_i32 s27, s58, s74
	v_lshl_add_u64 v[64:65], s[56:57], 0, v[144:145]
	s_mov_b32 m0, s27
	s_nop 0
	global_load_lds_dwordx4 v[64:65], off
	v_lshl_add_u64 v[64:65], s[56:57], 0, v[162:163]
	s_add_i32 m0, s27, 0x2000
	s_nop 0
	global_load_lds_dwordx4 v[64:65], off
	s_waitcnt vmcnt(6)
	s_setprio 1
	s_barrier
	v_mfma_f32_16x16x32_bf16 v[44:47], v[222:225], v[80:83], v[44:47]
	v_mfma_f32_16x16x32_bf16 v[12:15], v[232:235], v[80:83], v[12:15]
	v_mfma_f32_16x16x32_bf16 v[40:43], v[222:225], v[88:91], v[40:43]
	v_mfma_f32_16x16x32_bf16 v[8:11], v[232:235], v[88:91], v[8:11]
	v_mfma_f32_16x16x32_bf16 v[36:39], v[222:225], v[188:191], v[36:39]
	v_mfma_f32_16x16x32_bf16 v[4:7], v[232:235], v[188:191], v[4:7]
	v_mfma_f32_16x16x32_bf16 v[32:35], v[222:225], v[196:199], v[32:35]
	v_mfma_f32_16x16x32_bf16 v[0:3], v[232:235], v[196:199], v[0:3]
	v_mfma_f32_16x16x32_bf16 v[44:47], v[228:231], v[84:87], v[44:47]
	v_mfma_f32_16x16x32_bf16 v[12:15], v[236:239], v[84:87], v[12:15]
	v_mfma_f32_16x16x32_bf16 v[40:43], v[228:231], v[92:95], v[40:43]
	v_mfma_f32_16x16x32_bf16 v[8:11], v[236:239], v[92:95], v[8:11]
	v_mfma_f32_16x16x32_bf16 v[36:39], v[228:231], v[192:195], v[36:39]
	v_mfma_f32_16x16x32_bf16 v[4:7], v[236:239], v[192:195], v[4:7]
	v_mfma_f32_16x16x32_bf16 v[32:35], v[228:231], v[200:203], v[32:35]
	v_mfma_f32_16x16x32_bf16 v[0:3], v[236:239], v[200:203], v[0:3]
	s_barrier
	s_setprio 0
	s_add_i32 s37, s37, 2
	s_add_u32 s86, s86, 0x100
	s_addc_u32 s87, s87, 0
	s_add_u32 s33, s33, 0x100
	s_addc_u32 s36, s36, 0
	s_cmp_gt_u32 s37, 13
	s_cbranch_scc0 .LBB0_125
	s_lshl_b32 s1, s84, 8
	v_readlane_b32 s10, v254, 61
	s_add_i32 s1, s1, s10
	v_or_b32_e32 v198, s1, v216
	s_add_i32 s10, s1, 0x80
	v_or_b32_e32 v168, s10, v216
	v_lshl_or_b32 v188, s0, 7, v219
	v_lshlrev_b32_e32 v190, 2, v188
	v_lshlrev_b32_e32 v189, 1, v188
	s_ashr_i32 s11, s1, 5
	s_movk_i32 s10, 0xb00
	s_movk_i32 s20, 0x1600
	s_mov_b32 s101, 0xbfb8aa3b
	s_cmp_eq_u32 s84, s100
	s_cbranch_scc1 .Ldepi_w
	v_ashrrev_i32_e32 v199, 31, v198
	v_ashrrev_i32_e32 v169, 31, v168
	v_lshl_add_u64 v[170:171], v[198:199], 3, s[48:49]
	v_lshl_add_u64 v[172:173], v[168:169], 3, s[48:49]
	global_load_dwordx2 v[176:177], v[170:171], off
	global_load_dwordx2 v[202:203], v[170:171], off offset:128
	global_load_dwordx2 v[206:207], v[170:171], off offset:256
	global_load_dwordx2 v[222:223], v[170:171], off offset:384
	global_load_dwordx2 v[200:201], v[172:173], off
	global_load_dwordx2 v[196:197], v[172:173], off offset:128
	global_load_dwordx2 v[194:195], v[172:173], off offset:256
	global_load_dwordx2 v[192:193], v[172:173], off offset:384

.LBB0_195:
	s_add_u32 s42, s78, 0x80
	s_addc_u32 s43, s79, 0
	s_add_u32 s33, s44, 0x100
	s_addc_u32 s37, s45, 0
	s_mov_b32 s27, 0
	s_waitcnt lgkmcnt(0)
	s_add_i32 s56, s27, 2
	s_add_u32 s44, s42, 0x80
	s_addc_u32 s45, s43, 0
	s_add_i32 s57, 0, 0x10000
	v_add_u32_e32 v140, s57, v207
	ds_read_b128 v[128:131], v140
	ds_read_b128 v[132:135], v140 offset:1024
	ds_read_b128 v[136:139], v140 offset:2048
	ds_read_b128 v[140:143], v140 offset:3072
	s_cmp_eq_u32 s82, s27
	s_cselect_b32 s45, s77, s45
	s_cselect_b32 s44, s76, s44
	s_cselect_b32 s79, s1, s37
	s_cselect_b32 s78, s0, s33
	v_lshl_add_u64 v[176:177], s[42:43], 0, v[190:191]
	s_add_i32 m0, s85, 0xc000
	ds_read_b128 v[146:149], v217
	ds_read_b128 v[150:153], v217 offset:1024
	ds_read_b128 v[154:157], v217 offset:2048
	ds_read_b128 v[158:161], v217 offset:3072
	ds_read_b128 v[162:165], v217 offset:4096
	ds_read_b128 v[166:169], v217 offset:5120
	ds_read_b128 v[194:197], v217 offset:6144
	ds_read_b128 v[198:201], v217 offset:7168
	global_load_lds_dwordx4 v[176:177], off
	v_lshl_add_u64 v[176:177], s[42:43], 0, v[192:193]
	s_add_i32 m0, s85, 0xe000
	s_nop 0
	global_load_lds_dwordx4 v[176:177], off
	s_waitcnt lgkmcnt(8)
	s_setprio 1
	s_barrier
	s_waitcnt lgkmcnt(0)
	v_mfma_f32_16x16x32_bf16 v[124:127], v[128:131], v[146:149], 0
	v_mfma_f32_16x16x32_bf16 v[120:123], v[136:139], v[146:149], 0
	v_mfma_f32_16x16x32_bf16 v[108:111], v[128:131], v[154:157], 0
	v_mfma_f32_16x16x32_bf16 v[104:107], v[136:139], v[154:157], 0
	v_mfma_f32_16x16x32_bf16 v[92:95], v[128:131], v[162:165], 0
	v_mfma_f32_16x16x32_bf16 v[88:91], v[136:139], v[162:165], 0
	v_mfma_f32_16x16x32_bf16 v[76:79], v[128:131], v[194:197], 0
	v_mfma_f32_16x16x32_bf16 v[72:75], v[136:139], v[194:197], 0
	v_mfma_f32_16x16x32_bf16 v[124:127], v[132:135], v[150:153], v[124:127]
	v_mfma_f32_16x16x32_bf16 v[120:123], v[140:143], v[150:153], v[120:123]
	v_mfma_f32_16x16x32_bf16 v[108:111], v[132:135], v[158:161], v[108:111]
	v_mfma_f32_16x16x32_bf16 v[104:107], v[140:143], v[158:161], v[104:107]
	v_mfma_f32_16x16x32_bf16 v[92:95], v[132:135], v[166:169], v[92:95]
	v_mfma_f32_16x16x32_bf16 v[88:91], v[140:143], v[166:169], v[88:91]
	v_mfma_f32_16x16x32_bf16 v[76:79], v[132:135], v[198:201], v[76:79]
	v_mfma_f32_16x16x32_bf16 v[72:75], v[140:143], v[198:201], v[72:75]
	s_barrier
	s_setprio 0
	s_add_i32 s27, 0, 0x14000
	v_add_u32_e32 v176, s27, v207
	s_add_i32 s57, s57, s84
	ds_read_b128 v[202:205], v176
	ds_read_b128 v[218:221], v176 offset:1024
	ds_read_b128 v[222:225], v176 offset:2048
	ds_read_b128 v[228:231], v176 offset:3072
	v_lshl_add_u64 v[176:177], s[78:79], 0, v[144:145]
	s_mov_b32 m0, s57
	v_lshl_add_u64 v[232:233], s[78:79], 0, v[188:189]
	global_load_lds_dwordx4 v[176:177], off
	s_add_i32 m0, s57, 0x2000
	s_nop 0
	global_load_lds_dwordx4 v[232:233], off
	s_setprio 1
	s_barrier
	s_waitcnt lgkmcnt(0)
	v_mfma_f32_16x16x32_bf16 v[116:119], v[202:205], v[146:149], 0
	v_mfma_f32_16x16x32_bf16 v[112:115], v[222:225], v[146:149], 0
	v_mfma_f32_16x16x32_bf16 v[100:103], v[202:205], v[154:157], 0
	v_mfma_f32_16x16x32_bf16 v[96:99], v[222:225], v[154:157], 0
	v_mfma_f32_16x16x32_bf16 v[84:87], v[202:205], v[162:165], 0
	v_mfma_f32_16x16x32_bf16 v[80:83], v[222:225], v[162:165], 0
	v_mfma_f32_16x16x32_bf16 v[68:71], v[202:205], v[194:197], 0
	v_mfma_f32_16x16x32_bf16 v[64:67], v[222:225], v[194:197], 0
	v_mfma_f32_16x16x32_bf16 v[116:119], v[218:221], v[150:153], v[116:119]
	v_mfma_f32_16x16x32_bf16 v[112:115], v[228:231], v[150:153], v[112:115]
	v_mfma_f32_16x16x32_bf16 v[100:103], v[218:221], v[158:161], v[100:103]
	v_mfma_f32_16x16x32_bf16 v[96:99], v[228:231], v[158:161], v[96:99]
	v_mfma_f32_16x16x32_bf16 v[84:87], v[218:221], v[166:169], v[84:87]
	v_mfma_f32_16x16x32_bf16 v[80:83], v[228:231], v[166:169], v[80:83]
	v_mfma_f32_16x16x32_bf16 v[68:71], v[218:221], v[198:201], v[68:71]
	v_mfma_f32_16x16x32_bf16 v[64:67], v[228:231], v[198:201], v[64:67]
	s_barrier
	s_setprio 0
	s_mov_b32 m0, s85
	v_lshl_add_u64 v[234:235], s[44:45], 0, v[144:145]
	ds_read_b128 v[146:149], v217 offset:16384
	ds_read_b128 v[150:153], v217 offset:17408
	ds_read_b128 v[154:157], v217 offset:18432
	ds_read_b128 v[158:161], v217 offset:19456
	ds_read_b128 v[162:165], v217 offset:20480
	ds_read_b128 v[166:169], v217 offset:21504
	ds_read_b128 v[194:197], v217 offset:22528
	ds_read_b128 v[198:201], v217 offset:23552
	global_load_lds_dwordx4 v[234:235], off
	v_lshl_add_u64 v[236:237], s[44:45], 0, v[188:189]
	s_mov_b32 m0, s86
	s_nop 0
	global_load_lds_dwordx4 v[236:237], off
	s_setprio 1
	s_barrier
	s_waitcnt lgkmcnt(0)
	v_mfma_f32_16x16x32_bf16 v[60:63], v[128:131], v[146:149], 0
	v_mfma_f32_16x16x32_bf16 v[56:59], v[136:139], v[146:149], 0
	v_mfma_f32_16x16x32_bf16 v[44:47], v[128:131], v[154:157], 0
	v_mfma_f32_16x16x32_bf16 v[40:43], v[136:139], v[154:157], 0
	v_mfma_f32_16x16x32_bf16 v[28:31], v[128:131], v[162:165], 0
	v_mfma_f32_16x16x32_bf16 v[24:27], v[136:139], v[162:165], 0
	v_mfma_f32_16x16x32_bf16 v[12:15], v[128:131], v[194:197], 0
	v_mfma_f32_16x16x32_bf16 v[8:11], v[136:139], v[194:197], 0
	v_mfma_f32_16x16x32_bf16 v[60:63], v[132:135], v[150:153], v[60:63]
	v_mfma_f32_16x16x32_bf16 v[56:59], v[140:143], v[150:153], v[56:59]
	v_mfma_f32_16x16x32_bf16 v[44:47], v[132:135], v[158:161], v[44:47]
	v_mfma_f32_16x16x32_bf16 v[40:43], v[140:143], v[158:161], v[40:43]
	v_mfma_f32_16x16x32_bf16 v[28:31], v[132:135], v[166:169], v[28:31]
	v_mfma_f32_16x16x32_bf16 v[24:27], v[140:143], v[166:169], v[24:27]
	v_mfma_f32_16x16x32_bf16 v[12:15], v[132:135], v[198:201], v[12:15]
	v_mfma_f32_16x16x32_bf16 v[8:11], v[140:143], v[198:201], v[8:11]
	s_barrier
	s_setprio 0
	s_add_u32 s58, s78, s98
	s_addc_u32 s59, s79, 0
	s_add_i32 s27, s27, s84
	v_lshl_add_u64 v[238:239], s[58:59], 0, v[144:145]
	s_mov_b32 m0, s27
	v_lshl_add_u64 v[240:241], s[58:59], 0, v[188:189]
	global_load_lds_dwordx4 v[238:239], off
	s_add_i32 m0, s27, 0x2000
	s_nop 0
	global_load_lds_dwordx4 v[240:241], off
	s_waitcnt vmcnt(6)
	s_setprio 1
	s_barrier
	v_mfma_f32_16x16x32_bf16 v[52:55], v[202:205], v[146:149], 0
	v_mfma_f32_16x16x32_bf16 v[48:51], v[222:225], v[146:149], 0
	v_mfma_f32_16x16x32_bf16 v[36:39], v[202:205], v[154:157], 0
	v_mfma_f32_16x16x32_bf16 v[32:35], v[222:225], v[154:157], 0
	v_mfma_f32_16x16x32_bf16 v[20:23], v[202:205], v[162:165], 0
	v_mfma_f32_16x16x32_bf16 v[16:19], v[222:225], v[162:165], 0
	v_mfma_f32_16x16x32_bf16 v[4:7], v[202:205], v[194:197], 0
	v_mfma_f32_16x16x32_bf16 v[0:3], v[222:225], v[194:197], 0
	v_mfma_f32_16x16x32_bf16 v[52:55], v[218:221], v[150:153], v[52:55]
	v_mfma_f32_16x16x32_bf16 v[48:51], v[228:231], v[150:153], v[48:51]
	v_mfma_f32_16x16x32_bf16 v[36:39], v[218:221], v[158:161], v[36:39]
	v_mfma_f32_16x16x32_bf16 v[32:35], v[228:231], v[158:161], v[32:35]
	v_mfma_f32_16x16x32_bf16 v[20:23], v[218:221], v[166:169], v[20:23]
	v_mfma_f32_16x16x32_bf16 v[16:19], v[228:231], v[166:169], v[16:19]
	v_mfma_f32_16x16x32_bf16 v[4:7], v[218:221], v[198:201], v[4:7]
	v_mfma_f32_16x16x32_bf16 v[0:3], v[228:231], v[198:201], v[0:3]
	s_barrier
	s_setprio 0
	s_add_i32 s27, 0, 0x18000
	v_add_u32_e32 v140, s27, v207
	ds_read_b128 v[128:131], v140
	ds_read_b128 v[132:135], v140 offset:1024
	ds_read_b128 v[136:139], v140 offset:2048
	ds_read_b128 v[140:143], v140 offset:3072
	s_add_u32 s44, s44, s98
	s_addc_u32 s45, s45, 0
	s_mov_b32 m0, s87
	v_lshl_add_u64 v[202:203], s[44:45], 0, v[144:145]
	ds_read_b128 v[146:149], v217 offset:32768
	ds_read_b128 v[150:153], v217 offset:33792
	ds_read_b128 v[154:157], v217 offset:34816
	ds_read_b128 v[158:161], v217 offset:35840
	ds_read_b128 v[162:165], v217 offset:36864
	ds_read_b128 v[166:169], v217 offset:37888
	ds_read_b128 v[194:197], v217 offset:38912
	ds_read_b128 v[198:201], v217 offset:39936
	global_load_lds_dwordx4 v[202:203], off
	v_lshl_add_u64 v[202:203], s[44:45], 0, v[188:189]
	s_mov_b32 m0, s80
	s_nop 0
	global_load_lds_dwordx4 v[202:203], off
	s_waitcnt lgkmcnt(8)
	s_setprio 1
	s_barrier
	s_waitcnt lgkmcnt(0)
	v_mfma_f32_16x16x32_bf16 v[124:127], v[128:131], v[146:149], v[124:127]
	v_mfma_f32_16x16x32_bf16 v[120:123], v[136:139], v[146:149], v[120:123]
	v_mfma_f32_16x16x32_bf16 v[108:111], v[128:131], v[154:157], v[108:111]
	v_mfma_f32_16x16x32_bf16 v[104:107], v[136:139], v[154:157], v[104:107]
	v_mfma_f32_16x16x32_bf16 v[92:95], v[128:131], v[162:165], v[92:95]
	v_mfma_f32_16x16x32_bf16 v[88:91], v[136:139], v[162:165], v[88:91]
	v_mfma_f32_16x16x32_bf16 v[76:79], v[128:131], v[194:197], v[76:79]
	v_mfma_f32_16x16x32_bf16 v[72:75], v[136:139], v[194:197], v[72:75]
	v_mfma_f32_16x16x32_bf16 v[124:127], v[132:135], v[150:153], v[124:127]
	v_mfma_f32_16x16x32_bf16 v[120:123], v[140:143], v[150:153], v[120:123]
	v_mfma_f32_16x16x32_bf16 v[108:111], v[132:135], v[158:161], v[108:111]
	v_mfma_f32_16x16x32_bf16 v[104:107], v[140:143], v[158:161], v[104:107]
	v_mfma_f32_16x16x32_bf16 v[92:95], v[132:135], v[166:169], v[92:95]
	v_mfma_f32_16x16x32_bf16 v[88:91], v[140:143], v[166:169], v[88:91]
	v_mfma_f32_16x16x32_bf16 v[76:79], v[132:135], v[198:201], v[76:79]
	v_mfma_f32_16x16x32_bf16 v[72:75], v[140:143], v[198:201], v[72:75]
	s_barrier
	s_setprio 0
	s_add_i32 s44, 0, 0x1c000
	s_add_i32 s27, s27, s84
	v_add_u32_e32 v228, s44, v207
	v_lshl_add_u64 v[176:177], v[176:177], 0, s[18:19]
	s_mov_b32 m0, s27
	ds_read_b128 v[202:205], v228
	ds_read_b128 v[218:221], v228 offset:1024
	ds_read_b128 v[222:225], v228 offset:2048
	ds_read_b128 v[228:231], v228 offset:3072
	global_load_lds_dwordx4 v[176:177], off
	v_lshl_add_u64 v[176:177], v[232:233], 0, s[18:19]
	s_add_i32 m0, s27, 0x2000
	s_nop 0
	global_load_lds_dwordx4 v[176:177], off
	s_setprio 1
	s_barrier
	s_waitcnt lgkmcnt(0)
	v_mfma_f32_16x16x32_bf16 v[116:119], v[202:205], v[146:149], v[116:119]
	v_mfma_f32_16x16x32_bf16 v[112:115], v[222:225], v[146:149], v[112:115]
	v_mfma_f32_16x16x32_bf16 v[100:103], v[202:205], v[154:157], v[100:103]
	v_mfma_f32_16x16x32_bf16 v[96:99], v[222:225], v[154:157], v[96:99]
	v_mfma_f32_16x16x32_bf16 v[84:87], v[202:205], v[162:165], v[84:87]
	v_mfma_f32_16x16x32_bf16 v[80:83], v[222:225], v[162:165], v[80:83]
	v_mfma_f32_16x16x32_bf16 v[68:71], v[202:205], v[194:197], v[68:71]
	v_mfma_f32_16x16x32_bf16 v[64:67], v[222:225], v[194:197], v[64:67]
	v_mfma_f32_16x16x32_bf16 v[116:119], v[218:221], v[150:153], v[116:119]
	v_mfma_f32_16x16x32_bf16 v[112:115], v[228:231], v[150:153], v[112:115]
	v_mfma_f32_16x16x32_bf16 v[100:103], v[218:221], v[158:161], v[100:103]
	v_mfma_f32_16x16x32_bf16 v[96:99], v[228:231], v[158:161], v[96:99]
	v_mfma_f32_16x16x32_bf16 v[84:87], v[218:221], v[166:169], v[84:87]
	v_mfma_f32_16x16x32_bf16 v[80:83], v[228:231], v[166:169], v[80:83]
	v_mfma_f32_16x16x32_bf16 v[68:71], v[218:221], v[198:201], v[68:71]
	v_mfma_f32_16x16x32_bf16 v[64:67], v[228:231], v[198:201], v[64:67]
	s_barrier
	s_setprio 0
	s_mov_b32 m0, s30
	v_lshl_add_u64 v[176:177], v[234:235], 0, s[18:19]
	ds_read_b128 v[146:149], v217 offset:49152
	ds_read_b128 v[150:153], v217 offset:50176
	ds_read_b128 v[154:157], v217 offset:51200
	ds_read_b128 v[158:161], v217 offset:52224
	ds_read_b128 v[162:165], v217 offset:53248
	ds_read_b128 v[166:169], v217 offset:54272
	ds_read_b128 v[194:197], v217 offset:55296
	ds_read_b128 v[198:201], v217 offset:56320
	global_load_lds_dwordx4 v[176:177], off
	v_lshl_add_u64 v[176:177], v[236:237], 0, s[18:19]
	s_mov_b32 m0, s31
	s_nop 0
	global_load_lds_dwordx4 v[176:177], off
	s_setprio 1
	s_barrier
	s_waitcnt lgkmcnt(0)
	v_mfma_f32_16x16x32_bf16 v[60:63], v[128:131], v[146:149], v[60:63]
	v_mfma_f32_16x16x32_bf16 v[56:59], v[136:139], v[146:149], v[56:59]
	v_mfma_f32_16x16x32_bf16 v[44:47], v[128:131], v[154:157], v[44:47]
	v_mfma_f32_16x16x32_bf16 v[40:43], v[136:139], v[154:157], v[40:43]
	v_mfma_f32_16x16x32_bf16 v[28:31], v[128:131], v[162:165], v[28:31]
	v_mfma_f32_16x16x32_bf16 v[24:27], v[136:139], v[162:165], v[24:27]
	v_mfma_f32_16x16x32_bf16 v[12:15], v[128:131], v[194:197], v[12:15]
	v_mfma_f32_16x16x32_bf16 v[8:11], v[136:139], v[194:197], v[8:11]
	v_mfma_f32_16x16x32_bf16 v[60:63], v[132:135], v[150:153], v[60:63]
	v_mfma_f32_16x16x32_bf16 v[56:59], v[140:143], v[150:153], v[56:59]
	v_mfma_f32_16x16x32_bf16 v[44:47], v[132:135], v[158:161], v[44:47]
	v_mfma_f32_16x16x32_bf16 v[40:43], v[140:143], v[158:161], v[40:43]
	v_mfma_f32_16x16x32_bf16 v[28:31], v[132:135], v[166:169], v[28:31]
	v_mfma_f32_16x16x32_bf16 v[24:27], v[140:143], v[166:169], v[24:27]
	v_mfma_f32_16x16x32_bf16 v[12:15], v[132:135], v[198:201], v[12:15]
	v_mfma_f32_16x16x32_bf16 v[8:11], v[140:143], v[198:201], v[8:11]
	s_barrier
	s_setprio 0
	s_add_i32 s27, s44, s84
	v_lshl_add_u64 v[128:129], v[238:239], 0, s[18:19]
	s_mov_b32 m0, s27
	s_nop 0
	global_load_lds_dwordx4 v[128:129], off
	v_lshl_add_u64 v[128:129], v[240:241], 0, s[18:19]
	s_add_i32 m0, s27, 0x2000
	s_nop 0
	global_load_lds_dwordx4 v[128:129], off
	s_waitcnt vmcnt(6)
	s_setprio 1
	s_barrier
	v_mfma_f32_16x16x32_bf16 v[52:55], v[202:205], v[146:149], v[52:55]
	v_mfma_f32_16x16x32_bf16 v[48:51], v[222:225], v[146:149], v[48:51]
	v_mfma_f32_16x16x32_bf16 v[36:39], v[202:205], v[154:157], v[36:39]
	v_mfma_f32_16x16x32_bf16 v[32:35], v[222:225], v[154:157], v[32:35]
	v_mfma_f32_16x16x32_bf16 v[20:23], v[202:205], v[162:165], v[20:23]
	v_mfma_f32_16x16x32_bf16 v[16:19], v[222:225], v[162:165], v[16:19]
	v_mfma_f32_16x16x32_bf16 v[4:7], v[202:205], v[194:197], v[4:7]
	v_mfma_f32_16x16x32_bf16 v[0:3], v[222:225], v[194:197], v[0:3]
	v_mfma_f32_16x16x32_bf16 v[52:55], v[218:221], v[150:153], v[52:55]
	v_mfma_f32_16x16x32_bf16 v[48:51], v[228:231], v[150:153], v[48:51]
	v_mfma_f32_16x16x32_bf16 v[36:39], v[218:221], v[158:161], v[36:39]
	v_mfma_f32_16x16x32_bf16 v[32:35], v[228:231], v[158:161], v[32:35]
	v_mfma_f32_16x16x32_bf16 v[20:23], v[218:221], v[166:169], v[20:23]
	v_mfma_f32_16x16x32_bf16 v[16:19], v[228:231], v[166:169], v[16:19]
	v_mfma_f32_16x16x32_bf16 v[4:7], v[218:221], v[198:201], v[4:7]
	v_mfma_f32_16x16x32_bf16 v[0:3], v[228:231], v[198:201], v[0:3]
	s_barrier
	s_setprio 0
	s_add_u32 s42, s42, 0x100
	s_addc_u32 s43, s43, 0
	s_add_u32 s33, s33, 0x100
	s_addc_u32 s37, s37, 0
	s_cmp_ge_u32 s56, s34
	s_mov_b32 s27, s56
.LBB0_196:
	s_add_i32 s56, s27, 2
	s_add_u32 s44, s42, 0x80
	s_addc_u32 s45, s43, 0
	s_add_i32 s57, 0, 0x10000
	v_add_u32_e32 v140, s57, v207
	ds_read_b128 v[128:131], v140
	ds_read_b128 v[132:135], v140 offset:1024
	ds_read_b128 v[136:139], v140 offset:2048
	ds_read_b128 v[140:143], v140 offset:3072
	s_cmp_eq_u32 s82, s27
	s_cselect_b32 s45, s77, s45
	s_cselect_b32 s44, s76, s44
	s_cselect_b32 s79, s1, s37
	s_cselect_b32 s78, s0, s33
	v_lshl_add_u64 v[176:177], s[42:43], 0, v[190:191]
	s_add_i32 m0, s85, 0xc000
	ds_read_b128 v[146:149], v217
	ds_read_b128 v[150:153], v217 offset:1024
	ds_read_b128 v[154:157], v217 offset:2048
	ds_read_b128 v[158:161], v217 offset:3072
	ds_read_b128 v[162:165], v217 offset:4096
	ds_read_b128 v[166:169], v217 offset:5120
	ds_read_b128 v[194:197], v217 offset:6144
	ds_read_b128 v[198:201], v217 offset:7168
	global_load_lds_dwordx4 v[176:177], off
	v_lshl_add_u64 v[176:177], s[42:43], 0, v[192:193]
	s_add_i32 m0, s85, 0xe000
	s_nop 0
	global_load_lds_dwordx4 v[176:177], off
	s_waitcnt lgkmcnt(8)
	s_setprio 1
	s_barrier
	s_waitcnt lgkmcnt(0)
	v_mfma_f32_16x16x32_bf16 v[124:127], v[128:131], v[146:149], v[124:127]
	v_mfma_f32_16x16x32_bf16 v[120:123], v[136:139], v[146:149], v[120:123]
	v_mfma_f32_16x16x32_bf16 v[108:111], v[128:131], v[154:157], v[108:111]
	v_mfma_f32_16x16x32_bf16 v[104:107], v[136:139], v[154:157], v[104:107]
	v_mfma_f32_16x16x32_bf16 v[92:95], v[128:131], v[162:165], v[92:95]
	v_mfma_f32_16x16x32_bf16 v[88:91], v[136:139], v[162:165], v[88:91]
	v_mfma_f32_16x16x32_bf16 v[76:79], v[128:131], v[194:197], v[76:79]
	v_mfma_f32_16x16x32_bf16 v[72:75], v[136:139], v[194:197], v[72:75]
	v_mfma_f32_16x16x32_bf16 v[124:127], v[132:135], v[150:153], v[124:127]
	v_mfma_f32_16x16x32_bf16 v[120:123], v[140:143], v[150:153], v[120:123]
	v_mfma_f32_16x16x32_bf16 v[108:111], v[132:135], v[158:161], v[108:111]
	v_mfma_f32_16x16x32_bf16 v[104:107], v[140:143], v[158:161], v[104:107]
	v_mfma_f32_16x16x32_bf16 v[92:95], v[132:135], v[166:169], v[92:95]
	v_mfma_f32_16x16x32_bf16 v[88:91], v[140:143], v[166:169], v[88:91]
	v_mfma_f32_16x16x32_bf16 v[76:79], v[132:135], v[198:201], v[76:79]
	v_mfma_f32_16x16x32_bf16 v[72:75], v[140:143], v[198:201], v[72:75]
	s_barrier
	s_setprio 0
	s_add_i32 s27, 0, 0x14000
	v_add_u32_e32 v176, s27, v207
	s_add_i32 s57, s57, s84
	ds_read_b128 v[202:205], v176
	ds_read_b128 v[218:221], v176 offset:1024
	ds_read_b128 v[222:225], v176 offset:2048
	ds_read_b128 v[228:231], v176 offset:3072
	v_lshl_add_u64 v[176:177], s[78:79], 0, v[144:145]
	s_mov_b32 m0, s57
	v_lshl_add_u64 v[232:233], s[78:79], 0, v[188:189]
	global_load_lds_dwordx4 v[176:177], off
	s_add_i32 m0, s57, 0x2000
	s_nop 0
	global_load_lds_dwordx4 v[232:233], off
	s_setprio 1
	s_barrier
	s_waitcnt lgkmcnt(0)
	v_mfma_f32_16x16x32_bf16 v[116:119], v[202:205], v[146:149], v[116:119]
	v_mfma_f32_16x16x32_bf16 v[112:115], v[222:225], v[146:149], v[112:115]
	v_mfma_f32_16x16x32_bf16 v[100:103], v[202:205], v[154:157], v[100:103]
	v_mfma_f32_16x16x32_bf16 v[96:99], v[222:225], v[154:157], v[96:99]
	v_mfma_f32_16x16x32_bf16 v[84:87], v[202:205], v[162:165], v[84:87]
	v_mfma_f32_16x16x32_bf16 v[80:83], v[222:225], v[162:165], v[80:83]
	v_mfma_f32_16x16x32_bf16 v[68:71], v[202:205], v[194:197], v[68:71]
	v_mfma_f32_16x16x32_bf16 v[64:67], v[222:225], v[194:197], v[64:67]
	v_mfma_f32_16x16x32_bf16 v[116:119], v[218:221], v[150:153], v[116:119]
	v_mfma_f32_16x16x32_bf16 v[112:115], v[228:231], v[150:153], v[112:115]
	v_mfma_f32_16x16x32_bf16 v[100:103], v[218:221], v[158:161], v[100:103]
	v_mfma_f32_16x16x32_bf16 v[96:99], v[228:231], v[158:161], v[96:99]
	v_mfma_f32_16x16x32_bf16 v[84:87], v[218:221], v[166:169], v[84:87]
	v_mfma_f32_16x16x32_bf16 v[80:83], v[228:231], v[166:169], v[80:83]
	v_mfma_f32_16x16x32_bf16 v[68:71], v[218:221], v[198:201], v[68:71]
	v_mfma_f32_16x16x32_bf16 v[64:67], v[228:231], v[198:201], v[64:67]
	s_barrier
	s_setprio 0
	s_mov_b32 m0, s85
	v_lshl_add_u64 v[234:235], s[44:45], 0, v[144:145]
	ds_read_b128 v[146:149], v217 offset:16384
	ds_read_b128 v[150:153], v217 offset:17408
	ds_read_b128 v[154:157], v217 offset:18432
	ds_read_b128 v[158:161], v217 offset:19456
	ds_read_b128 v[162:165], v217 offset:20480
	ds_read_b128 v[166:169], v217 offset:21504
	ds_read_b128 v[194:197], v217 offset:22528
	ds_read_b128 v[198:201], v217 offset:23552
	global_load_lds_dwordx4 v[234:235], off
	v_lshl_add_u64 v[236:237], s[44:45], 0, v[188:189]
	s_mov_b32 m0, s86
	s_nop 0
	global_load_lds_dwordx4 v[236:237], off
	s_setprio 1
	s_barrier
	s_waitcnt lgkmcnt(0)
	v_mfma_f32_16x16x32_bf16 v[60:63], v[128:131], v[146:149], v[60:63]
	v_mfma_f32_16x16x32_bf16 v[56:59], v[136:139], v[146:149], v[56:59]
	v_mfma_f32_16x16x32_bf16 v[44:47], v[128:131], v[154:157], v[44:47]
	v_mfma_f32_16x16x32_bf16 v[40:43], v[136:139], v[154:157], v[40:43]
	v_mfma_f32_16x16x32_bf16 v[28:31], v[128:131], v[162:165], v[28:31]
	v_mfma_f32_16x16x32_bf16 v[24:27], v[136:139], v[162:165], v[24:27]
	v_mfma_f32_16x16x32_bf16 v[12:15], v[128:131], v[194:197], v[12:15]
	v_mfma_f32_16x16x32_bf16 v[8:11], v[136:139], v[194:197], v[8:11]
	v_mfma_f32_16x16x32_bf16 v[60:63], v[132:135], v[150:153], v[60:63]
	v_mfma_f32_16x16x32_bf16 v[56:59], v[140:143], v[150:153], v[56:59]
	v_mfma_f32_16x16x32_bf16 v[44:47], v[132:135], v[158:161], v[44:47]
	v_mfma_f32_16x16x32_bf16 v[40:43], v[140:143], v[158:161], v[40:43]
	v_mfma_f32_16x16x32_bf16 v[28:31], v[132:135], v[166:169], v[28:31]
	v_mfma_f32_16x16x32_bf16 v[24:27], v[140:143], v[166:169], v[24:27]
	v_mfma_f32_16x16x32_bf16 v[12:15], v[132:135], v[198:201], v[12:15]
	v_mfma_f32_16x16x32_bf16 v[8:11], v[140:143], v[198:201], v[8:11]
	s_barrier
	s_setprio 0
	s_add_u32 s58, s78, s98
	s_addc_u32 s59, s79, 0
	s_add_i32 s27, s27, s84
	v_lshl_add_u64 v[238:239], s[58:59], 0, v[144:145]
	s_mov_b32 m0, s27
	v_lshl_add_u64 v[240:241], s[58:59], 0, v[188:189]
	global_load_lds_dwordx4 v[238:239], off
	s_add_i32 m0, s27, 0x2000
	s_nop 0
	global_load_lds_dwordx4 v[240:241], off
	s_waitcnt vmcnt(6)
	s_setprio 1
	s_barrier
	v_mfma_f32_16x16x32_bf16 v[52:55], v[202:205], v[146:149], v[52:55]
	v_mfma_f32_16x16x32_bf16 v[48:51], v[222:225], v[146:149], v[48:51]
	v_mfma_f32_16x16x32_bf16 v[36:39], v[202:205], v[154:157], v[36:39]
	v_mfma_f32_16x16x32_bf16 v[32:35], v[222:225], v[154:157], v[32:35]
	v_mfma_f32_16x16x32_bf16 v[20:23], v[202:205], v[162:165], v[20:23]
	v_mfma_f32_16x16x32_bf16 v[16:19], v[222:225], v[162:165], v[16:19]
	v_mfma_f32_16x16x32_bf16 v[4:7], v[202:205], v[194:197], v[4:7]
	v_mfma_f32_16x16x32_bf16 v[0:3], v[222:225], v[194:197], v[0:3]
	v_mfma_f32_16x16x32_bf16 v[52:55], v[218:221], v[150:153], v[52:55]
	v_mfma_f32_16x16x32_bf16 v[48:51], v[228:231], v[150:153], v[48:51]
	v_mfma_f32_16x16x32_bf16 v[36:39], v[218:221], v[158:161], v[36:39]
	v_mfma_f32_16x16x32_bf16 v[32:35], v[228:231], v[158:161], v[32:35]
	v_mfma_f32_16x16x32_bf16 v[20:23], v[218:221], v[166:169], v[20:23]
	v_mfma_f32_16x16x32_bf16 v[16:19], v[228:231], v[166:169], v[16:19]
	v_mfma_f32_16x16x32_bf16 v[4:7], v[218:221], v[198:201], v[4:7]
	v_mfma_f32_16x16x32_bf16 v[0:3], v[228:231], v[198:201], v[0:3]
	s_barrier
	s_setprio 0
	s_add_i32 s27, 0, 0x18000
	v_add_u32_e32 v140, s27, v207
	ds_read_b128 v[128:131], v140
	ds_read_b128 v[132:135], v140 offset:1024
	ds_read_b128 v[136:139], v140 offset:2048
	ds_read_b128 v[140:143], v140 offset:3072
	s_add_u32 s44, s44, s98
	s_addc_u32 s45, s45, 0
	s_mov_b32 m0, s87
	v_lshl_add_u64 v[202:203], s[44:45], 0, v[144:145]
	ds_read_b128 v[146:149], v217 offset:32768
	ds_read_b128 v[150:153], v217 offset:33792
	ds_read_b128 v[154:157], v217 offset:34816
	ds_read_b128 v[158:161], v217 offset:35840
	ds_read_b128 v[162:165], v217 offset:36864
	ds_read_b128 v[166:169], v217 offset:37888
	ds_read_b128 v[194:197], v217 offset:38912
	ds_read_b128 v[198:201], v217 offset:39936
	global_load_lds_dwordx4 v[202:203], off
	v_lshl_add_u64 v[202:203], s[44:45], 0, v[188:189]
	s_mov_b32 m0, s80
	s_nop 0
	global_load_lds_dwordx4 v[202:203], off
	s_waitcnt lgkmcnt(8)
	s_setprio 1
	s_barrier
	s_waitcnt lgkmcnt(0)
	v_mfma_f32_16x16x32_bf16 v[124:127], v[128:131], v[146:149], v[124:127]
	v_mfma_f32_16x16x32_bf16 v[120:123], v[136:139], v[146:149], v[120:123]
	v_mfma_f32_16x16x32_bf16 v[108:111], v[128:131], v[154:157], v[108:111]
	v_mfma_f32_16x16x32_bf16 v[104:107], v[136:139], v[154:157], v[104:107]
	v_mfma_f32_16x16x32_bf16 v[92:95], v[128:131], v[162:165], v[92:95]
	v_mfma_f32_16x16x32_bf16 v[88:91], v[136:139], v[162:165], v[88:91]
	v_mfma_f32_16x16x32_bf16 v[76:79], v[128:131], v[194:197], v[76:79]
	v_mfma_f32_16x16x32_bf16 v[72:75], v[136:139], v[194:197], v[72:75]
	v_mfma_f32_16x16x32_bf16 v[124:127], v[132:135], v[150:153], v[124:127]
	v_mfma_f32_16x16x32_bf16 v[120:123], v[140:143], v[150:153], v[120:123]
	v_mfma_f32_16x16x32_bf16 v[108:111], v[132:135], v[158:161], v[108:111]
	v_mfma_f32_16x16x32_bf16 v[104:107], v[140:143], v[158:161], v[104:107]
	v_mfma_f32_16x16x32_bf16 v[92:95], v[132:135], v[166:169], v[92:95]
	v_mfma_f32_16x16x32_bf16 v[88:91], v[140:143], v[166:169], v[88:91]
	v_mfma_f32_16x16x32_bf16 v[76:79], v[132:135], v[198:201], v[76:79]
	v_mfma_f32_16x16x32_bf16 v[72:75], v[140:143], v[198:201], v[72:75]
	s_barrier
	s_setprio 0
	s_add_i32 s44, 0, 0x1c000
	s_add_i32 s27, s27, s84
	v_add_u32_e32 v228, s44, v207
	v_lshl_add_u64 v[176:177], v[176:177], 0, s[18:19]
	s_mov_b32 m0, s27
	ds_read_b128 v[202:205], v228
	ds_read_b128 v[218:221], v228 offset:1024
	ds_read_b128 v[222:225], v228 offset:2048
	ds_read_b128 v[228:231], v228 offset:3072
	global_load_lds_dwordx4 v[176:177], off
	v_lshl_add_u64 v[176:177], v[232:233], 0, s[18:19]
	s_add_i32 m0, s27, 0x2000
	s_nop 0
	global_load_lds_dwordx4 v[176:177], off
	s_setprio 1
	s_barrier
	s_waitcnt lgkmcnt(0)
	v_mfma_f32_16x16x32_bf16 v[116:119], v[202:205], v[146:149], v[116:119]
	v_mfma_f32_16x16x32_bf16 v[112:115], v[222:225], v[146:149], v[112:115]
	v_mfma_f32_16x16x32_bf16 v[100:103], v[202:205], v[154:157], v[100:103]
	v_mfma_f32_16x16x32_bf16 v[96:99], v[222:225], v[154:157], v[96:99]
	v_mfma_f32_16x16x32_bf16 v[84:87], v[202:205], v[162:165], v[84:87]
	v_mfma_f32_16x16x32_bf16 v[80:83], v[222:225], v[162:165], v[80:83]
	v_mfma_f32_16x16x32_bf16 v[68:71], v[202:205], v[194:197], v[68:71]
	v_mfma_f32_16x16x32_bf16 v[64:67], v[222:225], v[194:197], v[64:67]
	v_mfma_f32_16x16x32_bf16 v[116:119], v[218:221], v[150:153], v[116:119]
	v_mfma_f32_16x16x32_bf16 v[112:115], v[228:231], v[150:153], v[112:115]
	v_mfma_f32_16x16x32_bf16 v[100:103], v[218:221], v[158:161], v[100:103]
	v_mfma_f32_16x16x32_bf16 v[96:99], v[228:231], v[158:161], v[96:99]
	v_mfma_f32_16x16x32_bf16 v[84:87], v[218:221], v[166:169], v[84:87]
	v_mfma_f32_16x16x32_bf16 v[80:83], v[228:231], v[166:169], v[80:83]
	v_mfma_f32_16x16x32_bf16 v[68:71], v[218:221], v[198:201], v[68:71]
	v_mfma_f32_16x16x32_bf16 v[64:67], v[228:231], v[198:201], v[64:67]
	s_barrier
	s_setprio 0
	s_mov_b32 m0, s30
	v_lshl_add_u64 v[176:177], v[234:235], 0, s[18:19]
	ds_read_b128 v[146:149], v217 offset:49152
	ds_read_b128 v[150:153], v217 offset:50176
	ds_read_b128 v[154:157], v217 offset:51200
	ds_read_b128 v[158:161], v217 offset:52224
	ds_read_b128 v[162:165], v217 offset:53248
	ds_read_b128 v[166:169], v217 offset:54272
	ds_read_b128 v[194:197], v217 offset:55296
	ds_read_b128 v[198:201], v217 offset:56320
	global_load_lds_dwordx4 v[176:177], off
	v_lshl_add_u64 v[176:177], v[236:237], 0, s[18:19]
	s_mov_b32 m0, s31
	s_nop 0
	global_load_lds_dwordx4 v[176:177], off
	s_setprio 1
	s_barrier
	s_waitcnt lgkmcnt(0)
	v_mfma_f32_16x16x32_bf16 v[60:63], v[128:131], v[146:149], v[60:63]
	v_mfma_f32_16x16x32_bf16 v[56:59], v[136:139], v[146:149], v[56:59]
	v_mfma_f32_16x16x32_bf16 v[44:47], v[128:131], v[154:157], v[44:47]
	v_mfma_f32_16x16x32_bf16 v[40:43], v[136:139], v[154:157], v[40:43]
	v_mfma_f32_16x16x32_bf16 v[28:31], v[128:131], v[162:165], v[28:31]
	v_mfma_f32_16x16x32_bf16 v[24:27], v[136:139], v[162:165], v[24:27]
	v_mfma_f32_16x16x32_bf16 v[12:15], v[128:131], v[194:197], v[12:15]
	v_mfma_f32_16x16x32_bf16 v[8:11], v[136:139], v[194:197], v[8:11]
	v_mfma_f32_16x16x32_bf16 v[60:63], v[132:135], v[150:153], v[60:63]
	v_mfma_f32_16x16x32_bf16 v[56:59], v[140:143], v[150:153], v[56:59]
	v_mfma_f32_16x16x32_bf16 v[44:47], v[132:135], v[158:161], v[44:47]
	v_mfma_f32_16x16x32_bf16 v[40:43], v[140:143], v[158:161], v[40:43]
	v_mfma_f32_16x16x32_bf16 v[28:31], v[132:135], v[166:169], v[28:31]
	v_mfma_f32_16x16x32_bf16 v[24:27], v[140:143], v[166:169], v[24:27]
	v_mfma_f32_16x16x32_bf16 v[12:15], v[132:135], v[198:201], v[12:15]
	v_mfma_f32_16x16x32_bf16 v[8:11], v[140:143], v[198:201], v[8:11]
	s_barrier
	s_setprio 0
	s_add_i32 s27, s44, s84
	v_lshl_add_u64 v[128:129], v[238:239], 0, s[18:19]
	s_mov_b32 m0, s27
	s_nop 0
	global_load_lds_dwordx4 v[128:129], off
	v_lshl_add_u64 v[128:129], v[240:241], 0, s[18:19]
	s_add_i32 m0, s27, 0x2000
	s_nop 0
	global_load_lds_dwordx4 v[128:129], off
	s_waitcnt vmcnt(6)
	s_setprio 1
	s_barrier
	v_mfma_f32_16x16x32_bf16 v[52:55], v[202:205], v[146:149], v[52:55]
	v_mfma_f32_16x16x32_bf16 v[48:51], v[222:225], v[146:149], v[48:51]
	v_mfma_f32_16x16x32_bf16 v[36:39], v[202:205], v[154:157], v[36:39]
	v_mfma_f32_16x16x32_bf16 v[32:35], v[222:225], v[154:157], v[32:35]
	v_mfma_f32_16x16x32_bf16 v[20:23], v[202:205], v[162:165], v[20:23]
	v_mfma_f32_16x16x32_bf16 v[16:19], v[222:225], v[162:165], v[16:19]
	v_mfma_f32_16x16x32_bf16 v[4:7], v[202:205], v[194:197], v[4:7]
	v_mfma_f32_16x16x32_bf16 v[0:3], v[222:225], v[194:197], v[0:3]
	v_mfma_f32_16x16x32_bf16 v[52:55], v[218:221], v[150:153], v[52:55]
	v_mfma_f32_16x16x32_bf16 v[48:51], v[228:231], v[150:153], v[48:51]
	v_mfma_f32_16x16x32_bf16 v[36:39], v[218:221], v[158:161], v[36:39]
	v_mfma_f32_16x16x32_bf16 v[32:35], v[228:231], v[158:161], v[32:35]
	v_mfma_f32_16x16x32_bf16 v[20:23], v[218:221], v[166:169], v[20:23]
	v_mfma_f32_16x16x32_bf16 v[16:19], v[228:231], v[166:169], v[16:19]
	v_mfma_f32_16x16x32_bf16 v[4:7], v[218:221], v[198:201], v[4:7]
	v_mfma_f32_16x16x32_bf16 v[0:3], v[228:231], v[198:201], v[0:3]
	s_barrier
	s_setprio 0
	s_add_u32 s42, s42, 0x100
	s_addc_u32 s43, s43, 0
	s_add_u32 s33, s33, 0x100
	s_addc_u32 s37, s37, 0
	s_cmp_ge_u32 s56, s34
	s_mov_b32 s27, s56
	s_cbranch_scc0 .LBB0_196
	v_lshl_add_u32 v194, s11, 8, v206
	v_ashrrev_i32_e32 v195, 31, v194
	v_lshl_or_b32 v196, s10, 8, v216
	v_lshlrev_b64 v[128:129], 11, v[194:195]
	v_ashrrev_i32_e32 v197, 31, v196
	s_and_b64 vcc, exec, s[92:93]
	v_or_b32_e32 v198, 16, v194
	v_lshl_add_u64 v[200:201], s[54:55], 0, v[128:129]
	s_cbranch_vccz .LBB0_215
	v_lshlrev_b64 v[128:129], 12, v[194:195]
	v_lshl_add_u64 v[128:129], s[50:51], 0, v[128:129]
	v_lshlrev_b64 v[130:131], 2, v[196:197]
	v_lshl_add_u64 v[128:129], v[128:129], 0, v[130:131]
	global_load_dwordx4 v[146:149], v[128:129], off offset:16
	global_load_dwordx4 v[150:153], v[128:129], off
	global_load_dwordx4 v[154:157], v[128:129], off offset:528
	global_load_dwordx4 v[158:161], v[128:129], off offset:512
	v_ashrrev_i32_e32 v199, 31, v198
	v_lshlrev_b64 v[128:129], 12, v[198:199]
	v_lshl_add_u64 v[128:129], s[50:51], 0, v[128:129]
	v_lshl_add_u64 v[132:133], v[128:129], 0, v[130:131]
	global_load_dwordx4 v[136:139], v[132:133], off offset:16
	global_load_dwordx4 v[140:143], v[132:133], off
	global_load_dwordx4 v[128:131], v[132:133], off offset:528
	s_nop 0
	global_load_dwordx4 v[132:135], v[132:133], off offset:512
	v_lshl_add_u64 v[166:167], v[196:197], 1, v[200:201]
	s_waitcnt vmcnt(0)
	v_pk_add_f32 v[164:165], v[120:121], v[146:147]
	v_pk_add_f32 v[152:153], v[126:127], v[152:153]
	v_pk_add_f32 v[150:151], v[124:125], v[150:151]
	v_pk_add_f32 v[162:163], v[122:123], v[148:149]
	v_cvt_pk_bf16_f32 v146, v150, v151
	v_cvt_pk_bf16_f32 v147, v152, v153
	v_cvt_pk_bf16_f32 v148, v164, v165
	v_pk_add_f32 v[156:157], v[114:115], v[156:157]
	v_cvt_pk_bf16_f32 v149, v162, v163
	global_store_dwordx4 v[166:167], v[146:149], off
	v_pk_add_f32 v[154:155], v[112:113], v[154:155]
	s_nop 0
	v_mul_f32_e32 v146, v151, v151
	v_mul_f32_e32 v147, v153, v153
	v_fmac_f32_e32 v146, v150, v150
	v_fmac_f32_e32 v147, v152, v152
	v_add_f32_e32 v146, v146, v147
	v_mul_f32_e32 v147, v165, v165
	v_mul_f32_e32 v148, v163, v163
	v_fmac_f32_e32 v147, v164, v164
	v_fmac_f32_e32 v148, v162, v162
	v_add_f32_e32 v147, v147, v148
	v_add_f32_e32 v162, v146, v147
	v_pk_add_f32 v[150:151], v[118:119], v[160:161]
	v_pk_add_f32 v[152:153], v[116:117], v[158:159]
	s_nop 0
	v_cvt_pk_bf16_f32 v146, v152, v153
	v_cvt_pk_bf16_f32 v147, v150, v151
	v_cvt_pk_bf16_f32 v148, v154, v155
	v_cvt_pk_bf16_f32 v149, v156, v157
	global_store_dwordx4 v[166:167], v[146:149], off offset:256
	s_nop 1
	v_mul_f32_e32 v146, v153, v153
	v_mul_f32_e32 v147, v151, v151
	v_fmac_f32_e32 v146, v152, v152
	v_fmac_f32_e32 v147, v150, v150
	v_add_f32_e32 v146, v146, v147
	v_mul_f32_e32 v147, v155, v155
	v_mul_f32_e32 v148, v157, v157
	v_fmac_f32_e32 v147, v154, v154
	v_fmac_f32_e32 v148, v156, v156
	v_add_f32_e32 v147, v147, v148
	v_and_b32_e32 v148, 64, v214
	v_add_f32_e32 v146, v146, v147
	v_xor_b32_e32 v147, 16, v214
	v_add_u32_e32 v148, 64, v148
	v_cmp_lt_i32_e32 vcc, v147, v148
	v_add_f32_e32 v146, v162, v146
	s_nop 0
	v_cndmask_b32_e32 v147, v214, v147, vcc
	v_lshlrev_b32_e32 v218, 2, v147
	ds_bpermute_b32 v147, v218, v146
	s_waitcnt lgkmcnt(0)
	v_add_f32_e32 v146, v146, v147
	v_xor_b32_e32 v147, 32, v214
	v_cmp_lt_i32_e32 vcc, v147, v148
	s_nop 1
	v_cndmask_b32_e32 v147, v214, v147, vcc
	v_lshlrev_b32_e32 v219, 2, v147
	ds_bpermute_b32 v147, v219, v146
	s_and_saveexec_b64 s[42:43], s[38:39]
	s_cbranch_execz .LBB0_200
	s_waitcnt lgkmcnt(0)
	v_add_f32_e32 v146, v146, v147
	v_fma_f32 v146, v146, s91, 0.5
	v_trunc_f32_e32 v146, v146
	v_mul_f32_e32 v147, 0x2f800000, v146
	v_floor_f32_e32 v147, v147
	v_fmac_f32_e32 v146, 0xcf800000, v147
	v_cvt_u32_f32_e32 v146, v146
	v_cvt_u32_f32_e32 v147, v147
	v_lshl_add_u64 v[148:149], v[194:195], 3, s[52:53]
	global_atomic_add_x2 v[148:149], v[146:147], off

.LBB0_325:
	s_ashr_i32 s93, s92, 31
	s_lshl_b64 s[30:31], s[92:93], 19
	s_add_u32 s94, s54, s30
	v_cmp_lt_i64_e32 vcc, s[50:51], v[186:187]
	s_addc_u32 s95, s55, s31
	s_and_b64 s[30:31], vcc, exec
	s_cselect_b32 s1, s95, s53
	s_cselect_b32 s11, s94, s52
	s_ashr_i32 s9, s8, 31
	s_lshl_b64 s[30:31], s[8:9], 19
	s_add_u32 s28, s80, s30
	s_addc_u32 s29, s78, s31
	s_and_b64 s[30:31], vcc, exec
	s_cselect_b32 s25, s29, s73
	s_cselect_b32 s30, s28, s72
	s_add_u32 s52, s52, 0x40080
	s_addc_u32 s53, s53, 0
	s_add_u32 s31, s72, 0x100
	s_addc_u32 s33, s73, 0
	s_mov_b32 s34, -2
	s_add_u32 s27, s52, 0xfffc0080
	s_addc_u32 s35, s53, -1
	s_add_i32 s36, 0, 0x10000
	v_add_u32_e32 v140, s36, v216
	ds_read_b128 v[128:131], v140
	ds_read_b128 v[132:135], v140 offset:1024
	ds_read_b128 v[136:139], v140 offset:2048
	ds_read_b128 v[140:143], v140 offset:3072
	s_cmp_eq_u32 s34, 12
	s_cselect_b32 s75, s1, s35
	s_cselect_b32 s74, s11, s27
	s_cselect_b32 s73, s25, s33
	s_cselect_b32 s72, s30, s31
	v_lshl_add_u64 v[168:169], s[52:53], 0, v[152:153]
	s_add_i32 m0, s83, 0xc000
	ds_read_b128 v[156:159], v217
	ds_read_b128 v[160:163], v217 offset:1024
	ds_read_b128 v[164:167], v217 offset:2048
	ds_read_b128 v[188:191], v217 offset:3072
	ds_read_b128 v[192:195], v217 offset:4096
	ds_read_b128 v[196:199], v217 offset:5120
	ds_read_b128 v[200:203], v217 offset:6144
	ds_read_b128 v[204:207], v217 offset:7168
	global_load_lds_dwordx4 v[168:169], off
	v_lshl_add_u64 v[168:169], s[52:53], 0, v[154:155]
	s_add_i32 m0, s83, 0xe000
	s_nop 0
	global_load_lds_dwordx4 v[168:169], off
	s_waitcnt lgkmcnt(8)
	s_setprio 1
	s_barrier
	s_waitcnt lgkmcnt(0)
	v_mfma_f32_16x16x32_bf16 v[124:127], v[128:131], v[156:159], 0
	v_mfma_f32_16x16x32_bf16 v[120:123], v[136:139], v[156:159], 0
	v_mfma_f32_16x16x32_bf16 v[108:111], v[128:131], v[164:167], 0
	v_mfma_f32_16x16x32_bf16 v[104:107], v[136:139], v[164:167], 0
	v_mfma_f32_16x16x32_bf16 v[92:95], v[128:131], v[192:195], 0
	v_mfma_f32_16x16x32_bf16 v[88:91], v[136:139], v[192:195], 0
	v_mfma_f32_16x16x32_bf16 v[76:79], v[128:131], v[200:203], 0
	v_mfma_f32_16x16x32_bf16 v[72:75], v[136:139], v[200:203], 0
	v_mfma_f32_16x16x32_bf16 v[124:127], v[132:135], v[160:163], v[124:127]
	v_mfma_f32_16x16x32_bf16 v[120:123], v[140:143], v[160:163], v[120:123]
	v_mfma_f32_16x16x32_bf16 v[108:111], v[132:135], v[188:191], v[108:111]
	v_mfma_f32_16x16x32_bf16 v[104:107], v[140:143], v[188:191], v[104:107]
	v_mfma_f32_16x16x32_bf16 v[92:95], v[132:135], v[196:199], v[92:95]
	v_mfma_f32_16x16x32_bf16 v[88:91], v[140:143], v[196:199], v[88:91]
	v_mfma_f32_16x16x32_bf16 v[76:79], v[132:135], v[204:207], v[76:79]
	v_mfma_f32_16x16x32_bf16 v[72:75], v[140:143], v[204:207], v[72:75]
	s_barrier
	s_setprio 0
	s_add_i32 s27, 0, 0x14000
	s_add_i32 s35, s36, s81
	v_add_u32_e32 v144, s27, v216
	v_lshl_add_u64 v[168:169], s[72:73], 0, v[148:149]
	s_mov_b32 m0, s35
	ds_read_b128 v[220:223], v144
	ds_read_b128 v[228:231], v144 offset:1024
	ds_read_b128 v[232:235], v144 offset:2048
	ds_read_b128 v[236:239], v144 offset:3072
	global_load_lds_dwordx4 v[168:169], off
	v_lshl_add_u64 v[176:177], s[72:73], 0, v[146:147]
	s_add_i32 m0, s35, 0x2000
	s_nop 0
	global_load_lds_dwordx4 v[176:177], off
	s_setprio 1
	s_barrier
	s_waitcnt lgkmcnt(0)
	v_mfma_f32_16x16x32_bf16 v[116:119], v[220:223], v[156:159], 0
	v_mfma_f32_16x16x32_bf16 v[112:115], v[232:235], v[156:159], 0
	v_mfma_f32_16x16x32_bf16 v[100:103], v[220:223], v[164:167], 0
	v_mfma_f32_16x16x32_bf16 v[96:99], v[232:235], v[164:167], 0
	v_mfma_f32_16x16x32_bf16 v[84:87], v[220:223], v[192:195], 0
	v_mfma_f32_16x16x32_bf16 v[80:83], v[232:235], v[192:195], 0
	v_mfma_f32_16x16x32_bf16 v[68:71], v[220:223], v[200:203], 0
	v_mfma_f32_16x16x32_bf16 v[64:67], v[232:235], v[200:203], 0
	v_mfma_f32_16x16x32_bf16 v[116:119], v[228:231], v[160:163], v[116:119]
	v_mfma_f32_16x16x32_bf16 v[112:115], v[236:239], v[160:163], v[112:115]
	v_mfma_f32_16x16x32_bf16 v[100:103], v[228:231], v[188:191], v[100:103]
	v_mfma_f32_16x16x32_bf16 v[96:99], v[236:239], v[188:191], v[96:99]
	v_mfma_f32_16x16x32_bf16 v[84:87], v[228:231], v[196:199], v[84:87]
	v_mfma_f32_16x16x32_bf16 v[80:83], v[236:239], v[196:199], v[80:83]
	v_mfma_f32_16x16x32_bf16 v[68:71], v[228:231], v[204:207], v[68:71]
	v_mfma_f32_16x16x32_bf16 v[64:67], v[236:239], v[204:207], v[64:67]
	s_barrier
	s_setprio 0
	s_mov_b32 m0, s83
	v_lshl_add_u64 v[224:225], s[74:75], 0, v[148:149]
	ds_read_b128 v[156:159], v217 offset:16384
	ds_read_b128 v[160:163], v217 offset:17408
	ds_read_b128 v[164:167], v217 offset:18432
	ds_read_b128 v[188:191], v217 offset:19456
	ds_read_b128 v[192:195], v217 offset:20480
	ds_read_b128 v[196:199], v217 offset:21504
	ds_read_b128 v[200:203], v217 offset:22528
	ds_read_b128 v[204:207], v217 offset:23552
	global_load_lds_dwordx4 v[224:225], off
	v_lshl_add_u64 v[240:241], s[74:75], 0, v[146:147]
	s_mov_b32 m0, s84
	s_nop 0
	global_load_lds_dwordx4 v[240:241], off
	s_setprio 1
	s_barrier
	s_waitcnt lgkmcnt(0)
	v_mfma_f32_16x16x32_bf16 v[60:63], v[128:131], v[156:159], 0
	v_mfma_f32_16x16x32_bf16 v[56:59], v[136:139], v[156:159], 0
	v_mfma_f32_16x16x32_bf16 v[44:47], v[128:131], v[164:167], 0
	v_mfma_f32_16x16x32_bf16 v[40:43], v[136:139], v[164:167], 0
	v_mfma_f32_16x16x32_bf16 v[28:31], v[128:131], v[192:195], 0
	v_mfma_f32_16x16x32_bf16 v[24:27], v[136:139], v[192:195], 0
	v_mfma_f32_16x16x32_bf16 v[12:15], v[128:131], v[200:203], 0
	v_mfma_f32_16x16x32_bf16 v[8:11], v[136:139], v[200:203], 0
	v_mfma_f32_16x16x32_bf16 v[60:63], v[132:135], v[160:163], v[60:63]
	v_mfma_f32_16x16x32_bf16 v[56:59], v[140:143], v[160:163], v[56:59]
	v_mfma_f32_16x16x32_bf16 v[44:47], v[132:135], v[188:191], v[44:47]
	v_mfma_f32_16x16x32_bf16 v[40:43], v[140:143], v[188:191], v[40:43]
	v_mfma_f32_16x16x32_bf16 v[28:31], v[132:135], v[196:199], v[28:31]
	v_mfma_f32_16x16x32_bf16 v[24:27], v[140:143], v[196:199], v[24:27]
	v_mfma_f32_16x16x32_bf16 v[12:15], v[132:135], v[204:207], v[12:15]
	v_mfma_f32_16x16x32_bf16 v[8:11], v[140:143], v[204:207], v[8:11]
	s_barrier
	s_setprio 0
	s_add_u32 s36, s72, 0x40000
	s_addc_u32 s37, s73, 0
	s_add_i32 s27, s27, s81
	v_lshl_add_u64 v[128:129], s[36:37], 0, v[148:149]
	s_mov_b32 m0, s27
	s_nop 0
	global_load_lds_dwordx4 v[128:129], off
	v_lshl_add_u64 v[128:129], s[36:37], 0, v[146:147]
	s_add_i32 m0, s27, 0x2000
	s_nop 0
	global_load_lds_dwordx4 v[128:129], off
	s_waitcnt vmcnt(6)
	s_setprio 1
	s_barrier
	v_mfma_f32_16x16x32_bf16 v[52:55], v[220:223], v[156:159], 0
	v_mfma_f32_16x16x32_bf16 v[48:51], v[232:235], v[156:159], 0
	v_mfma_f32_16x16x32_bf16 v[36:39], v[220:223], v[164:167], 0
	v_mfma_f32_16x16x32_bf16 v[32:35], v[232:235], v[164:167], 0
	v_mfma_f32_16x16x32_bf16 v[20:23], v[220:223], v[192:195], 0
	v_mfma_f32_16x16x32_bf16 v[16:19], v[232:235], v[192:195], 0
	v_mfma_f32_16x16x32_bf16 v[4:7], v[220:223], v[200:203], 0
	v_mfma_f32_16x16x32_bf16 v[0:3], v[232:235], v[200:203], 0
	v_mfma_f32_16x16x32_bf16 v[52:55], v[228:231], v[160:163], v[52:55]
	v_mfma_f32_16x16x32_bf16 v[48:51], v[236:239], v[160:163], v[48:51]
	v_mfma_f32_16x16x32_bf16 v[36:39], v[228:231], v[188:191], v[36:39]
	v_mfma_f32_16x16x32_bf16 v[32:35], v[236:239], v[188:191], v[32:35]
	v_mfma_f32_16x16x32_bf16 v[20:23], v[228:231], v[196:199], v[20:23]
	v_mfma_f32_16x16x32_bf16 v[16:19], v[236:239], v[196:199], v[16:19]
	v_mfma_f32_16x16x32_bf16 v[4:7], v[228:231], v[204:207], v[4:7]
	v_mfma_f32_16x16x32_bf16 v[0:3], v[236:239], v[204:207], v[0:3]
	s_barrier
	s_setprio 0
	s_add_i32 s27, 0, 0x18000
	v_add_u32_e32 v140, s27, v216
	ds_read_b128 v[128:131], v140
	ds_read_b128 v[132:135], v140 offset:1024
	ds_read_b128 v[136:139], v140 offset:2048
	ds_read_b128 v[140:143], v140 offset:3072
	s_add_u32 s36, s74, 0x40000
	s_addc_u32 s37, s75, 0
	s_mov_b32 m0, s85
	v_lshl_add_u64 v[220:221], s[36:37], 0, v[148:149]
	ds_read_b128 v[156:159], v217 offset:32768
	ds_read_b128 v[160:163], v217 offset:33792
	ds_read_b128 v[164:167], v217 offset:34816
	ds_read_b128 v[188:191], v217 offset:35840
	ds_read_b128 v[192:195], v217 offset:36864
	ds_read_b128 v[196:199], v217 offset:37888
	ds_read_b128 v[200:203], v217 offset:38912
	ds_read_b128 v[204:207], v217 offset:39936
	global_load_lds_dwordx4 v[220:221], off
	v_lshl_add_u64 v[220:221], s[36:37], 0, v[146:147]
	s_mov_b32 m0, s86
	s_nop 0
	global_load_lds_dwordx4 v[220:221], off
	s_waitcnt lgkmcnt(8)
	s_setprio 1
	s_barrier
	s_waitcnt lgkmcnt(0)
	v_mfma_f32_16x16x32_bf16 v[124:127], v[128:131], v[156:159], v[124:127]
	v_mfma_f32_16x16x32_bf16 v[120:123], v[136:139], v[156:159], v[120:123]
	v_mfma_f32_16x16x32_bf16 v[108:111], v[128:131], v[164:167], v[108:111]
	v_mfma_f32_16x16x32_bf16 v[104:107], v[136:139], v[164:167], v[104:107]
	v_mfma_f32_16x16x32_bf16 v[92:95], v[128:131], v[192:195], v[92:95]
	v_mfma_f32_16x16x32_bf16 v[88:91], v[136:139], v[192:195], v[88:91]
	v_mfma_f32_16x16x32_bf16 v[76:79], v[128:131], v[200:203], v[76:79]
	v_mfma_f32_16x16x32_bf16 v[72:75], v[136:139], v[200:203], v[72:75]
	v_mfma_f32_16x16x32_bf16 v[124:127], v[132:135], v[160:163], v[124:127]
	v_mfma_f32_16x16x32_bf16 v[120:123], v[140:143], v[160:163], v[120:123]
	v_mfma_f32_16x16x32_bf16 v[108:111], v[132:135], v[188:191], v[108:111]
	v_mfma_f32_16x16x32_bf16 v[104:107], v[140:143], v[188:191], v[104:107]
	v_mfma_f32_16x16x32_bf16 v[92:95], v[132:135], v[196:199], v[92:95]
	v_mfma_f32_16x16x32_bf16 v[88:91], v[140:143], v[196:199], v[88:91]
	v_mfma_f32_16x16x32_bf16 v[76:79], v[132:135], v[204:207], v[76:79]
	v_mfma_f32_16x16x32_bf16 v[72:75], v[140:143], v[204:207], v[72:75]
	s_barrier
	s_setprio 0
	s_add_i32 s35, 0, 0x1c000
	s_add_i32 s27, s27, s81
	v_add_u32_e32 v144, s35, v216
	v_lshl_add_u64 v[168:169], v[168:169], 0, s[18:19]
	s_mov_b32 m0, s27
	ds_read_b128 v[220:223], v144
	ds_read_b128 v[228:231], v144 offset:1024
	ds_read_b128 v[232:235], v144 offset:2048
	ds_read_b128 v[236:239], v144 offset:3072
	global_load_lds_dwordx4 v[168:169], off
	v_lshl_add_u64 v[168:169], v[176:177], 0, s[18:19]
	s_add_i32 m0, s27, 0x2000
	s_nop 0
	global_load_lds_dwordx4 v[168:169], off
	s_setprio 1
	s_barrier
	s_waitcnt lgkmcnt(0)
	v_mfma_f32_16x16x32_bf16 v[116:119], v[220:223], v[156:159], v[116:119]
	v_mfma_f32_16x16x32_bf16 v[112:115], v[232:235], v[156:159], v[112:115]
	v_mfma_f32_16x16x32_bf16 v[100:103], v[220:223], v[164:167], v[100:103]
	v_mfma_f32_16x16x32_bf16 v[96:99], v[232:235], v[164:167], v[96:99]
	v_mfma_f32_16x16x32_bf16 v[84:87], v[220:223], v[192:195], v[84:87]
	v_mfma_f32_16x16x32_bf16 v[80:83], v[232:235], v[192:195], v[80:83]
	v_mfma_f32_16x16x32_bf16 v[68:71], v[220:223], v[200:203], v[68:71]
	v_mfma_f32_16x16x32_bf16 v[64:67], v[232:235], v[200:203], v[64:67]
	v_mfma_f32_16x16x32_bf16 v[116:119], v[228:231], v[160:163], v[116:119]
	v_mfma_f32_16x16x32_bf16 v[112:115], v[236:239], v[160:163], v[112:115]
	v_mfma_f32_16x16x32_bf16 v[100:103], v[228:231], v[188:191], v[100:103]
	v_mfma_f32_16x16x32_bf16 v[96:99], v[236:239], v[188:191], v[96:99]
	v_mfma_f32_16x16x32_bf16 v[84:87], v[228:231], v[196:199], v[84:87]
	v_mfma_f32_16x16x32_bf16 v[80:83], v[236:239], v[196:199], v[80:83]
	v_mfma_f32_16x16x32_bf16 v[68:71], v[228:231], v[204:207], v[68:71]
	v_mfma_f32_16x16x32_bf16 v[64:67], v[236:239], v[204:207], v[64:67]
	s_barrier
	s_setprio 0
	s_mov_b32 m0, s87
	v_lshl_add_u64 v[168:169], v[224:225], 0, s[18:19]
	ds_read_b128 v[156:159], v217 offset:49152
	ds_read_b128 v[160:163], v217 offset:50176
	ds_read_b128 v[164:167], v217 offset:51200
	ds_read_b128 v[188:191], v217 offset:52224
	ds_read_b128 v[192:195], v217 offset:53248
	ds_read_b128 v[196:199], v217 offset:54272
	ds_read_b128 v[200:203], v217 offset:55296
	ds_read_b128 v[204:207], v217 offset:56320
	global_load_lds_dwordx4 v[168:169], off
	v_lshl_add_u64 v[168:169], v[240:241], 0, s[18:19]
	s_mov_b32 m0, s79
	s_nop 0
	global_load_lds_dwordx4 v[168:169], off
	s_setprio 1
	s_barrier
	s_waitcnt lgkmcnt(0)
	v_mfma_f32_16x16x32_bf16 v[60:63], v[128:131], v[156:159], v[60:63]
	v_mfma_f32_16x16x32_bf16 v[56:59], v[136:139], v[156:159], v[56:59]
	v_mfma_f32_16x16x32_bf16 v[44:47], v[128:131], v[164:167], v[44:47]
	v_mfma_f32_16x16x32_bf16 v[40:43], v[136:139], v[164:167], v[40:43]
	v_mfma_f32_16x16x32_bf16 v[28:31], v[128:131], v[192:195], v[28:31]
	v_mfma_f32_16x16x32_bf16 v[24:27], v[136:139], v[192:195], v[24:27]
	v_mfma_f32_16x16x32_bf16 v[12:15], v[128:131], v[200:203], v[12:15]
	v_mfma_f32_16x16x32_bf16 v[8:11], v[136:139], v[200:203], v[8:11]
	v_mfma_f32_16x16x32_bf16 v[60:63], v[132:135], v[160:163], v[60:63]
	v_mfma_f32_16x16x32_bf16 v[56:59], v[140:143], v[160:163], v[56:59]
	v_mfma_f32_16x16x32_bf16 v[44:47], v[132:135], v[188:191], v[44:47]
	v_mfma_f32_16x16x32_bf16 v[40:43], v[140:143], v[188:191], v[40:43]
	v_mfma_f32_16x16x32_bf16 v[28:31], v[132:135], v[196:199], v[28:31]
	v_mfma_f32_16x16x32_bf16 v[24:27], v[140:143], v[196:199], v[24:27]
	v_mfma_f32_16x16x32_bf16 v[12:15], v[132:135], v[204:207], v[12:15]
	v_mfma_f32_16x16x32_bf16 v[8:11], v[140:143], v[204:207], v[8:11]
	s_barrier
	s_setprio 0
	s_add_u32 s36, s72, 0x40080
	s_addc_u32 s37, s73, 0
	s_add_i32 s27, s35, s81
	v_lshl_add_u64 v[128:129], s[36:37], 0, v[148:149]
	s_mov_b32 m0, s27
	s_nop 0
	global_load_lds_dwordx4 v[128:129], off
	v_lshl_add_u64 v[128:129], s[36:37], 0, v[146:147]
	s_add_i32 m0, s27, 0x2000
	s_nop 0
	global_load_lds_dwordx4 v[128:129], off
	s_waitcnt vmcnt(6)
	s_setprio 1
	s_barrier
	v_mfma_f32_16x16x32_bf16 v[52:55], v[220:223], v[156:159], v[52:55]
	v_mfma_f32_16x16x32_bf16 v[48:51], v[232:235], v[156:159], v[48:51]
	v_mfma_f32_16x16x32_bf16 v[36:39], v[220:223], v[164:167], v[36:39]
	v_mfma_f32_16x16x32_bf16 v[32:35], v[232:235], v[164:167], v[32:35]
	v_mfma_f32_16x16x32_bf16 v[20:23], v[220:223], v[192:195], v[20:23]
	v_mfma_f32_16x16x32_bf16 v[16:19], v[232:235], v[192:195], v[16:19]
	v_mfma_f32_16x16x32_bf16 v[4:7], v[220:223], v[200:203], v[4:7]
	v_mfma_f32_16x16x32_bf16 v[0:3], v[232:235], v[200:203], v[0:3]
	v_mfma_f32_16x16x32_bf16 v[52:55], v[228:231], v[160:163], v[52:55]
	v_mfma_f32_16x16x32_bf16 v[48:51], v[236:239], v[160:163], v[48:51]
	v_mfma_f32_16x16x32_bf16 v[36:39], v[228:231], v[188:191], v[36:39]
	v_mfma_f32_16x16x32_bf16 v[32:35], v[236:239], v[188:191], v[32:35]
	v_mfma_f32_16x16x32_bf16 v[20:23], v[228:231], v[196:199], v[20:23]
	v_mfma_f32_16x16x32_bf16 v[16:19], v[236:239], v[196:199], v[16:19]
	v_mfma_f32_16x16x32_bf16 v[4:7], v[228:231], v[204:207], v[4:7]
	v_mfma_f32_16x16x32_bf16 v[0:3], v[236:239], v[204:207], v[0:3]
	s_barrier
	s_setprio 0
	s_add_i32 s34, s34, 2
	s_add_u32 s52, s52, 0x100
	s_addc_u32 s53, s53, 0
	s_add_u32 s31, s31, 0x100
	s_addc_u32 s33, s33, 0
	s_cmp_gt_u32 s34, 13
.LBB0_326:
	s_add_u32 s27, s52, 0xfffc0080
	s_addc_u32 s35, s53, -1
	s_add_i32 s36, 0, 0x10000
	v_add_u32_e32 v140, s36, v216
	ds_read_b128 v[128:131], v140
	ds_read_b128 v[132:135], v140 offset:1024
	ds_read_b128 v[136:139], v140 offset:2048
	ds_read_b128 v[140:143], v140 offset:3072
	s_cmp_eq_u32 s34, 12
	s_cselect_b32 s75, s1, s35
	s_cselect_b32 s74, s11, s27
	s_cselect_b32 s73, s25, s33
	s_cselect_b32 s72, s30, s31
	v_lshl_add_u64 v[168:169], s[52:53], 0, v[152:153]
	s_add_i32 m0, s83, 0xc000
	ds_read_b128 v[156:159], v217
	ds_read_b128 v[160:163], v217 offset:1024
	ds_read_b128 v[164:167], v217 offset:2048
	ds_read_b128 v[188:191], v217 offset:3072
	ds_read_b128 v[192:195], v217 offset:4096
	ds_read_b128 v[196:199], v217 offset:5120
	ds_read_b128 v[200:203], v217 offset:6144
	ds_read_b128 v[204:207], v217 offset:7168
	global_load_lds_dwordx4 v[168:169], off
	v_lshl_add_u64 v[168:169], s[52:53], 0, v[154:155]
	s_add_i32 m0, s83, 0xe000
	s_nop 0
	global_load_lds_dwordx4 v[168:169], off
	s_waitcnt lgkmcnt(8)
	s_setprio 1
	s_barrier
	s_waitcnt lgkmcnt(0)
	v_mfma_f32_16x16x32_bf16 v[124:127], v[128:131], v[156:159], v[124:127]
	v_mfma_f32_16x16x32_bf16 v[120:123], v[136:139], v[156:159], v[120:123]
	v_mfma_f32_16x16x32_bf16 v[108:111], v[128:131], v[164:167], v[108:111]
	v_mfma_f32_16x16x32_bf16 v[104:107], v[136:139], v[164:167], v[104:107]
	v_mfma_f32_16x16x32_bf16 v[92:95], v[128:131], v[192:195], v[92:95]
	v_mfma_f32_16x16x32_bf16 v[88:91], v[136:139], v[192:195], v[88:91]
	v_mfma_f32_16x16x32_bf16 v[76:79], v[128:131], v[200:203], v[76:79]
	v_mfma_f32_16x16x32_bf16 v[72:75], v[136:139], v[200:203], v[72:75]
	v_mfma_f32_16x16x32_bf16 v[124:127], v[132:135], v[160:163], v[124:127]
	v_mfma_f32_16x16x32_bf16 v[120:123], v[140:143], v[160:163], v[120:123]
	v_mfma_f32_16x16x32_bf16 v[108:111], v[132:135], v[188:191], v[108:111]
	v_mfma_f32_16x16x32_bf16 v[104:107], v[140:143], v[188:191], v[104:107]
	v_mfma_f32_16x16x32_bf16 v[92:95], v[132:135], v[196:199], v[92:95]
	v_mfma_f32_16x16x32_bf16 v[88:91], v[140:143], v[196:199], v[88:91]
	v_mfma_f32_16x16x32_bf16 v[76:79], v[132:135], v[204:207], v[76:79]
	v_mfma_f32_16x16x32_bf16 v[72:75], v[140:143], v[204:207], v[72:75]
	s_barrier
	s_setprio 0
	s_add_i32 s27, 0, 0x14000
	s_add_i32 s35, s36, s81
	v_add_u32_e32 v144, s27, v216
	v_lshl_add_u64 v[168:169], s[72:73], 0, v[148:149]
	s_mov_b32 m0, s35
	ds_read_b128 v[220:223], v144
	ds_read_b128 v[228:231], v144 offset:1024
	ds_read_b128 v[232:235], v144 offset:2048
	ds_read_b128 v[236:239], v144 offset:3072
	global_load_lds_dwordx4 v[168:169], off
	v_lshl_add_u64 v[176:177], s[72:73], 0, v[146:147]
	s_add_i32 m0, s35, 0x2000
	s_nop 0
	global_load_lds_dwordx4 v[176:177], off
	s_setprio 1
	s_barrier
	s_waitcnt lgkmcnt(0)
	v_mfma_f32_16x16x32_bf16 v[116:119], v[220:223], v[156:159], v[116:119]
	v_mfma_f32_16x16x32_bf16 v[112:115], v[232:235], v[156:159], v[112:115]
	v_mfma_f32_16x16x32_bf16 v[100:103], v[220:223], v[164:167], v[100:103]
	v_mfma_f32_16x16x32_bf16 v[96:99], v[232:235], v[164:167], v[96:99]
	v_mfma_f32_16x16x32_bf16 v[84:87], v[220:223], v[192:195], v[84:87]
	v_mfma_f32_16x16x32_bf16 v[80:83], v[232:235], v[192:195], v[80:83]
	v_mfma_f32_16x16x32_bf16 v[68:71], v[220:223], v[200:203], v[68:71]
	v_mfma_f32_16x16x32_bf16 v[64:67], v[232:235], v[200:203], v[64:67]
	v_mfma_f32_16x16x32_bf16 v[116:119], v[228:231], v[160:163], v[116:119]
	v_mfma_f32_16x16x32_bf16 v[112:115], v[236:239], v[160:163], v[112:115]
	v_mfma_f32_16x16x32_bf16 v[100:103], v[228:231], v[188:191], v[100:103]
	v_mfma_f32_16x16x32_bf16 v[96:99], v[236:239], v[188:191], v[96:99]
	v_mfma_f32_16x16x32_bf16 v[84:87], v[228:231], v[196:199], v[84:87]
	v_mfma_f32_16x16x32_bf16 v[80:83], v[236:239], v[196:199], v[80:83]
	v_mfma_f32_16x16x32_bf16 v[68:71], v[228:231], v[204:207], v[68:71]
	v_mfma_f32_16x16x32_bf16 v[64:67], v[236:239], v[204:207], v[64:67]
	s_barrier
	s_setprio 0
	s_mov_b32 m0, s83
	v_lshl_add_u64 v[224:225], s[74:75], 0, v[148:149]
	ds_read_b128 v[156:159], v217 offset:16384
	ds_read_b128 v[160:163], v217 offset:17408
	ds_read_b128 v[164:167], v217 offset:18432
	ds_read_b128 v[188:191], v217 offset:19456
	ds_read_b128 v[192:195], v217 offset:20480
	ds_read_b128 v[196:199], v217 offset:21504
	ds_read_b128 v[200:203], v217 offset:22528
	ds_read_b128 v[204:207], v217 offset:23552
	global_load_lds_dwordx4 v[224:225], off
	v_lshl_add_u64 v[240:241], s[74:75], 0, v[146:147]
	s_mov_b32 m0, s84
	s_nop 0
	global_load_lds_dwordx4 v[240:241], off
	s_setprio 1
	s_barrier
	s_waitcnt lgkmcnt(0)
	v_mfma_f32_16x16x32_bf16 v[60:63], v[128:131], v[156:159], v[60:63]
	v_mfma_f32_16x16x32_bf16 v[56:59], v[136:139], v[156:159], v[56:59]
	v_mfma_f32_16x16x32_bf16 v[44:47], v[128:131], v[164:167], v[44:47]
	v_mfma_f32_16x16x32_bf16 v[40:43], v[136:139], v[164:167], v[40:43]
	v_mfma_f32_16x16x32_bf16 v[28:31], v[128:131], v[192:195], v[28:31]
	v_mfma_f32_16x16x32_bf16 v[24:27], v[136:139], v[192:195], v[24:27]
	v_mfma_f32_16x16x32_bf16 v[12:15], v[128:131], v[200:203], v[12:15]
	v_mfma_f32_16x16x32_bf16 v[8:11], v[136:139], v[200:203], v[8:11]
	v_mfma_f32_16x16x32_bf16 v[60:63], v[132:135], v[160:163], v[60:63]
	v_mfma_f32_16x16x32_bf16 v[56:59], v[140:143], v[160:163], v[56:59]
	v_mfma_f32_16x16x32_bf16 v[44:47], v[132:135], v[188:191], v[44:47]
	v_mfma_f32_16x16x32_bf16 v[40:43], v[140:143], v[188:191], v[40:43]
	v_mfma_f32_16x16x32_bf16 v[28:31], v[132:135], v[196:199], v[28:31]
	v_mfma_f32_16x16x32_bf16 v[24:27], v[140:143], v[196:199], v[24:27]
	v_mfma_f32_16x16x32_bf16 v[12:15], v[132:135], v[204:207], v[12:15]
	v_mfma_f32_16x16x32_bf16 v[8:11], v[140:143], v[204:207], v[8:11]
	s_barrier
	s_setprio 0
	s_add_u32 s36, s72, 0x40000
	s_addc_u32 s37, s73, 0
	s_add_i32 s27, s27, s81
	v_lshl_add_u64 v[128:129], s[36:37], 0, v[148:149]
	s_mov_b32 m0, s27
	s_nop 0
	global_load_lds_dwordx4 v[128:129], off
	v_lshl_add_u64 v[128:129], s[36:37], 0, v[146:147]
	s_add_i32 m0, s27, 0x2000
	s_nop 0
	global_load_lds_dwordx4 v[128:129], off
	s_waitcnt vmcnt(6)
	s_setprio 1
	s_barrier
	v_mfma_f32_16x16x32_bf16 v[52:55], v[220:223], v[156:159], v[52:55]
	v_mfma_f32_16x16x32_bf16 v[48:51], v[232:235], v[156:159], v[48:51]
	v_mfma_f32_16x16x32_bf16 v[36:39], v[220:223], v[164:167], v[36:39]
	v_mfma_f32_16x16x32_bf16 v[32:35], v[232:235], v[164:167], v[32:35]
	v_mfma_f32_16x16x32_bf16 v[20:23], v[220:223], v[192:195], v[20:23]
	v_mfma_f32_16x16x32_bf16 v[16:19], v[232:235], v[192:195], v[16:19]
	v_mfma_f32_16x16x32_bf16 v[4:7], v[220:223], v[200:203], v[4:7]
	v_mfma_f32_16x16x32_bf16 v[0:3], v[232:235], v[200:203], v[0:3]
	v_mfma_f32_16x16x32_bf16 v[52:55], v[228:231], v[160:163], v[52:55]
	v_mfma_f32_16x16x32_bf16 v[48:51], v[236:239], v[160:163], v[48:51]
	v_mfma_f32_16x16x32_bf16 v[36:39], v[228:231], v[188:191], v[36:39]
	v_mfma_f32_16x16x32_bf16 v[32:35], v[236:239], v[188:191], v[32:35]
	v_mfma_f32_16x16x32_bf16 v[20:23], v[228:231], v[196:199], v[20:23]
	v_mfma_f32_16x16x32_bf16 v[16:19], v[236:239], v[196:199], v[16:19]
	v_mfma_f32_16x16x32_bf16 v[4:7], v[228:231], v[204:207], v[4:7]
	v_mfma_f32_16x16x32_bf16 v[0:3], v[236:239], v[204:207], v[0:3]
	s_barrier
	s_setprio 0
	s_add_i32 s27, 0, 0x18000
	v_add_u32_e32 v140, s27, v216
	ds_read_b128 v[128:131], v140
	ds_read_b128 v[132:135], v140 offset:1024
	ds_read_b128 v[136:139], v140 offset:2048
	ds_read_b128 v[140:143], v140 offset:3072
	s_add_u32 s36, s74, 0x40000
	s_addc_u32 s37, s75, 0
	s_mov_b32 m0, s85
	v_lshl_add_u64 v[220:221], s[36:37], 0, v[148:149]
	ds_read_b128 v[156:159], v217 offset:32768
	ds_read_b128 v[160:163], v217 offset:33792
	ds_read_b128 v[164:167], v217 offset:34816
	ds_read_b128 v[188:191], v217 offset:35840
	ds_read_b128 v[192:195], v217 offset:36864
	ds_read_b128 v[196:199], v217 offset:37888
	ds_read_b128 v[200:203], v217 offset:38912
	ds_read_b128 v[204:207], v217 offset:39936
	global_load_lds_dwordx4 v[220:221], off
	v_lshl_add_u64 v[220:221], s[36:37], 0, v[146:147]
	s_mov_b32 m0, s86
	s_nop 0
	global_load_lds_dwordx4 v[220:221], off
	s_waitcnt lgkmcnt(8)
	s_setprio 1
	s_barrier
	s_waitcnt lgkmcnt(0)
	v_mfma_f32_16x16x32_bf16 v[124:127], v[128:131], v[156:159], v[124:127]
	v_mfma_f32_16x16x32_bf16 v[120:123], v[136:139], v[156:159], v[120:123]
	v_mfma_f32_16x16x32_bf16 v[108:111], v[128:131], v[164:167], v[108:111]
	v_mfma_f32_16x16x32_bf16 v[104:107], v[136:139], v[164:167], v[104:107]
	v_mfma_f32_16x16x32_bf16 v[92:95], v[128:131], v[192:195], v[92:95]
	v_mfma_f32_16x16x32_bf16 v[88:91], v[136:139], v[192:195], v[88:91]
	v_mfma_f32_16x16x32_bf16 v[76:79], v[128:131], v[200:203], v[76:79]
	v_mfma_f32_16x16x32_bf16 v[72:75], v[136:139], v[200:203], v[72:75]
	v_mfma_f32_16x16x32_bf16 v[124:127], v[132:135], v[160:163], v[124:127]
	v_mfma_f32_16x16x32_bf16 v[120:123], v[140:143], v[160:163], v[120:123]
	v_mfma_f32_16x16x32_bf16 v[108:111], v[132:135], v[188:191], v[108:111]
	v_mfma_f32_16x16x32_bf16 v[104:107], v[140:143], v[188:191], v[104:107]
	v_mfma_f32_16x16x32_bf16 v[92:95], v[132:135], v[196:199], v[92:95]
	v_mfma_f32_16x16x32_bf16 v[88:91], v[140:143], v[196:199], v[88:91]
	v_mfma_f32_16x16x32_bf16 v[76:79], v[132:135], v[204:207], v[76:79]
	v_mfma_f32_16x16x32_bf16 v[72:75], v[140:143], v[204:207], v[72:75]
	s_barrier
	s_setprio 0
	s_add_i32 s35, 0, 0x1c000
	s_add_i32 s27, s27, s81
	v_add_u32_e32 v144, s35, v216
	v_lshl_add_u64 v[168:169], v[168:169], 0, s[18:19]
	s_mov_b32 m0, s27
	ds_read_b128 v[220:223], v144
	ds_read_b128 v[228:231], v144 offset:1024
	ds_read_b128 v[232:235], v144 offset:2048
	ds_read_b128 v[236:239], v144 offset:3072
	global_load_lds_dwordx4 v[168:169], off
	v_lshl_add_u64 v[168:169], v[176:177], 0, s[18:19]
	s_add_i32 m0, s27, 0x2000
	s_nop 0
	global_load_lds_dwordx4 v[168:169], off
	s_setprio 1
	s_barrier
	s_waitcnt lgkmcnt(0)
	v_mfma_f32_16x16x32_bf16 v[116:119], v[220:223], v[156:159], v[116:119]
	v_mfma_f32_16x16x32_bf16 v[112:115], v[232:235], v[156:159], v[112:115]
	v_mfma_f32_16x16x32_bf16 v[100:103], v[220:223], v[164:167], v[100:103]
	v_mfma_f32_16x16x32_bf16 v[96:99], v[232:235], v[164:167], v[96:99]
	v_mfma_f32_16x16x32_bf16 v[84:87], v[220:223], v[192:195], v[84:87]
	v_mfma_f32_16x16x32_bf16 v[80:83], v[232:235], v[192:195], v[80:83]
	v_mfma_f32_16x16x32_bf16 v[68:71], v[220:223], v[200:203], v[68:71]
	v_mfma_f32_16x16x32_bf16 v[64:67], v[232:235], v[200:203], v[64:67]
	v_mfma_f32_16x16x32_bf16 v[116:119], v[228:231], v[160:163], v[116:119]
	v_mfma_f32_16x16x32_bf16 v[112:115], v[236:239], v[160:163], v[112:115]
	v_mfma_f32_16x16x32_bf16 v[100:103], v[228:231], v[188:191], v[100:103]
	v_mfma_f32_16x16x32_bf16 v[96:99], v[236:239], v[188:191], v[96:99]
	v_mfma_f32_16x16x32_bf16 v[84:87], v[228:231], v[196:199], v[84:87]
	v_mfma_f32_16x16x32_bf16 v[80:83], v[236:239], v[196:199], v[80:83]
	v_mfma_f32_16x16x32_bf16 v[68:71], v[228:231], v[204:207], v[68:71]
	v_mfma_f32_16x16x32_bf16 v[64:67], v[236:239], v[204:207], v[64:67]
	s_barrier
	s_setprio 0
	s_mov_b32 m0, s87
	v_lshl_add_u64 v[168:169], v[224:225], 0, s[18:19]
	ds_read_b128 v[156:159], v217 offset:49152
	ds_read_b128 v[160:163], v217 offset:50176
	ds_read_b128 v[164:167], v217 offset:51200
	ds_read_b128 v[188:191], v217 offset:52224
	ds_read_b128 v[192:195], v217 offset:53248
	ds_read_b128 v[196:199], v217 offset:54272
	ds_read_b128 v[200:203], v217 offset:55296
	ds_read_b128 v[204:207], v217 offset:56320
	global_load_lds_dwordx4 v[168:169], off
	v_lshl_add_u64 v[168:169], v[240:241], 0, s[18:19]
	s_mov_b32 m0, s79
	s_nop 0
	global_load_lds_dwordx4 v[168:169], off
	s_setprio 1
	s_barrier
	s_waitcnt lgkmcnt(0)
	v_mfma_f32_16x16x32_bf16 v[60:63], v[128:131], v[156:159], v[60:63]
	v_mfma_f32_16x16x32_bf16 v[56:59], v[136:139], v[156:159], v[56:59]
	v_mfma_f32_16x16x32_bf16 v[44:47], v[128:131], v[164:167], v[44:47]
	v_mfma_f32_16x16x32_bf16 v[40:43], v[136:139], v[164:167], v[40:43]
	v_mfma_f32_16x16x32_bf16 v[28:31], v[128:131], v[192:195], v[28:31]
	v_mfma_f32_16x16x32_bf16 v[24:27], v[136:139], v[192:195], v[24:27]
	v_mfma_f32_16x16x32_bf16 v[12:15], v[128:131], v[200:203], v[12:15]
	v_mfma_f32_16x16x32_bf16 v[8:11], v[136:139], v[200:203], v[8:11]
	v_mfma_f32_16x16x32_bf16 v[60:63], v[132:135], v[160:163], v[60:63]
	v_mfma_f32_16x16x32_bf16 v[56:59], v[140:143], v[160:163], v[56:59]
	v_mfma_f32_16x16x32_bf16 v[44:47], v[132:135], v[188:191], v[44:47]
	v_mfma_f32_16x16x32_bf16 v[40:43], v[140:143], v[188:191], v[40:43]
	v_mfma_f32_16x16x32_bf16 v[28:31], v[132:135], v[196:199], v[28:31]
	v_mfma_f32_16x16x32_bf16 v[24:27], v[140:143], v[196:199], v[24:27]
	v_mfma_f32_16x16x32_bf16 v[12:15], v[132:135], v[204:207], v[12:15]
	v_mfma_f32_16x16x32_bf16 v[8:11], v[140:143], v[204:207], v[8:11]
	s_barrier
	s_setprio 0
	s_add_u32 s36, s72, 0x40080
	s_addc_u32 s37, s73, 0
	s_add_i32 s27, s35, s81
	v_lshl_add_u64 v[128:129], s[36:37], 0, v[148:149]
	s_mov_b32 m0, s27
	s_nop 0
	global_load_lds_dwordx4 v[128:129], off
	v_lshl_add_u64 v[128:129], s[36:37], 0, v[146:147]
	s_add_i32 m0, s27, 0x2000
	s_nop 0
	global_load_lds_dwordx4 v[128:129], off
	s_waitcnt vmcnt(6)
	s_setprio 1
	s_barrier
	v_mfma_f32_16x16x32_bf16 v[52:55], v[220:223], v[156:159], v[52:55]
	v_mfma_f32_16x16x32_bf16 v[48:51], v[232:235], v[156:159], v[48:51]
	v_mfma_f32_16x16x32_bf16 v[36:39], v[220:223], v[164:167], v[36:39]
	v_mfma_f32_16x16x32_bf16 v[32:35], v[232:235], v[164:167], v[32:35]
	v_mfma_f32_16x16x32_bf16 v[20:23], v[220:223], v[192:195], v[20:23]
	v_mfma_f32_16x16x32_bf16 v[16:19], v[232:235], v[192:195], v[16:19]
	v_mfma_f32_16x16x32_bf16 v[4:7], v[220:223], v[200:203], v[4:7]
	v_mfma_f32_16x16x32_bf16 v[0:3], v[232:235], v[200:203], v[0:3]
	v_mfma_f32_16x16x32_bf16 v[52:55], v[228:231], v[160:163], v[52:55]
	v_mfma_f32_16x16x32_bf16 v[48:51], v[236:239], v[160:163], v[48:51]
	v_mfma_f32_16x16x32_bf16 v[36:39], v[228:231], v[188:191], v[36:39]
	v_mfma_f32_16x16x32_bf16 v[32:35], v[236:239], v[188:191], v[32:35]
	v_mfma_f32_16x16x32_bf16 v[20:23], v[228:231], v[196:199], v[20:23]
	v_mfma_f32_16x16x32_bf16 v[16:19], v[236:239], v[196:199], v[16:19]
	v_mfma_f32_16x16x32_bf16 v[4:7], v[228:231], v[204:207], v[4:7]
	v_mfma_f32_16x16x32_bf16 v[0:3], v[236:239], v[204:207], v[0:3]
	s_barrier
	s_setprio 0
	s_add_i32 s34, s34, 2
	s_add_u32 s52, s52, 0x100
	s_addc_u32 s53, s53, 0
	s_add_u32 s31, s31, 0x100
	s_addc_u32 s33, s33, 0
	s_cmp_gt_u32 s34, 13
	s_cbranch_scc0 .LBB0_326
	v_lshl_add_u32 v128, s0, 8, v151
	v_readlane_b32 s0, v252, 36
	v_ashrrev_i32_e32 v129, 31, v128
	v_readlane_b32 s1, v252, 37
	v_or_b32_e32 v132, 16, v128
	v_or_b32_e32 v136, 32, v128
	v_lshl_add_u64 v[130:131], v[128:129], 3, s[0:1]
	v_ashrrev_i32_e32 v133, 31, v132
	v_ashrrev_i32_e32 v137, 31, v136
	v_or_b32_e32 v140, 48, v128
	v_lshl_add_u64 v[134:135], v[132:133], 3, s[0:1]
	v_lshl_add_u64 v[138:139], v[136:137], 3, s[0:1]
	v_ashrrev_i32_e32 v141, 31, v140
	global_load_dwordx2 v[202:203], v[130:131], off
	global_load_dwordx2 v[200:201], v[134:135], off
	global_load_dwordx2 v[192:193], v[138:139], off
	global_load_dwordx2 v[166:167], v[130:131], off offset:1024
	v_add_u32_e32 v164, 0x90, v128
	v_add_u32_e32 v158, 0xa0, v128
	v_add_u32_e32 v156, 0xb0, v128
	v_lshl_add_u64 v[142:143], v[140:141], 3, s[0:1]
	v_ashrrev_i32_e32 v165, 31, v164
	v_ashrrev_i32_e32 v159, 31, v158
	v_ashrrev_i32_e32 v157, 31, v156
	v_lshl_add_u64 v[130:131], v[164:165], 3, s[0:1]
	v_lshl_add_u64 v[134:135], v[158:159], 3, s[0:1]
	v_lshl_add_u64 v[138:139], v[156:157], 3, s[0:1]
	global_load_dwordx2 v[196:197], v[142:143], off
	global_load_dwordx2 v[188:189], v[130:131], off
	global_load_dwordx2 v[162:163], v[134:135], off
	global_load_dwordx2 v[160:161], v[138:139], off
	v_add_u32_e32 v168, 0x80, v128
	s_mov_b64 s[0:1], -1
	s_cmp_gt_u32 s10, 1
	v_lshlrev_b32_e32 v144, 1, v150
	v_ashrrev_i32_e32 v169, 31, v168
	v_lshlrev_b64 v[204:205], 10, v[128:129]
	v_lshlrev_b64 v[198:199], 10, v[132:133]
	v_lshlrev_b64 v[194:195], 10, v[136:137]
	v_lshlrev_b64 v[190:191], 10, v[140:141]
	s_waitcnt vmcnt(0)
	v_ffbh_u32_e32 v222, v203
	v_ffbh_u32_e32 v221, v201
	v_ffbh_u32_e32 v220, v193
	v_ffbh_u32_e32 v219, v197
	s_cbranch_scc0 .LBB0_329
	s_cmp_lt_u32 s10, 4
	s_cselect_b64 vcc, -1, 0
	v_readlane_b32 s56, v254, 23
	s_and_b64 s[0:1], vcc, exec
	v_readlane_b32 s70, v254, 37
	v_readlane_b32 s36, v252, 15
	v_readlane_b32 s71, v254, 38
	v_readlane_b32 s37, v252, 16
	s_cselect_b32 s0, s70, s36
	s_mov_b32 s11, 0x4400000
	v_readlane_b32 s30, v254, 62
	s_cselect_b32 s1, s71, s37
	s_cselect_b32 s11, s11, 0x4800000
	v_readlane_b32 s31, v254, 63
	s_add_u32 s0, s0, s30
	s_addc_u32 s1, s1, s31
	global_load_dwordx4 v[136:139], v218, s[0:1] offset:16
	global_load_dwordx4 v[140:143], v218, s[0:1]
	global_load_dwordx4 v[128:131], v218, s[0:1] offset:144
	global_load_dwordx4 v[132:135], v218, s[0:1] offset:128
	v_and_b32_e32 v177, 64, v214
	v_xor_b32_e32 v176, 16, v214
	v_add_u32_e32 v177, 64, v177
	v_cndmask_b32_e32 v223, 1.0, v215, vcc
	v_cmp_lt_i32_e32 vcc, v176, v177
	v_readlane_b32 s9, v254, 52
	s_add_u32 s11, s9, s11
	v_cndmask_b32_e32 v176, v214, v176, vcc
	v_lshlrev_b32_e32 v225, 2, v176
	v_xor_b32_e32 v176, 32, v214
	v_cmp_lt_i32_e32 vcc, v176, v177
	v_readlane_b32 s9, v254, 61
	s_addc_u32 s25, s9, 0
	v_cndmask_b32_e32 v176, v214, v176, vcc
	v_lshlrev_b32_e32 v224, 2, v176
	v_min_u32_e32 v176, 32, v222
	v_lshlrev_b64 v[228:229], v176, v[202:203]
	v_min_u32_e32 v177, 1, v228
	v_or_b32_e32 v177, v229, v177
	v_cvt_f32_u32_e32 v177, v177
	v_sub_u32_e32 v176, 32, v176
	s_lshl_b32 s0, s10, 9
	s_and_b32 s0, s0, 0x200
	v_ldexp_f32 v176, v177, v176
	v_mul_f32_e32 v176, 0x35800000, v176
	v_fmamk_f32 v176, v176, 0x3a800000, v210
	s_add_u32 s0, s11, s0
	v_rsq_f32_e32 v176, v176
	s_addc_u32 s1, s25, 0
	v_lshl_add_u64 v[206:207], s[0:1], 0, v[144:145]
	v_readlane_b32 s48, v252, 27
	v_mov_b32_e32 v228, v176
	v_pk_mul_f32 v[230:231], v[124:125], v[228:229] op_sel_hi:[1,0]
	v_pk_mul_f32 v[232:233], v[126:127], v[228:229] op_sel_hi:[1,0]
	v_pk_mul_f32 v[236:237], v[230:231], v[230:231]
	v_pk_mul_f32 v[234:235], v[232:233], v[232:233]
	v_pk_mul_f32 v[250:251], v[114:115], v[228:229] op_sel_hi:[1,0]
	v_pk_mov_b32 v[238:239], v[236:237], v[234:235] op_sel:[1,0]
	v_mov_b32_e32 v237, v235
	v_pk_add_f32 v[234:235], v[238:239], v[236:237]
	v_pk_mul_f32 v[236:237], v[120:121], v[228:229] op_sel_hi:[1,0]
	v_pk_mul_f32 v[238:239], v[122:123], v[228:229] op_sel_hi:[1,0]
	v_pk_mul_f32 v[242:243], v[236:237], v[236:237]
	v_pk_mul_f32 v[240:241], v[238:239], v[238:239]
	v_pk_add_f32 v[234:235], v[234:235], v[234:235] op_sel_hi:[0,1]
	v_pk_mov_b32 v[244:245], v[242:243], v[240:241] op_sel:[1,0]
	v_mov_b32_e32 v243, v241
	v_pk_add_f32 v[240:241], v[244:245], v[242:243]
	v_pk_mul_f32 v[244:245], v[116:117], v[228:229] op_sel_hi:[1,0]
	v_pk_mul_f32 v[242:243], v[118:119], v[228:229] op_sel_hi:[1,0]
	v_mul_f32_e32 v234, v244, v244
	v_pk_fma_f32 v[246:247], v[244:245], v[244:245], v[234:235] op_sel_hi:[1,1,0]
	v_mul_f32_e32 v234, v242, v242
	v_pk_add_f32 v[240:241], v[240:241], v[240:241] op_sel_hi:[0,1]
	v_pk_fma_f32 v[248:249], v[242:243], v[242:243], v[234:235] op_sel_hi:[1,1,0]
	v_pk_mul_f32 v[176:177], v[112:113], v[228:229] op_sel_hi:[1,0]
	v_mul_f32_e32 v234, v250, v250
	v_mul_f32_e32 v246, v176, v176
	v_mul_f32_e32 v248, v177, v177
	v_mul_f32_e32 v240, v251, v251
	v_pk_add_f32 v[228:229], v[246:247], v[248:249]
	v_pk_add_f32 v[234:235], v[234:235], v[240:241]
	v_lshl_add_u64 v[240:241], v[206:207], 0, v[204:205]
	v_pk_add_f32 v[228:229], v[228:229], v[234:235]
	v_readlane_b32 s57, v254, 24
	v_add_f32_e32 v228, v228, v229
	ds_bpermute_b32 v229, v225, v228
	v_readlane_b32 s58, v254, 25
	v_readlane_b32 s59, v254, 26
	v_readlane_b32 s60, v254, 27
	v_readlane_b32 s61, v254, 28
	s_waitcnt lgkmcnt(0)
	v_add_f32_e32 v228, v228, v229
	ds_bpermute_b32 v229, v224, v228
	v_readlane_b32 s62, v254, 29
	v_readlane_b32 s63, v254, 30
	v_readlane_b32 s64, v254, 31
	v_readlane_b32 s65, v254, 32
	s_waitcnt lgkmcnt(0)
	v_add_f32_e32 v228, v228, v229
	v_fmamk_f32 v228, v228, 0x3c800000, v210
	v_readlane_b32 s66, v254, 33
	v_rsq_f32_e32 v228, v228
	v_readlane_b32 s67, v254, 34
	v_readlane_b32 s68, v254, 35
	v_readlane_b32 s69, v254, 36
	v_mul_f32_e32 v234, v223, v228
	v_pk_mul_f32 v[228:229], v[230:231], v[234:235] op_sel_hi:[1,0]
	v_pk_mul_f32 v[230:231], v[232:233], v[234:235] op_sel_hi:[1,0]
	s_waitcnt vmcnt(2)
	v_pk_mul_f32 v[228:229], v[140:141], v[228:229]
	v_pk_mul_f32 v[230:231], v[142:143], v[230:231]
	v_pk_mul_f32 v[232:233], v[236:237], v[234:235] op_sel_hi:[1,0]
	v_pk_mul_f32 v[236:237], v[238:239], v[234:235] op_sel_hi:[1,0]
	v_cvt_pk_bf16_f32 v228, v228, v229
	v_cvt_pk_bf16_f32 v229, v230, v231
	v_pk_mul_f32 v[232:233], v[136:137], v[232:233]
	v_pk_mul_f32 v[236:237], v[138:139], v[236:237]
	v_cvt_pk_bf16_f32 v230, v232, v233
	v_pk_mul_f32 v[176:177], v[176:177], v[234:235] op_sel_hi:[1,0]
	v_cvt_pk_bf16_f32 v231, v236, v237
	global_store_dwordx4 v[240:241], v[228:231], off
	v_pk_mul_f32 v[232:233], v[250:251], v[234:235] op_sel_hi:[1,0]
	s_waitcnt vmcnt(2)
	v_pk_mul_f32 v[176:177], v[128:129], v[176:177]
	v_pk_mul_f32 v[228:229], v[244:245], v[234:235] op_sel_hi:[1,0]
	v_pk_mul_f32 v[230:231], v[242:243], v[234:235] op_sel_hi:[1,0]
	s_waitcnt vmcnt(1)
	v_pk_mul_f32 v[228:229], v[132:133], v[228:229]
	v_pk_mul_f32 v[230:231], v[134:135], v[230:231]
	v_cvt_pk_bf16_f32 v228, v228, v229
	v_pk_mul_f32 v[232:233], v[130:131], v[232:233]
	v_cvt_pk_bf16_f32 v229, v230, v231
	v_cvt_pk_bf16_f32 v230, v176, v177
	s_nop 1
	v_readlane_b32 s38, v252, 17
	v_cvt_pk_bf16_f32 v231, v232, v233
	s_nop 1
	global_store_dwordx4 v[240:241], v[228:231], off offset:64
	v_readlane_b32 s39, v252, 18
	v_readlane_b32 s40, v252, 19
	v_min_u32_e32 v228, 32, v221
	v_lshlrev_b64 v[176:177], v228, v[200:201]
	v_min_u32_e32 v176, 1, v176
	v_or_b32_e32 v176, v177, v176
	v_cvt_f32_u32_e32 v176, v176
	v_sub_u32_e32 v177, 32, v228
	v_readlane_b32 s41, v252, 20
	v_readlane_b32 s42, v252, 21
	v_ldexp_f32 v176, v176, v177
	v_mul_f32_e32 v176, 0x35800000, v176
	v_fmamk_f32 v176, v176, 0x3a800000, v210
	v_readlane_b32 s43, v252, 22
	v_rsq_f32_e32 v176, v176
	v_readlane_b32 s44, v252, 23
	v_readlane_b32 s45, v252, 24
	v_readlane_b32 s46, v252, 25
	v_pk_mul_f32 v[228:229], v[108:109], v[176:177] op_sel_hi:[1,0]
	v_pk_mul_f32 v[230:231], v[110:111], v[176:177] op_sel_hi:[1,0]
	v_pk_mul_f32 v[234:235], v[228:229], v[228:229]
	v_pk_mul_f32 v[232:233], v[230:231], v[230:231]
	v_pk_mul_f32 v[248:249], v[98:99], v[176:177] op_sel_hi:[1,0]
	v_pk_mov_b32 v[236:237], v[234:235], v[232:233] op_sel:[1,0]
	v_mov_b32_e32 v235, v233
	v_pk_add_f32 v[232:233], v[236:237], v[234:235]
	v_pk_mul_f32 v[234:235], v[104:105], v[176:177] op_sel_hi:[1,0]
	v_pk_mul_f32 v[236:237], v[106:107], v[176:177] op_sel_hi:[1,0]
	v_pk_mul_f32 v[240:241], v[234:235], v[234:235]
	v_pk_mul_f32 v[238:239], v[236:237], v[236:237]
	v_pk_add_f32 v[232:233], v[232:233], v[232:233] op_sel_hi:[0,1]
	v_pk_mov_b32 v[242:243], v[240:241], v[238:239] op_sel:[1,0]
	v_mov_b32_e32 v241, v239
	v_pk_add_f32 v[238:239], v[242:243], v[240:241]
	v_pk_mul_f32 v[242:243], v[100:101], v[176:177] op_sel_hi:[1,0]
	v_pk_mul_f32 v[240:241], v[102:103], v[176:177] op_sel_hi:[1,0]
	v_mul_f32_e32 v232, v242, v242
	v_pk_fma_f32 v[244:245], v[242:243], v[242:243], v[232:233] op_sel_hi:[1,1,0]
	v_mul_f32_e32 v232, v240, v240
	v_pk_add_f32 v[238:239], v[238:239], v[238:239] op_sel_hi:[0,1]
	v_pk_fma_f32 v[246:247], v[240:241], v[240:241], v[232:233] op_sel_hi:[1,1,0]
	v_pk_mul_f32 v[176:177], v[96:97], v[176:177] op_sel_hi:[1,0]
	v_mul_f32_e32 v232, v248, v248
	v_mul_f32_e32 v244, v176, v176
	v_mul_f32_e32 v246, v177, v177
	v_mul_f32_e32 v238, v249, v249
	v_pk_add_f32 v[244:245], v[244:245], v[246:247]
	v_pk_add_f32 v[232:233], v[232:233], v[238:239]
	v_lshl_add_u64 v[238:239], v[206:207], 0, v[198:199]
	v_pk_add_f32 v[232:233], v[244:245], v[232:233]
	v_readlane_b32 s47, v252, 26
	v_add_f32_e32 v232, v232, v233
	ds_bpermute_b32 v233, v225, v232
	v_readlane_b32 s49, v252, 28
	v_readlane_b32 s50, v252, 29
	v_readlane_b32 s51, v252, 30
	v_readlane_b32 s48, v252, 40
	s_waitcnt lgkmcnt(0)
	v_add_f32_e32 v232, v232, v233
	ds_bpermute_b32 v233, v224, v232
	s_mov_b64 s[0:1], 0
	s_waitcnt lgkmcnt(0)
	v_add_f32_e32 v232, v232, v233
	v_fmamk_f32 v232, v232, 0x3c800000, v210
	s_nop 0
	v_rsq_f32_e32 v232, v232
	s_nop 0
	v_mul_f32_e32 v232, v223, v232
	v_pk_mul_f32 v[228:229], v[228:229], v[232:233] op_sel_hi:[1,0]
	v_pk_mul_f32 v[230:231], v[230:231], v[232:233] op_sel_hi:[1,0]
	v_pk_mul_f32 v[228:229], v[140:141], v[228:229]
	v_pk_mul_f32 v[230:231], v[142:143], v[230:231]
	v_pk_mul_f32 v[234:235], v[234:235], v[232:233] op_sel_hi:[1,0]
	v_pk_mul_f32 v[236:237], v[236:237], v[232:233] op_sel_hi:[1,0]
	v_cvt_pk_bf16_f32 v228, v228, v229
	v_cvt_pk_bf16_f32 v229, v230, v231
	v_pk_mul_f32 v[234:235], v[136:137], v[234:235]
	v_pk_mul_f32 v[236:237], v[138:139], v[236:237]
	v_cvt_pk_bf16_f32 v230, v234, v235
	v_pk_mul_f32 v[176:177], v[176:177], v[232:233] op_sel_hi:[1,0]
	v_cvt_pk_bf16_f32 v231, v236, v237
	global_store_dwordx4 v[238:239], v[228:231], off
	v_pk_mul_f32 v[176:177], v[128:129], v[176:177]
	s_nop 0
	v_pk_mul_f32 v[228:229], v[242:243], v[232:233] op_sel_hi:[1,0]
	v_pk_mul_f32 v[230:231], v[240:241], v[232:233] op_sel_hi:[1,0]
	v_pk_mul_f32 v[228:229], v[132:133], v[228:229]
	v_pk_mul_f32 v[230:231], v[134:135], v[230:231]
	v_pk_mul_f32 v[232:233], v[248:249], v[232:233] op_sel_hi:[1,0]
	v_cvt_pk_bf16_f32 v228, v228, v229
	v_cvt_pk_bf16_f32 v229, v230, v231
	v_cvt_pk_bf16_f32 v230, v176, v177
	s_nop 0
	v_pk_mul_f32 v[232:233], v[130:131], v[232:233]
	s_nop 0
	v_cvt_pk_bf16_f32 v231, v232, v233
	global_store_dwordx4 v[238:239], v[228:231], off offset:64
	s_nop 1
	v_min_u32_e32 v228, 32, v220
	v_lshlrev_b64 v[176:177], v228, v[192:193]
	v_min_u32_e32 v176, 1, v176
	v_or_b32_e32 v176, v177, v176
	v_cvt_f32_u32_e32 v176, v176
	v_sub_u32_e32 v177, 32, v228
	v_ldexp_f32 v176, v176, v177
	v_mul_f32_e32 v176, 0x35800000, v176
	v_fmamk_f32 v176, v176, 0x3a800000, v210
	s_nop 0
	v_rsq_f32_e32 v176, v176
	s_nop 0
	v_pk_mul_f32 v[228:229], v[92:93], v[176:177] op_sel_hi:[1,0]
	v_pk_mul_f32 v[230:231], v[94:95], v[176:177] op_sel_hi:[1,0]
	v_pk_mul_f32 v[234:235], v[228:229], v[228:229]
	v_pk_mul_f32 v[232:233], v[230:231], v[230:231]
	v_pk_mul_f32 v[248:249], v[82:83], v[176:177] op_sel_hi:[1,0]
	v_pk_mov_b32 v[236:237], v[234:235], v[232:233] op_sel:[1,0]
	v_mov_b32_e32 v235, v233
	v_pk_add_f32 v[232:233], v[236:237], v[234:235]
	v_pk_mul_f32 v[234:235], v[88:89], v[176:177] op_sel_hi:[1,0]
	v_pk_mul_f32 v[236:237], v[90:91], v[176:177] op_sel_hi:[1,0]
	v_pk_mul_f32 v[240:241], v[234:235], v[234:235]
	v_pk_mul_f32 v[238:239], v[236:237], v[236:237]
	v_pk_add_f32 v[232:233], v[232:233], v[232:233] op_sel_hi:[0,1]
	v_pk_mov_b32 v[242:243], v[240:241], v[238:239] op_sel:[1,0]
	v_mov_b32_e32 v241, v239
	v_pk_add_f32 v[238:239], v[242:243], v[240:241]
	v_pk_mul_f32 v[242:243], v[84:85], v[176:177] op_sel_hi:[1,0]
	v_pk_mul_f32 v[240:241], v[86:87], v[176:177] op_sel_hi:[1,0]
	v_mul_f32_e32 v232, v242, v242
	v_pk_fma_f32 v[244:245], v[242:243], v[242:243], v[232:233] op_sel_hi:[1,1,0]
	v_mul_f32_e32 v232, v240, v240
	v_pk_add_f32 v[238:239], v[238:239], v[238:239] op_sel_hi:[0,1]
	v_pk_fma_f32 v[246:247], v[240:241], v[240:241], v[232:233] op_sel_hi:[1,1,0]
	v_pk_mul_f32 v[176:177], v[80:81], v[176:177] op_sel_hi:[1,0]
	v_mul_f32_e32 v232, v248, v248
	v_mul_f32_e32 v244, v176, v176
	v_mul_f32_e32 v246, v177, v177
	v_mul_f32_e32 v238, v249, v249
	v_pk_add_f32 v[244:245], v[244:245], v[246:247]
	v_pk_add_f32 v[232:233], v[232:233], v[238:239]
	v_lshl_add_u64 v[238:239], v[206:207], 0, v[194:195]
	v_pk_add_f32 v[232:233], v[244:245], v[232:233]
	s_nop 0
	v_add_f32_e32 v232, v232, v233
	ds_bpermute_b32 v233, v225, v232
	s_waitcnt lgkmcnt(0)
	v_add_f32_e32 v232, v232, v233
	ds_bpermute_b32 v233, v224, v232
	s_waitcnt lgkmcnt(0)
	v_add_f32_e32 v232, v232, v233
	v_fmamk_f32 v232, v232, 0x3c800000, v210
	s_nop 0
	v_rsq_f32_e32 v232, v232
	s_nop 0
	v_mul_f32_e32 v232, v223, v232
	v_pk_mul_f32 v[228:229], v[228:229], v[232:233] op_sel_hi:[1,0]
	v_pk_mul_f32 v[230:231], v[230:231], v[232:233] op_sel_hi:[1,0]
	v_pk_mul_f32 v[228:229], v[140:141], v[228:229]
	v_pk_mul_f32 v[230:231], v[142:143], v[230:231]
	v_pk_mul_f32 v[234:235], v[234:235], v[232:233] op_sel_hi:[1,0]
	v_pk_mul_f32 v[236:237], v[236:237], v[232:233] op_sel_hi:[1,0]
	v_cvt_pk_bf16_f32 v228, v228, v229
	v_cvt_pk_bf16_f32 v229, v230, v231
	v_pk_mul_f32 v[234:235], v[136:137], v[234:235]
	v_pk_mul_f32 v[236:237], v[138:139], v[236:237]
	v_cvt_pk_bf16_f32 v230, v234, v235
	v_pk_mul_f32 v[176:177], v[176:177], v[232:233] op_sel_hi:[1,0]
	v_cvt_pk_bf16_f32 v231, v236, v237
	global_store_dwordx4 v[238:239], v[228:231], off
	v_pk_mul_f32 v[176:177], v[128:129], v[176:177]
	s_nop 0
	v_pk_mul_f32 v[228:229], v[242:243], v[232:233] op_sel_hi:[1,0]
	v_pk_mul_f32 v[230:231], v[240:241], v[232:233] op_sel_hi:[1,0]
	v_pk_mul_f32 v[228:229], v[132:133], v[228:229]
	v_pk_mul_f32 v[230:231], v[134:135], v[230:231]
	v_pk_mul_f32 v[232:233], v[248:249], v[232:233] op_sel_hi:[1,0]
	v_cvt_pk_bf16_f32 v228, v228, v229
	v_cvt_pk_bf16_f32 v229, v230, v231
	v_cvt_pk_bf16_f32 v230, v176, v177
	s_nop 0
	v_pk_mul_f32 v[232:233], v[130:131], v[232:233]
	s_nop 0
	v_cvt_pk_bf16_f32 v231, v232, v233
	global_store_dwordx4 v[238:239], v[228:231], off offset:64
	s_nop 1
	v_min_u32_e32 v228, 32, v219
	v_lshlrev_b64 v[176:177], v228, v[196:197]
	v_min_u32_e32 v176, 1, v176
	v_or_b32_e32 v176, v177, v176
	v_cvt_f32_u32_e32 v176, v176
	v_sub_u32_e32 v177, 32, v228
	v_ldexp_f32 v176, v176, v177
	v_mul_f32_e32 v176, 0x35800000, v176
	v_fmamk_f32 v176, v176, 0x3a800000, v210
	s_nop 0
	v_rsq_f32_e32 v176, v176
	s_nop 0
	v_pk_mul_f32 v[228:229], v[76:77], v[176:177] op_sel_hi:[1,0]
	v_pk_mul_f32 v[230:231], v[78:79], v[176:177] op_sel_hi:[1,0]
	v_pk_mul_f32 v[234:235], v[228:229], v[228:229]
	v_pk_mul_f32 v[232:233], v[230:231], v[230:231]
	v_pk_mul_f32 v[248:249], v[66:67], v[176:177] op_sel_hi:[1,0]
	v_pk_mov_b32 v[236:237], v[234:235], v[232:233] op_sel:[1,0]
	v_mov_b32_e32 v235, v233
	v_pk_add_f32 v[232:233], v[236:237], v[234:235]
	v_pk_mul_f32 v[234:235], v[72:73], v[176:177] op_sel_hi:[1,0]
	v_pk_mul_f32 v[236:237], v[74:75], v[176:177] op_sel_hi:[1,0]
	v_pk_mul_f32 v[240:241], v[234:235], v[234:235]
	v_pk_mul_f32 v[238:239], v[236:237], v[236:237]
	v_pk_add_f32 v[232:233], v[232:233], v[232:233] op_sel_hi:[0,1]
	v_pk_mov_b32 v[242:243], v[240:241], v[238:239] op_sel:[1,0]
	v_mov_b32_e32 v241, v239
	v_pk_add_f32 v[238:239], v[242:243], v[240:241]
	v_pk_mul_f32 v[242:243], v[68:69], v[176:177] op_sel_hi:[1,0]
	v_pk_mul_f32 v[240:241], v[70:71], v[176:177] op_sel_hi:[1,0]
	v_mul_f32_e32 v232, v242, v242
	v_pk_fma_f32 v[244:245], v[242:243], v[242:243], v[232:233] op_sel_hi:[1,1,0]
	v_mul_f32_e32 v232, v240, v240
	v_pk_add_f32 v[238:239], v[238:239], v[238:239] op_sel_hi:[0,1]
	v_pk_fma_f32 v[246:247], v[240:241], v[240:241], v[232:233] op_sel_hi:[1,1,0]
	v_pk_mul_f32 v[176:177], v[64:65], v[176:177] op_sel_hi:[1,0]
	v_mul_f32_e32 v232, v248, v248
	v_mul_f32_e32 v244, v176, v176
	v_mul_f32_e32 v246, v177, v177
	v_mul_f32_e32 v238, v249, v249
	v_pk_add_f32 v[244:245], v[244:245], v[246:247]
	v_pk_add_f32 v[232:233], v[232:233], v[238:239]
	v_lshl_add_u64 v[238:239], v[206:207], 0, v[190:191]
	v_pk_add_f32 v[232:233], v[244:245], v[232:233]
	s_nop 0
	v_add_f32_e32 v232, v232, v233
	ds_bpermute_b32 v233, v225, v232
	s_waitcnt lgkmcnt(0)
	v_add_f32_e32 v232, v232, v233
	ds_bpermute_b32 v233, v224, v232
	s_waitcnt lgkmcnt(0)
	v_add_f32_e32 v232, v232, v233
	v_fmamk_f32 v232, v232, 0x3c800000, v210
	s_nop 0
	v_rsq_f32_e32 v232, v232
	s_nop 0
	v_mul_f32_e32 v232, v223, v232
	v_pk_mul_f32 v[228:229], v[228:229], v[232:233] op_sel_hi:[1,0]
	v_pk_mul_f32 v[230:231], v[230:231], v[232:233] op_sel_hi:[1,0]
	v_pk_mul_f32 v[228:229], v[140:141], v[228:229]
	v_pk_mul_f32 v[230:231], v[142:143], v[230:231]
	v_pk_mul_f32 v[234:235], v[234:235], v[232:233] op_sel_hi:[1,0]
	v_pk_mul_f32 v[236:237], v[236:237], v[232:233] op_sel_hi:[1,0]
	v_pk_mul_f32 v[234:235], v[136:137], v[234:235]
	v_pk_mul_f32 v[236:237], v[138:139], v[236:237]
	v_cvt_pk_bf16_f32 v228, v228, v229
	v_cvt_pk_bf16_f32 v229, v230, v231
	v_cvt_pk_bf16_f32 v230, v234, v235
	v_pk_mul_f32 v[176:177], v[176:177], v[232:233] op_sel_hi:[1,0]
	v_cvt_pk_bf16_f32 v231, v236, v237
	global_store_dwordx4 v[238:239], v[228:231], off
	v_pk_mul_f32 v[176:177], v[128:129], v[176:177]
	s_nop 0
	v_pk_mul_f32 v[228:229], v[242:243], v[232:233] op_sel_hi:[1,0]
	v_pk_mul_f32 v[230:231], v[240:241], v[232:233] op_sel_hi:[1,0]
	v_pk_mul_f32 v[228:229], v[132:133], v[228:229]
	v_pk_mul_f32 v[230:231], v[134:135], v[230:231]
	v_pk_mul_f32 v[232:233], v[248:249], v[232:233] op_sel_hi:[1,0]
	v_cvt_pk_bf16_f32 v228, v228, v229
	v_cvt_pk_bf16_f32 v229, v230, v231
	v_cvt_pk_bf16_f32 v230, v176, v177
	v_ffbh_u32_e32 v176, v167
	v_pk_mul_f32 v[232:233], v[130:131], v[232:233]
	s_nop 0
	v_cvt_pk_bf16_f32 v231, v232, v233
	global_store_dwordx4 v[238:239], v[228:231], off offset:64
	s_nop 1
	v_min_u32_e32 v228, 32, v176
	v_lshlrev_b64 v[176:177], v228, v[166:167]
	v_min_u32_e32 v176, 1, v176
	v_or_b32_e32 v176, v177, v176
	v_cvt_f32_u32_e32 v176, v176
	v_sub_u32_e32 v177, 32, v228
	v_ldexp_f32 v176, v176, v177
	v_mul_f32_e32 v176, 0x35800000, v176
	v_fmamk_f32 v176, v176, 0x3a800000, v210
	s_nop 0
	v_rsq_f32_e32 v176, v176
	s_nop 0
	v_pk_mul_f32 v[228:229], v[60:61], v[176:177] op_sel_hi:[1,0]
	v_pk_mul_f32 v[230:231], v[62:63], v[176:177] op_sel_hi:[1,0]
	v_pk_mul_f32 v[234:235], v[228:229], v[228:229]
	v_pk_mul_f32 v[232:233], v[230:231], v[230:231]
	v_pk_mul_f32 v[248:249], v[50:51], v[176:177] op_sel_hi:[1,0]
	v_pk_mov_b32 v[236:237], v[234:235], v[232:233] op_sel:[1,0]
	v_mov_b32_e32 v235, v233
	v_pk_add_f32 v[232:233], v[236:237], v[234:235]
	v_pk_mul_f32 v[234:235], v[56:57], v[176:177] op_sel_hi:[1,0]
	v_pk_mul_f32 v[236:237], v[58:59], v[176:177] op_sel_hi:[1,0]
	v_pk_mul_f32 v[240:241], v[234:235], v[234:235]
	v_pk_mul_f32 v[238:239], v[236:237], v[236:237]
	v_pk_add_f32 v[232:233], v[232:233], v[232:233] op_sel_hi:[0,1]
	v_pk_mov_b32 v[242:243], v[240:241], v[238:239] op_sel:[1,0]
	v_mov_b32_e32 v241, v239
	v_pk_add_f32 v[238:239], v[242:243], v[240:241]
	v_pk_mul_f32 v[242:243], v[52:53], v[176:177] op_sel_hi:[1,0]
	v_pk_mul_f32 v[240:241], v[54:55], v[176:177] op_sel_hi:[1,0]
	v_mul_f32_e32 v232, v242, v242
	v_pk_fma_f32 v[244:245], v[242:243], v[242:243], v[232:233] op_sel_hi:[1,1,0]
	v_mul_f32_e32 v232, v240, v240
	v_pk_add_f32 v[238:239], v[238:239], v[238:239] op_sel_hi:[0,1]
	v_pk_fma_f32 v[246:247], v[240:241], v[240:241], v[232:233] op_sel_hi:[1,1,0]
	v_pk_mul_f32 v[176:177], v[48:49], v[176:177] op_sel_hi:[1,0]
	v_mul_f32_e32 v232, v248, v248
	v_mul_f32_e32 v244, v176, v176
	v_mul_f32_e32 v246, v177, v177
	v_mul_f32_e32 v238, v249, v249
	v_pk_add_f32 v[244:245], v[244:245], v[246:247]
	v_pk_add_f32 v[232:233], v[232:233], v[238:239]
	v_lshlrev_b64 v[238:239], 10, v[168:169]
	v_pk_add_f32 v[232:233], v[244:245], v[232:233]
	v_lshl_add_u64 v[238:239], v[206:207], 0, v[238:239]
	v_add_f32_e32 v232, v232, v233
	ds_bpermute_b32 v233, v225, v232
	s_waitcnt lgkmcnt(0)
	v_add_f32_e32 v232, v232, v233
	ds_bpermute_b32 v233, v224, v232
	s_waitcnt lgkmcnt(0)
	v_add_f32_e32 v232, v232, v233
	v_fmamk_f32 v232, v232, 0x3c800000, v210
	s_nop 0
	v_rsq_f32_e32 v232, v232
	s_nop 0
	v_mul_f32_e32 v232, v223, v232
	v_pk_mul_f32 v[228:229], v[228:229], v[232:233] op_sel_hi:[1,0]
	v_pk_mul_f32 v[230:231], v[230:231], v[232:233] op_sel_hi:[1,0]
	v_pk_mul_f32 v[228:229], v[140:141], v[228:229]
	v_pk_mul_f32 v[230:231], v[142:143], v[230:231]
	v_pk_mul_f32 v[234:235], v[234:235], v[232:233] op_sel_hi:[1,0]
	v_pk_mul_f32 v[236:237], v[236:237], v[232:233] op_sel_hi:[1,0]
	v_pk_mul_f32 v[234:235], v[136:137], v[234:235]
	v_pk_mul_f32 v[236:237], v[138:139], v[236:237]
	v_cvt_pk_bf16_f32 v228, v228, v229
	v_cvt_pk_bf16_f32 v229, v230, v231
	v_cvt_pk_bf16_f32 v230, v234, v235
	v_pk_mul_f32 v[176:177], v[176:177], v[232:233] op_sel_hi:[1,0]
	v_cvt_pk_bf16_f32 v231, v236, v237
	global_store_dwordx4 v[238:239], v[228:231], off
	v_pk_mul_f32 v[176:177], v[128:129], v[176:177]
	s_nop 0
	v_pk_mul_f32 v[228:229], v[242:243], v[232:233] op_sel_hi:[1,0]
	v_pk_mul_f32 v[230:231], v[240:241], v[232:233] op_sel_hi:[1,0]
	v_pk_mul_f32 v[228:229], v[132:133], v[228:229]
	v_pk_mul_f32 v[230:231], v[134:135], v[230:231]
	v_pk_mul_f32 v[232:233], v[248:249], v[232:233] op_sel_hi:[1,0]
	v_cvt_pk_bf16_f32 v228, v228, v229
	v_cvt_pk_bf16_f32 v229, v230, v231
	v_cvt_pk_bf16_f32 v230, v176, v177
	v_ffbh_u32_e32 v176, v189
	v_pk_mul_f32 v[232:233], v[130:131], v[232:233]
	s_nop 0
	v_cvt_pk_bf16_f32 v231, v232, v233
	global_store_dwordx4 v[238:239], v[228:231], off offset:64
	s_nop 1
	v_min_u32_e32 v228, 32, v176
	v_lshlrev_b64 v[176:177], v228, v[188:189]
	v_min_u32_e32 v176, 1, v176
	v_or_b32_e32 v176, v177, v176
	v_cvt_f32_u32_e32 v176, v176
	v_sub_u32_e32 v177, 32, v228
	v_ldexp_f32 v176, v176, v177
	v_mul_f32_e32 v176, 0x35800000, v176
	v_fmamk_f32 v176, v176, 0x3a800000, v210
	s_nop 0
	v_rsq_f32_e32 v176, v176
	s_nop 0
	v_pk_mul_f32 v[228:229], v[44:45], v[176:177] op_sel_hi:[1,0]
	v_pk_mul_f32 v[230:231], v[46:47], v[176:177] op_sel_hi:[1,0]
	v_pk_mul_f32 v[234:235], v[228:229], v[228:229]
	v_pk_mul_f32 v[232:233], v[230:231], v[230:231]
	v_pk_mul_f32 v[248:249], v[34:35], v[176:177] op_sel_hi:[1,0]
	v_pk_mov_b32 v[236:237], v[234:235], v[232:233] op_sel:[1,0]
	v_mov_b32_e32 v235, v233
	v_pk_add_f32 v[232:233], v[236:237], v[234:235]
	v_pk_mul_f32 v[234:235], v[40:41], v[176:177] op_sel_hi:[1,0]
	v_pk_mul_f32 v[236:237], v[42:43], v[176:177] op_sel_hi:[1,0]
	v_pk_mul_f32 v[240:241], v[234:235], v[234:235]
	v_pk_mul_f32 v[238:239], v[236:237], v[236:237]
	v_pk_add_f32 v[232:233], v[232:233], v[232:233] op_sel_hi:[0,1]
	v_pk_mov_b32 v[242:243], v[240:241], v[238:239] op_sel:[1,0]
	v_mov_b32_e32 v241, v239
	v_pk_add_f32 v[238:239], v[242:243], v[240:241]
	v_pk_mul_f32 v[242:243], v[36:37], v[176:177] op_sel_hi:[1,0]
	v_pk_mul_f32 v[240:241], v[38:39], v[176:177] op_sel_hi:[1,0]
	v_mul_f32_e32 v232, v242, v242
	v_pk_fma_f32 v[244:245], v[242:243], v[242:243], v[232:233] op_sel_hi:[1,1,0]
	v_mul_f32_e32 v232, v240, v240
	v_pk_add_f32 v[238:239], v[238:239], v[238:239] op_sel_hi:[0,1]
	v_pk_fma_f32 v[246:247], v[240:241], v[240:241], v[232:233] op_sel_hi:[1,1,0]
	v_pk_mul_f32 v[176:177], v[32:33], v[176:177] op_sel_hi:[1,0]
	v_mul_f32_e32 v232, v248, v248
	v_mul_f32_e32 v244, v176, v176
	v_mul_f32_e32 v246, v177, v177
	v_mul_f32_e32 v238, v249, v249
	v_pk_add_f32 v[244:245], v[244:245], v[246:247]
	v_pk_add_f32 v[232:233], v[232:233], v[238:239]
	v_lshlrev_b64 v[238:239], 10, v[164:165]
	v_pk_add_f32 v[232:233], v[244:245], v[232:233]
	v_lshl_add_u64 v[238:239], v[206:207], 0, v[238:239]
	v_add_f32_e32 v232, v232, v233
	ds_bpermute_b32 v233, v225, v232
	s_waitcnt lgkmcnt(0)
	v_add_f32_e32 v232, v232, v233
	ds_bpermute_b32 v233, v224, v232
	s_waitcnt lgkmcnt(0)
	v_add_f32_e32 v232, v232, v233
	v_fmamk_f32 v232, v232, 0x3c800000, v210
	s_nop 0
	v_rsq_f32_e32 v232, v232
	s_nop 0
	v_mul_f32_e32 v232, v223, v232
	v_pk_mul_f32 v[228:229], v[228:229], v[232:233] op_sel_hi:[1,0]
	v_pk_mul_f32 v[230:231], v[230:231], v[232:233] op_sel_hi:[1,0]
	v_pk_mul_f32 v[228:229], v[140:141], v[228:229]
	v_pk_mul_f32 v[230:231], v[142:143], v[230:231]
	v_pk_mul_f32 v[234:235], v[234:235], v[232:233] op_sel_hi:[1,0]
	v_pk_mul_f32 v[236:237], v[236:237], v[232:233] op_sel_hi:[1,0]
	v_pk_mul_f32 v[234:235], v[136:137], v[234:235]
	v_pk_mul_f32 v[236:237], v[138:139], v[236:237]
	v_cvt_pk_bf16_f32 v228, v228, v229
	v_cvt_pk_bf16_f32 v229, v230, v231
	v_cvt_pk_bf16_f32 v230, v234, v235
	v_pk_mul_f32 v[176:177], v[176:177], v[232:233] op_sel_hi:[1,0]
	v_cvt_pk_bf16_f32 v231, v236, v237
	global_store_dwordx4 v[238:239], v[228:231], off
	v_pk_mul_f32 v[176:177], v[128:129], v[176:177]
	s_nop 0
	v_pk_mul_f32 v[228:229], v[242:243], v[232:233] op_sel_hi:[1,0]
	v_pk_mul_f32 v[230:231], v[240:241], v[232:233] op_sel_hi:[1,0]
	v_pk_mul_f32 v[228:229], v[132:133], v[228:229]
	v_pk_mul_f32 v[230:231], v[134:135], v[230:231]
	v_pk_mul_f32 v[232:233], v[248:249], v[232:233] op_sel_hi:[1,0]
	v_cvt_pk_bf16_f32 v228, v228, v229
	v_cvt_pk_bf16_f32 v229, v230, v231
	v_cvt_pk_bf16_f32 v230, v176, v177
	v_ffbh_u32_e32 v176, v163
	v_pk_mul_f32 v[232:233], v[130:131], v[232:233]
	s_nop 0
	v_cvt_pk_bf16_f32 v231, v232, v233
	global_store_dwordx4 v[238:239], v[228:231], off offset:64
	s_nop 1
	v_min_u32_e32 v228, 32, v176
	v_lshlrev_b64 v[176:177], v228, v[162:163]
	v_min_u32_e32 v176, 1, v176
	v_or_b32_e32 v176, v177, v176
	v_cvt_f32_u32_e32 v176, v176
	v_sub_u32_e32 v177, 32, v228
	v_ldexp_f32 v176, v176, v177
	v_mul_f32_e32 v176, 0x35800000, v176
	v_fmamk_f32 v176, v176, 0x3a800000, v210
	s_nop 0
	v_rsq_f32_e32 v176, v176
	s_nop 0
	v_pk_mul_f32 v[228:229], v[28:29], v[176:177] op_sel_hi:[1,0]
	v_pk_mul_f32 v[230:231], v[30:31], v[176:177] op_sel_hi:[1,0]
	v_pk_mul_f32 v[234:235], v[228:229], v[228:229]
	v_pk_mul_f32 v[232:233], v[230:231], v[230:231]
	v_pk_mul_f32 v[248:249], v[18:19], v[176:177] op_sel_hi:[1,0]
	v_pk_mov_b32 v[236:237], v[234:235], v[232:233] op_sel:[1,0]
	v_mov_b32_e32 v235, v233
	v_pk_add_f32 v[232:233], v[236:237], v[234:235]
	v_pk_mul_f32 v[234:235], v[24:25], v[176:177] op_sel_hi:[1,0]
	v_pk_mul_f32 v[236:237], v[26:27], v[176:177] op_sel_hi:[1,0]
	v_pk_mul_f32 v[240:241], v[234:235], v[234:235]
	v_pk_mul_f32 v[238:239], v[236:237], v[236:237]
	v_pk_add_f32 v[232:233], v[232:233], v[232:233] op_sel_hi:[0,1]
	v_pk_mov_b32 v[242:243], v[240:241], v[238:239] op_sel:[1,0]
	v_mov_b32_e32 v241, v239
	v_pk_add_f32 v[238:239], v[242:243], v[240:241]
	v_pk_mul_f32 v[242:243], v[20:21], v[176:177] op_sel_hi:[1,0]
	v_pk_mul_f32 v[240:241], v[22:23], v[176:177] op_sel_hi:[1,0]
	v_mul_f32_e32 v232, v242, v242
	v_pk_fma_f32 v[244:245], v[242:243], v[242:243], v[232:233] op_sel_hi:[1,1,0]
	v_mul_f32_e32 v232, v240, v240
	v_pk_add_f32 v[238:239], v[238:239], v[238:239] op_sel_hi:[0,1]
	v_pk_fma_f32 v[246:247], v[240:241], v[240:241], v[232:233] op_sel_hi:[1,1,0]
	v_pk_mul_f32 v[176:177], v[16:17], v[176:177] op_sel_hi:[1,0]
	v_mul_f32_e32 v232, v248, v248
	v_mul_f32_e32 v244, v176, v176
	v_mul_f32_e32 v246, v177, v177
	v_mul_f32_e32 v238, v249, v249
	v_pk_add_f32 v[244:245], v[244:245], v[246:247]
	v_pk_add_f32 v[232:233], v[232:233], v[238:239]
	v_lshlrev_b64 v[238:239], 10, v[158:159]
	v_pk_add_f32 v[232:233], v[244:245], v[232:233]
	v_lshl_add_u64 v[238:239], v[206:207], 0, v[238:239]
	v_add_f32_e32 v232, v232, v233
	ds_bpermute_b32 v233, v225, v232
	s_waitcnt lgkmcnt(0)
	v_add_f32_e32 v232, v232, v233
	ds_bpermute_b32 v233, v224, v232
	s_waitcnt lgkmcnt(0)
	v_add_f32_e32 v232, v232, v233
	v_fmamk_f32 v232, v232, 0x3c800000, v210
	s_nop 0
	v_rsq_f32_e32 v232, v232
	s_nop 0
	v_mul_f32_e32 v232, v223, v232
	v_pk_mul_f32 v[228:229], v[228:229], v[232:233] op_sel_hi:[1,0]
	v_pk_mul_f32 v[230:231], v[230:231], v[232:233] op_sel_hi:[1,0]
	v_pk_mul_f32 v[228:229], v[140:141], v[228:229]
	v_pk_mul_f32 v[230:231], v[142:143], v[230:231]
	v_pk_mul_f32 v[234:235], v[234:235], v[232:233] op_sel_hi:[1,0]
	v_pk_mul_f32 v[236:237], v[236:237], v[232:233] op_sel_hi:[1,0]
	v_pk_mul_f32 v[234:235], v[136:137], v[234:235]
	v_pk_mul_f32 v[236:237], v[138:139], v[236:237]
	v_cvt_pk_bf16_f32 v228, v228, v229
	v_cvt_pk_bf16_f32 v229, v230, v231
	v_cvt_pk_bf16_f32 v230, v234, v235
	v_pk_mul_f32 v[176:177], v[176:177], v[232:233] op_sel_hi:[1,0]
	v_cvt_pk_bf16_f32 v231, v236, v237
	global_store_dwordx4 v[238:239], v[228:231], off
	v_pk_mul_f32 v[176:177], v[128:129], v[176:177]
	s_nop 0
	v_pk_mul_f32 v[228:229], v[242:243], v[232:233] op_sel_hi:[1,0]
	v_pk_mul_f32 v[230:231], v[240:241], v[232:233] op_sel_hi:[1,0]
	v_pk_mul_f32 v[228:229], v[132:133], v[228:229]
	v_pk_mul_f32 v[230:231], v[134:135], v[230:231]
	v_pk_mul_f32 v[232:233], v[248:249], v[232:233] op_sel_hi:[1,0]
	v_cvt_pk_bf16_f32 v228, v228, v229
	v_cvt_pk_bf16_f32 v229, v230, v231
	v_cvt_pk_bf16_f32 v230, v176, v177
	v_ffbh_u32_e32 v176, v161
	v_pk_mul_f32 v[232:233], v[130:131], v[232:233]
	s_nop 0
	v_cvt_pk_bf16_f32 v231, v232, v233
	global_store_dwordx4 v[238:239], v[228:231], off offset:64
	s_nop 1
	v_min_u32_e32 v228, 32, v176
	v_lshlrev_b64 v[176:177], v228, v[160:161]
	v_min_u32_e32 v176, 1, v176
	v_or_b32_e32 v176, v177, v176
	v_cvt_f32_u32_e32 v176, v176
	v_sub_u32_e32 v177, 32, v228
	v_ldexp_f32 v176, v176, v177
	v_mul_f32_e32 v176, 0x35800000, v176
	v_fmamk_f32 v176, v176, 0x3a800000, v210
	s_nop 0
	v_rsq_f32_e32 v176, v176
	s_nop 0
	v_pk_mul_f32 v[228:229], v[12:13], v[176:177] op_sel_hi:[1,0]
	v_pk_mul_f32 v[230:231], v[14:15], v[176:177] op_sel_hi:[1,0]
	v_pk_mul_f32 v[234:235], v[228:229], v[228:229]
	v_pk_mul_f32 v[232:233], v[230:231], v[230:231]
	v_pk_mul_f32 v[248:249], v[2:3], v[176:177] op_sel_hi:[1,0]
	v_pk_mov_b32 v[236:237], v[234:235], v[232:233] op_sel:[1,0]
	v_mov_b32_e32 v235, v233
	v_pk_add_f32 v[232:233], v[236:237], v[234:235]
	v_pk_mul_f32 v[234:235], v[8:9], v[176:177] op_sel_hi:[1,0]
	v_pk_mul_f32 v[236:237], v[10:11], v[176:177] op_sel_hi:[1,0]
	v_pk_mul_f32 v[240:241], v[234:235], v[234:235]
	v_pk_mul_f32 v[238:239], v[236:237], v[236:237]
	v_pk_add_f32 v[232:233], v[232:233], v[232:233] op_sel_hi:[0,1]
	v_pk_mov_b32 v[242:243], v[240:241], v[238:239] op_sel:[1,0]
	v_mov_b32_e32 v241, v239
	v_pk_add_f32 v[238:239], v[242:243], v[240:241]
	v_pk_mul_f32 v[242:243], v[4:5], v[176:177] op_sel_hi:[1,0]
	v_pk_mul_f32 v[240:241], v[6:7], v[176:177] op_sel_hi:[1,0]
	v_mul_f32_e32 v232, v242, v242
	v_pk_fma_f32 v[244:245], v[242:243], v[242:243], v[232:233] op_sel_hi:[1,1,0]
	v_mul_f32_e32 v232, v240, v240
	v_pk_add_f32 v[238:239], v[238:239], v[238:239] op_sel_hi:[0,1]
	v_pk_fma_f32 v[246:247], v[240:241], v[240:241], v[232:233] op_sel_hi:[1,1,0]
	v_pk_mul_f32 v[176:177], v[0:1], v[176:177] op_sel_hi:[1,0]
	v_mul_f32_e32 v232, v248, v248
	v_mul_f32_e32 v244, v176, v176
	v_mul_f32_e32 v246, v177, v177
	v_mul_f32_e32 v238, v249, v249
	v_pk_add_f32 v[244:245], v[244:245], v[246:247]
	v_pk_add_f32 v[232:233], v[232:233], v[238:239]
	s_nop 0
	v_pk_add_f32 v[232:233], v[244:245], v[232:233]
	s_nop 0
	v_add_f32_e32 v232, v232, v233
	ds_bpermute_b32 v225, v225, v232
	s_waitcnt lgkmcnt(0)
	v_add_f32_e32 v225, v232, v225
	ds_bpermute_b32 v224, v224, v225
	v_lshlrev_b64 v[232:233], 10, v[156:157]
	v_lshl_add_u64 v[206:207], v[206:207], 0, v[232:233]
	s_waitcnt lgkmcnt(0)
	v_add_f32_e32 v224, v225, v224
	v_fmamk_f32 v224, v224, 0x3c800000, v210
	s_nop 0
	v_rsq_f32_e32 v224, v224
	s_nop 0
	v_mul_f32_e32 v224, v223, v224
	v_pk_mul_f32 v[228:229], v[228:229], v[224:225] op_sel_hi:[1,0]
	v_pk_mul_f32 v[230:231], v[230:231], v[224:225] op_sel_hi:[1,0]
	v_pk_mul_f32 v[140:141], v[140:141], v[228:229]
	v_pk_mul_f32 v[142:143], v[142:143], v[230:231]
	v_pk_mul_f32 v[228:229], v[234:235], v[224:225] op_sel_hi:[1,0]
	v_pk_mul_f32 v[230:231], v[236:237], v[224:225] op_sel_hi:[1,0]
	s_nop 0
	v_pk_mul_f32 v[230:231], v[138:139], v[230:231]
	v_pk_mul_f32 v[138:139], v[136:137], v[228:229]
	v_cvt_pk_bf16_f32 v136, v140, v141
	v_cvt_pk_bf16_f32 v137, v142, v143
	s_nop 0
	v_cvt_pk_bf16_f32 v138, v138, v139
	v_cvt_pk_bf16_f32 v139, v230, v231
	global_store_dwordx4 v[206:207], v[136:139], off
	s_nop 1
	v_pk_mul_f32 v[136:137], v[242:243], v[224:225] op_sel_hi:[1,0]
	v_pk_mul_f32 v[138:139], v[240:241], v[224:225] op_sel_hi:[1,0]
	v_pk_mul_f32 v[132:133], v[132:133], v[136:137]
	v_pk_mul_f32 v[134:135], v[134:135], v[138:139]
	v_pk_mul_f32 v[136:137], v[176:177], v[224:225] op_sel_hi:[1,0]
	v_pk_mul_f32 v[138:139], v[248:249], v[224:225] op_sel_hi:[1,0]
	s_nop 0
	v_pk_mul_f32 v[138:139], v[130:131], v[138:139]
	v_pk_mul_f32 v[130:131], v[128:129], v[136:137]
	v_cvt_pk_bf16_f32 v128, v132, v133
	v_cvt_pk_bf16_f32 v129, v134, v135
	s_nop 0
	v_cvt_pk_bf16_f32 v130, v130, v131
	v_cvt_pk_bf16_f32 v131, v138, v139
	s_nop 1

.LBB0_350:
	s_lshl_b32 s25, s84, 1
	s_add_i32 s25, s85, s25
	s_and_b32 s85, s25, 3
	s_lshl_b32 s25, s85, 19
	s_add_u32 s92, s74, s25
	v_cmp_lt_i64_e32 vcc, s[52:53], v[180:181]
	s_addc_u32 s93, s75, 0
	s_and_b64 s[30:31], vcc, exec
	s_cselect_b32 s25, s93, s1
	s_cselect_b32 s30, s92, s0
	s_ashr_i32 s47, s46, 31
	s_lshl_b64 s[34:35], s[46:47], 19
	s_add_u32 s94, s54, s34
	s_addc_u32 s95, s55, s35
	s_and_b64 s[34:35], vcc, exec
	s_cselect_b32 s31, s95, s51
	s_cselect_b32 s33, s94, s50
	s_add_u32 s0, s0, 0x40080
	s_addc_u32 s1, s1, 0
	s_add_u32 s34, s50, 0x100
	s_addc_u32 s35, s51, 0
	s_mov_b32 s36, -2
	s_add_u32 s27, s0, 0xfffc0080
	s_addc_u32 s37, s1, -1
	s_add_i32 s47, 0, 0x10000
	v_add_u32_e32 v140, s47, v192
	ds_read_b128 v[128:131], v140
	ds_read_b128 v[132:135], v140 offset:1024
	ds_read_b128 v[136:139], v140 offset:2048
	ds_read_b128 v[140:143], v140 offset:3072
	s_cmp_eq_u32 s36, 12
	s_cselect_b32 s53, s25, s37
	s_cselect_b32 s52, s30, s27
	s_cselect_b32 s51, s31, s35
	s_cselect_b32 s50, s33, s34
	v_lshl_add_u64 v[176:177], s[0:1], 0, v[156:157]
	s_add_i32 m0, s77, 0xc000
	ds_read_b128 v[162:165], v194
	ds_read_b128 v[166:169], v194 offset:1024
	ds_read_b128 v[196:199], v194 offset:2048
	ds_read_b128 v[200:203], v194 offset:3072
	ds_read_b128 v[204:207], v194 offset:4096
	ds_read_b128 v[216:219], v194 offset:5120
	ds_read_b128 v[220:223], v194 offset:6144
	ds_read_b128 v[228:231], v194 offset:7168
	global_load_lds_dwordx4 v[176:177], off
	v_lshl_add_u64 v[176:177], s[0:1], 0, v[158:159]
	s_add_i32 m0, s77, 0xe000
	s_nop 0
	global_load_lds_dwordx4 v[176:177], off
	s_waitcnt lgkmcnt(8)
	s_setprio 1
	s_barrier
	s_waitcnt lgkmcnt(0)
	v_mfma_f32_16x16x32_bf16 v[124:127], v[128:131], v[162:165], 0
	v_mfma_f32_16x16x32_bf16 v[120:123], v[136:139], v[162:165], 0
	v_mfma_f32_16x16x32_bf16 v[116:119], v[128:131], v[196:199], 0
	v_mfma_f32_16x16x32_bf16 v[112:115], v[136:139], v[196:199], 0
	v_mfma_f32_16x16x32_bf16 v[108:111], v[128:131], v[204:207], 0
	v_mfma_f32_16x16x32_bf16 v[104:107], v[136:139], v[204:207], 0
	v_mfma_f32_16x16x32_bf16 v[100:103], v[128:131], v[220:223], 0
	v_mfma_f32_16x16x32_bf16 v[96:99], v[136:139], v[220:223], 0
	v_mfma_f32_16x16x32_bf16 v[124:127], v[132:135], v[166:169], v[124:127]
	v_mfma_f32_16x16x32_bf16 v[120:123], v[140:143], v[166:169], v[120:123]
	v_mfma_f32_16x16x32_bf16 v[116:119], v[132:135], v[200:203], v[116:119]
	v_mfma_f32_16x16x32_bf16 v[112:115], v[140:143], v[200:203], v[112:115]
	v_mfma_f32_16x16x32_bf16 v[108:111], v[132:135], v[216:219], v[108:111]
	v_mfma_f32_16x16x32_bf16 v[104:107], v[140:143], v[216:219], v[104:107]
	v_mfma_f32_16x16x32_bf16 v[100:103], v[132:135], v[228:231], v[100:103]
	v_mfma_f32_16x16x32_bf16 v[96:99], v[140:143], v[228:231], v[96:99]
	s_barrier
	s_setprio 0
	s_add_i32 s27, 0, 0x14000
	s_add_i32 s37, s47, s76
	v_add_u32_e32 v161, s27, v192
	v_lshl_add_u64 v[176:177], s[50:51], 0, v[148:149]
	s_mov_b32 m0, s37
	ds_read_b128 v[232:235], v161
	ds_read_b128 v[236:239], v161 offset:1024
	ds_read_b128 v[240:243], v161 offset:2048
	ds_read_b128 v[244:247], v161 offset:3072
	global_load_lds_dwordx4 v[176:177], off
	v_lshl_add_u64 v[188:189], s[50:51], 0, v[152:153]
	s_add_i32 m0, s37, 0x2000
	s_nop 0
	global_load_lds_dwordx4 v[188:189], off
	s_setprio 1
	s_barrier
	s_waitcnt lgkmcnt(0)
	v_mfma_f32_16x16x32_bf16 v[92:95], v[232:235], v[162:165], 0
	v_mfma_f32_16x16x32_bf16 v[88:91], v[240:243], v[162:165], 0
	v_mfma_f32_16x16x32_bf16 v[84:87], v[232:235], v[196:199], 0
	v_mfma_f32_16x16x32_bf16 v[80:83], v[240:243], v[196:199], 0
	v_mfma_f32_16x16x32_bf16 v[76:79], v[232:235], v[204:207], 0
	v_mfma_f32_16x16x32_bf16 v[72:75], v[240:243], v[204:207], 0
	v_mfma_f32_16x16x32_bf16 v[68:71], v[232:235], v[220:223], 0
	v_mfma_f32_16x16x32_bf16 v[64:67], v[240:243], v[220:223], 0
	v_mfma_f32_16x16x32_bf16 v[92:95], v[236:239], v[166:169], v[92:95]
	v_mfma_f32_16x16x32_bf16 v[88:91], v[244:247], v[166:169], v[88:91]
	v_mfma_f32_16x16x32_bf16 v[84:87], v[236:239], v[200:203], v[84:87]
	v_mfma_f32_16x16x32_bf16 v[80:83], v[244:247], v[200:203], v[80:83]
	v_mfma_f32_16x16x32_bf16 v[76:79], v[236:239], v[216:219], v[76:79]
	v_mfma_f32_16x16x32_bf16 v[72:75], v[244:247], v[216:219], v[72:75]
	v_mfma_f32_16x16x32_bf16 v[68:71], v[236:239], v[228:231], v[68:71]
	v_mfma_f32_16x16x32_bf16 v[64:67], v[244:247], v[228:231], v[64:67]
	s_barrier
	s_setprio 0
	s_mov_b32 m0, s77
	v_lshl_add_u64 v[224:225], s[52:53], 0, v[146:147]
	ds_read_b128 v[162:165], v194 offset:16384
	ds_read_b128 v[166:169], v194 offset:17408
	ds_read_b128 v[196:199], v194 offset:18432
	ds_read_b128 v[200:203], v194 offset:19456
	ds_read_b128 v[204:207], v194 offset:20480
	ds_read_b128 v[216:219], v194 offset:21504
	ds_read_b128 v[220:223], v194 offset:22528
	ds_read_b128 v[228:231], v194 offset:23552
	global_load_lds_dwordx4 v[224:225], off
	v_lshl_add_u64 v[248:249], s[52:53], 0, v[150:151]
	s_mov_b32 m0, s78
	s_nop 0
	global_load_lds_dwordx4 v[248:249], off
	s_setprio 1
	s_barrier
	s_waitcnt lgkmcnt(0)
	v_mfma_f32_16x16x32_bf16 v[60:63], v[128:131], v[162:165], 0
	v_mfma_f32_16x16x32_bf16 v[56:59], v[136:139], v[162:165], 0
	v_mfma_f32_16x16x32_bf16 v[52:55], v[128:131], v[196:199], 0
	v_mfma_f32_16x16x32_bf16 v[48:51], v[136:139], v[196:199], 0
	v_mfma_f32_16x16x32_bf16 v[44:47], v[128:131], v[204:207], 0
	v_mfma_f32_16x16x32_bf16 v[40:43], v[136:139], v[204:207], 0
	v_mfma_f32_16x16x32_bf16 v[36:39], v[128:131], v[220:223], 0
	v_mfma_f32_16x16x32_bf16 v[32:35], v[136:139], v[220:223], 0
	v_mfma_f32_16x16x32_bf16 v[60:63], v[132:135], v[166:169], v[60:63]
	v_mfma_f32_16x16x32_bf16 v[56:59], v[140:143], v[166:169], v[56:59]
	v_mfma_f32_16x16x32_bf16 v[52:55], v[132:135], v[200:203], v[52:55]
	v_mfma_f32_16x16x32_bf16 v[48:51], v[140:143], v[200:203], v[48:51]
	v_mfma_f32_16x16x32_bf16 v[44:47], v[132:135], v[216:219], v[44:47]
	v_mfma_f32_16x16x32_bf16 v[40:43], v[140:143], v[216:219], v[40:43]
	v_mfma_f32_16x16x32_bf16 v[36:39], v[132:135], v[228:231], v[36:39]
	v_mfma_f32_16x16x32_bf16 v[32:35], v[140:143], v[228:231], v[32:35]
	s_barrier
	s_setprio 0
	s_add_u32 s56, s50, 0x40000
	s_addc_u32 s57, s51, 0
	s_add_i32 s27, s27, s76
	v_lshl_add_u64 v[128:129], s[56:57], 0, v[148:149]
	s_mov_b32 m0, s27
	s_nop 0
	global_load_lds_dwordx4 v[128:129], off
	v_lshl_add_u64 v[128:129], s[56:57], 0, v[152:153]
	s_add_i32 m0, s27, 0x2000
	s_nop 0
	global_load_lds_dwordx4 v[128:129], off
	s_waitcnt vmcnt(6)
	s_setprio 1
	s_barrier
	v_mfma_f32_16x16x32_bf16 v[28:31], v[232:235], v[162:165], 0
	v_mfma_f32_16x16x32_bf16 v[24:27], v[240:243], v[162:165], 0
	v_mfma_f32_16x16x32_bf16 v[20:23], v[232:235], v[196:199], 0
	v_mfma_f32_16x16x32_bf16 v[16:19], v[240:243], v[196:199], 0
	v_mfma_f32_16x16x32_bf16 v[12:15], v[232:235], v[204:207], 0
	v_mfma_f32_16x16x32_bf16 v[8:11], v[240:243], v[204:207], 0
	v_mfma_f32_16x16x32_bf16 v[4:7], v[232:235], v[220:223], 0
	v_mfma_f32_16x16x32_bf16 v[0:3], v[240:243], v[220:223], 0
	v_mfma_f32_16x16x32_bf16 v[28:31], v[236:239], v[166:169], v[28:31]
	v_mfma_f32_16x16x32_bf16 v[24:27], v[244:247], v[166:169], v[24:27]
	v_mfma_f32_16x16x32_bf16 v[20:23], v[236:239], v[200:203], v[20:23]
	v_mfma_f32_16x16x32_bf16 v[16:19], v[244:247], v[200:203], v[16:19]
	v_mfma_f32_16x16x32_bf16 v[12:15], v[236:239], v[216:219], v[12:15]
	v_mfma_f32_16x16x32_bf16 v[8:11], v[244:247], v[216:219], v[8:11]
	v_mfma_f32_16x16x32_bf16 v[4:7], v[236:239], v[228:231], v[4:7]
	v_mfma_f32_16x16x32_bf16 v[0:3], v[244:247], v[228:231], v[0:3]
	s_barrier
	s_setprio 0
	s_add_i32 s27, 0, 0x18000
	v_add_u32_e32 v140, s27, v192
	ds_read_b128 v[128:131], v140
	ds_read_b128 v[132:135], v140 offset:1024
	ds_read_b128 v[136:139], v140 offset:2048
	ds_read_b128 v[140:143], v140 offset:3072
	s_add_u32 s52, s52, 0x40000
	s_addc_u32 s53, s53, 0
	s_mov_b32 m0, s81
	v_lshl_add_u64 v[232:233], s[52:53], 0, v[146:147]
	ds_read_b128 v[162:165], v194 offset:32768
	ds_read_b128 v[166:169], v194 offset:33792
	ds_read_b128 v[196:199], v194 offset:34816
	ds_read_b128 v[200:203], v194 offset:35840
	ds_read_b128 v[204:207], v194 offset:36864
	ds_read_b128 v[216:219], v194 offset:37888
	ds_read_b128 v[220:223], v194 offset:38912
	ds_read_b128 v[228:231], v194 offset:39936
	global_load_lds_dwordx4 v[232:233], off
	v_lshl_add_u64 v[232:233], s[52:53], 0, v[150:151]
	s_mov_b32 m0, s82
	s_nop 0
	global_load_lds_dwordx4 v[232:233], off
	s_waitcnt lgkmcnt(8)
	s_setprio 1
	s_barrier
	s_waitcnt lgkmcnt(0)
	v_mfma_f32_16x16x32_bf16 v[124:127], v[128:131], v[162:165], v[124:127]
	v_mfma_f32_16x16x32_bf16 v[120:123], v[136:139], v[162:165], v[120:123]
	v_mfma_f32_16x16x32_bf16 v[116:119], v[128:131], v[196:199], v[116:119]
	v_mfma_f32_16x16x32_bf16 v[112:115], v[136:139], v[196:199], v[112:115]
	v_mfma_f32_16x16x32_bf16 v[108:111], v[128:131], v[204:207], v[108:111]
	v_mfma_f32_16x16x32_bf16 v[104:107], v[136:139], v[204:207], v[104:107]
	v_mfma_f32_16x16x32_bf16 v[100:103], v[128:131], v[220:223], v[100:103]
	v_mfma_f32_16x16x32_bf16 v[96:99], v[136:139], v[220:223], v[96:99]
	v_mfma_f32_16x16x32_bf16 v[124:127], v[132:135], v[166:169], v[124:127]
	v_mfma_f32_16x16x32_bf16 v[120:123], v[140:143], v[166:169], v[120:123]
	v_mfma_f32_16x16x32_bf16 v[116:119], v[132:135], v[200:203], v[116:119]
	v_mfma_f32_16x16x32_bf16 v[112:115], v[140:143], v[200:203], v[112:115]
	v_mfma_f32_16x16x32_bf16 v[108:111], v[132:135], v[216:219], v[108:111]
	v_mfma_f32_16x16x32_bf16 v[104:107], v[140:143], v[216:219], v[104:107]
	v_mfma_f32_16x16x32_bf16 v[100:103], v[132:135], v[228:231], v[100:103]
	v_mfma_f32_16x16x32_bf16 v[96:99], v[140:143], v[228:231], v[96:99]
	s_barrier
	s_setprio 0
	s_add_i32 s37, 0, 0x1c000
	s_add_i32 s27, s27, s76
	v_add_u32_e32 v161, s37, v192
	v_lshl_add_u64 v[176:177], v[176:177], 0, s[18:19]
	s_mov_b32 m0, s27
	ds_read_b128 v[232:235], v161
	ds_read_b128 v[236:239], v161 offset:1024
	ds_read_b128 v[240:243], v161 offset:2048
	ds_read_b128 v[244:247], v161 offset:3072
	global_load_lds_dwordx4 v[176:177], off
	v_lshl_add_u64 v[176:177], v[188:189], 0, s[18:19]
	s_add_i32 m0, s27, 0x2000
	s_nop 0
	global_load_lds_dwordx4 v[176:177], off
	s_setprio 1
	s_barrier
	s_waitcnt lgkmcnt(0)
	v_mfma_f32_16x16x32_bf16 v[92:95], v[232:235], v[162:165], v[92:95]
	v_mfma_f32_16x16x32_bf16 v[88:91], v[240:243], v[162:165], v[88:91]
	v_mfma_f32_16x16x32_bf16 v[84:87], v[232:235], v[196:199], v[84:87]
	v_mfma_f32_16x16x32_bf16 v[80:83], v[240:243], v[196:199], v[80:83]
	v_mfma_f32_16x16x32_bf16 v[76:79], v[232:235], v[204:207], v[76:79]
	v_mfma_f32_16x16x32_bf16 v[72:75], v[240:243], v[204:207], v[72:75]
	v_mfma_f32_16x16x32_bf16 v[68:71], v[232:235], v[220:223], v[68:71]
	v_mfma_f32_16x16x32_bf16 v[64:67], v[240:243], v[220:223], v[64:67]
	v_mfma_f32_16x16x32_bf16 v[92:95], v[236:239], v[166:169], v[92:95]
	v_mfma_f32_16x16x32_bf16 v[88:91], v[244:247], v[166:169], v[88:91]
	v_mfma_f32_16x16x32_bf16 v[84:87], v[236:239], v[200:203], v[84:87]
	v_mfma_f32_16x16x32_bf16 v[80:83], v[244:247], v[200:203], v[80:83]
	v_mfma_f32_16x16x32_bf16 v[76:79], v[236:239], v[216:219], v[76:79]
	v_mfma_f32_16x16x32_bf16 v[72:75], v[244:247], v[216:219], v[72:75]
	v_mfma_f32_16x16x32_bf16 v[68:71], v[236:239], v[228:231], v[68:71]
	v_mfma_f32_16x16x32_bf16 v[64:67], v[244:247], v[228:231], v[64:67]
	s_barrier
	s_setprio 0
	s_mov_b32 m0, s80
	v_lshl_add_u64 v[176:177], v[224:225], 0, s[18:19]
	ds_read_b128 v[162:165], v194 offset:49152
	ds_read_b128 v[166:169], v194 offset:50176
	ds_read_b128 v[196:199], v194 offset:51200
	ds_read_b128 v[200:203], v194 offset:52224
	ds_read_b128 v[204:207], v194 offset:53248
	ds_read_b128 v[216:219], v194 offset:54272
	ds_read_b128 v[220:223], v194 offset:55296
	ds_read_b128 v[228:231], v194 offset:56320
	global_load_lds_dwordx4 v[176:177], off
	v_lshl_add_u64 v[176:177], v[248:249], 0, s[18:19]
	s_mov_b32 m0, s83
	s_nop 0
	global_load_lds_dwordx4 v[176:177], off
	s_setprio 1
	s_barrier
	s_waitcnt lgkmcnt(0)
	v_mfma_f32_16x16x32_bf16 v[60:63], v[128:131], v[162:165], v[60:63]
	v_mfma_f32_16x16x32_bf16 v[56:59], v[136:139], v[162:165], v[56:59]
	v_mfma_f32_16x16x32_bf16 v[52:55], v[128:131], v[196:199], v[52:55]
	v_mfma_f32_16x16x32_bf16 v[48:51], v[136:139], v[196:199], v[48:51]
	v_mfma_f32_16x16x32_bf16 v[44:47], v[128:131], v[204:207], v[44:47]
	v_mfma_f32_16x16x32_bf16 v[40:43], v[136:139], v[204:207], v[40:43]
	v_mfma_f32_16x16x32_bf16 v[36:39], v[128:131], v[220:223], v[36:39]
	v_mfma_f32_16x16x32_bf16 v[32:35], v[136:139], v[220:223], v[32:35]
	v_mfma_f32_16x16x32_bf16 v[60:63], v[132:135], v[166:169], v[60:63]
	v_mfma_f32_16x16x32_bf16 v[56:59], v[140:143], v[166:169], v[56:59]
	v_mfma_f32_16x16x32_bf16 v[52:55], v[132:135], v[200:203], v[52:55]
	v_mfma_f32_16x16x32_bf16 v[48:51], v[140:143], v[200:203], v[48:51]
	v_mfma_f32_16x16x32_bf16 v[44:47], v[132:135], v[216:219], v[44:47]
	v_mfma_f32_16x16x32_bf16 v[40:43], v[140:143], v[216:219], v[40:43]
	v_mfma_f32_16x16x32_bf16 v[36:39], v[132:135], v[228:231], v[36:39]
	v_mfma_f32_16x16x32_bf16 v[32:35], v[140:143], v[228:231], v[32:35]
	s_barrier
	s_setprio 0
	s_add_u32 s50, s50, 0x40080
	s_addc_u32 s51, s51, 0
	s_add_i32 s27, s37, s76
	v_lshl_add_u64 v[128:129], s[50:51], 0, v[148:149]
	s_mov_b32 m0, s27
	s_nop 0
	global_load_lds_dwordx4 v[128:129], off
	v_lshl_add_u64 v[128:129], s[50:51], 0, v[152:153]
	s_add_i32 m0, s27, 0x2000
	s_nop 0
	global_load_lds_dwordx4 v[128:129], off
	s_waitcnt vmcnt(6)
	s_setprio 1
	s_barrier
	v_mfma_f32_16x16x32_bf16 v[28:31], v[232:235], v[162:165], v[28:31]
	v_mfma_f32_16x16x32_bf16 v[24:27], v[240:243], v[162:165], v[24:27]
	v_mfma_f32_16x16x32_bf16 v[20:23], v[232:235], v[196:199], v[20:23]
	v_mfma_f32_16x16x32_bf16 v[16:19], v[240:243], v[196:199], v[16:19]
	v_mfma_f32_16x16x32_bf16 v[12:15], v[232:235], v[204:207], v[12:15]
	v_mfma_f32_16x16x32_bf16 v[8:11], v[240:243], v[204:207], v[8:11]
	v_mfma_f32_16x16x32_bf16 v[4:7], v[232:235], v[220:223], v[4:7]
	v_mfma_f32_16x16x32_bf16 v[0:3], v[240:243], v[220:223], v[0:3]
	v_mfma_f32_16x16x32_bf16 v[28:31], v[236:239], v[166:169], v[28:31]
	v_mfma_f32_16x16x32_bf16 v[24:27], v[244:247], v[166:169], v[24:27]
	v_mfma_f32_16x16x32_bf16 v[20:23], v[236:239], v[200:203], v[20:23]
	v_mfma_f32_16x16x32_bf16 v[16:19], v[244:247], v[200:203], v[16:19]
	v_mfma_f32_16x16x32_bf16 v[12:15], v[236:239], v[216:219], v[12:15]
	v_mfma_f32_16x16x32_bf16 v[8:11], v[244:247], v[216:219], v[8:11]
	v_mfma_f32_16x16x32_bf16 v[4:7], v[236:239], v[228:231], v[4:7]
	v_mfma_f32_16x16x32_bf16 v[0:3], v[244:247], v[228:231], v[0:3]
	s_barrier
	s_setprio 0
	s_add_i32 s36, s36, 2
	s_add_u32 s0, s0, 0x100
	s_addc_u32 s1, s1, 0
	s_add_u32 s34, s34, 0x100
	s_addc_u32 s35, s35, 0
	s_cmp_gt_u32 s36, 13
.LBB0_351:
	s_add_u32 s27, s0, 0xfffc0080
	s_addc_u32 s37, s1, -1
	s_add_i32 s47, 0, 0x10000
	v_add_u32_e32 v140, s47, v192
	ds_read_b128 v[128:131], v140
	ds_read_b128 v[132:135], v140 offset:1024
	ds_read_b128 v[136:139], v140 offset:2048
	ds_read_b128 v[140:143], v140 offset:3072
	s_cmp_eq_u32 s36, 12
	s_cselect_b32 s53, s25, s37
	s_cselect_b32 s52, s30, s27
	s_cselect_b32 s51, s31, s35
	s_cselect_b32 s50, s33, s34
	v_lshl_add_u64 v[176:177], s[0:1], 0, v[156:157]
	s_add_i32 m0, s77, 0xc000
	ds_read_b128 v[162:165], v194
	ds_read_b128 v[166:169], v194 offset:1024
	ds_read_b128 v[196:199], v194 offset:2048
	ds_read_b128 v[200:203], v194 offset:3072
	ds_read_b128 v[204:207], v194 offset:4096
	ds_read_b128 v[216:219], v194 offset:5120
	ds_read_b128 v[220:223], v194 offset:6144
	ds_read_b128 v[228:231], v194 offset:7168
	global_load_lds_dwordx4 v[176:177], off
	v_lshl_add_u64 v[176:177], s[0:1], 0, v[158:159]
	s_add_i32 m0, s77, 0xe000
	s_nop 0
	global_load_lds_dwordx4 v[176:177], off
	s_waitcnt lgkmcnt(8)
	s_setprio 1
	s_barrier
	s_waitcnt lgkmcnt(0)
	v_mfma_f32_16x16x32_bf16 v[124:127], v[128:131], v[162:165], v[124:127]
	v_mfma_f32_16x16x32_bf16 v[120:123], v[136:139], v[162:165], v[120:123]
	v_mfma_f32_16x16x32_bf16 v[116:119], v[128:131], v[196:199], v[116:119]
	v_mfma_f32_16x16x32_bf16 v[112:115], v[136:139], v[196:199], v[112:115]
	v_mfma_f32_16x16x32_bf16 v[108:111], v[128:131], v[204:207], v[108:111]
	v_mfma_f32_16x16x32_bf16 v[104:107], v[136:139], v[204:207], v[104:107]
	v_mfma_f32_16x16x32_bf16 v[100:103], v[128:131], v[220:223], v[100:103]
	v_mfma_f32_16x16x32_bf16 v[96:99], v[136:139], v[220:223], v[96:99]
	v_mfma_f32_16x16x32_bf16 v[124:127], v[132:135], v[166:169], v[124:127]
	v_mfma_f32_16x16x32_bf16 v[120:123], v[140:143], v[166:169], v[120:123]
	v_mfma_f32_16x16x32_bf16 v[116:119], v[132:135], v[200:203], v[116:119]
	v_mfma_f32_16x16x32_bf16 v[112:115], v[140:143], v[200:203], v[112:115]
	v_mfma_f32_16x16x32_bf16 v[108:111], v[132:135], v[216:219], v[108:111]
	v_mfma_f32_16x16x32_bf16 v[104:107], v[140:143], v[216:219], v[104:107]
	v_mfma_f32_16x16x32_bf16 v[100:103], v[132:135], v[228:231], v[100:103]
	v_mfma_f32_16x16x32_bf16 v[96:99], v[140:143], v[228:231], v[96:99]
	s_barrier
	s_setprio 0
	s_add_i32 s27, 0, 0x14000
	s_add_i32 s37, s47, s76
	v_add_u32_e32 v161, s27, v192
	v_lshl_add_u64 v[176:177], s[50:51], 0, v[148:149]
	s_mov_b32 m0, s37
	ds_read_b128 v[232:235], v161
	ds_read_b128 v[236:239], v161 offset:1024
	ds_read_b128 v[240:243], v161 offset:2048
	ds_read_b128 v[244:247], v161 offset:3072
	global_load_lds_dwordx4 v[176:177], off
	v_lshl_add_u64 v[188:189], s[50:51], 0, v[152:153]
	s_add_i32 m0, s37, 0x2000
	s_nop 0
	global_load_lds_dwordx4 v[188:189], off
	s_setprio 1
	s_barrier
	s_waitcnt lgkmcnt(0)
	v_mfma_f32_16x16x32_bf16 v[92:95], v[232:235], v[162:165], v[92:95]
	v_mfma_f32_16x16x32_bf16 v[88:91], v[240:243], v[162:165], v[88:91]
	v_mfma_f32_16x16x32_bf16 v[84:87], v[232:235], v[196:199], v[84:87]
	v_mfma_f32_16x16x32_bf16 v[80:83], v[240:243], v[196:199], v[80:83]
	v_mfma_f32_16x16x32_bf16 v[76:79], v[232:235], v[204:207], v[76:79]
	v_mfma_f32_16x16x32_bf16 v[72:75], v[240:243], v[204:207], v[72:75]
	v_mfma_f32_16x16x32_bf16 v[68:71], v[232:235], v[220:223], v[68:71]
	v_mfma_f32_16x16x32_bf16 v[64:67], v[240:243], v[220:223], v[64:67]
	v_mfma_f32_16x16x32_bf16 v[92:95], v[236:239], v[166:169], v[92:95]
	v_mfma_f32_16x16x32_bf16 v[88:91], v[244:247], v[166:169], v[88:91]
	v_mfma_f32_16x16x32_bf16 v[84:87], v[236:239], v[200:203], v[84:87]
	v_mfma_f32_16x16x32_bf16 v[80:83], v[244:247], v[200:203], v[80:83]
	v_mfma_f32_16x16x32_bf16 v[76:79], v[236:239], v[216:219], v[76:79]
	v_mfma_f32_16x16x32_bf16 v[72:75], v[244:247], v[216:219], v[72:75]
	v_mfma_f32_16x16x32_bf16 v[68:71], v[236:239], v[228:231], v[68:71]
	v_mfma_f32_16x16x32_bf16 v[64:67], v[244:247], v[228:231], v[64:67]
	s_barrier
	s_setprio 0
	s_mov_b32 m0, s77
	v_lshl_add_u64 v[224:225], s[52:53], 0, v[146:147]
	ds_read_b128 v[162:165], v194 offset:16384
	ds_read_b128 v[166:169], v194 offset:17408
	ds_read_b128 v[196:199], v194 offset:18432
	ds_read_b128 v[200:203], v194 offset:19456
	ds_read_b128 v[204:207], v194 offset:20480
	ds_read_b128 v[216:219], v194 offset:21504
	ds_read_b128 v[220:223], v194 offset:22528
	ds_read_b128 v[228:231], v194 offset:23552
	global_load_lds_dwordx4 v[224:225], off
	v_lshl_add_u64 v[248:249], s[52:53], 0, v[150:151]
	s_mov_b32 m0, s78
	s_nop 0
	global_load_lds_dwordx4 v[248:249], off
	s_setprio 1
	s_barrier
	s_waitcnt lgkmcnt(0)
	v_mfma_f32_16x16x32_bf16 v[60:63], v[128:131], v[162:165], v[60:63]
	v_mfma_f32_16x16x32_bf16 v[56:59], v[136:139], v[162:165], v[56:59]
	v_mfma_f32_16x16x32_bf16 v[52:55], v[128:131], v[196:199], v[52:55]
	v_mfma_f32_16x16x32_bf16 v[48:51], v[136:139], v[196:199], v[48:51]
	v_mfma_f32_16x16x32_bf16 v[44:47], v[128:131], v[204:207], v[44:47]
	v_mfma_f32_16x16x32_bf16 v[40:43], v[136:139], v[204:207], v[40:43]
	v_mfma_f32_16x16x32_bf16 v[36:39], v[128:131], v[220:223], v[36:39]
	v_mfma_f32_16x16x32_bf16 v[32:35], v[136:139], v[220:223], v[32:35]
	v_mfma_f32_16x16x32_bf16 v[60:63], v[132:135], v[166:169], v[60:63]
	v_mfma_f32_16x16x32_bf16 v[56:59], v[140:143], v[166:169], v[56:59]
	v_mfma_f32_16x16x32_bf16 v[52:55], v[132:135], v[200:203], v[52:55]
	v_mfma_f32_16x16x32_bf16 v[48:51], v[140:143], v[200:203], v[48:51]
	v_mfma_f32_16x16x32_bf16 v[44:47], v[132:135], v[216:219], v[44:47]
	v_mfma_f32_16x16x32_bf16 v[40:43], v[140:143], v[216:219], v[40:43]
	v_mfma_f32_16x16x32_bf16 v[36:39], v[132:135], v[228:231], v[36:39]
	v_mfma_f32_16x16x32_bf16 v[32:35], v[140:143], v[228:231], v[32:35]
	s_barrier
	s_setprio 0
	s_add_u32 s56, s50, 0x40000
	s_addc_u32 s57, s51, 0
	s_add_i32 s27, s27, s76
	v_lshl_add_u64 v[128:129], s[56:57], 0, v[148:149]
	s_mov_b32 m0, s27
	s_nop 0
	global_load_lds_dwordx4 v[128:129], off
	v_lshl_add_u64 v[128:129], s[56:57], 0, v[152:153]
	s_add_i32 m0, s27, 0x2000
	s_nop 0
	global_load_lds_dwordx4 v[128:129], off
	s_waitcnt vmcnt(6)
	s_setprio 1
	s_barrier
	v_mfma_f32_16x16x32_bf16 v[28:31], v[232:235], v[162:165], v[28:31]
	v_mfma_f32_16x16x32_bf16 v[24:27], v[240:243], v[162:165], v[24:27]
	v_mfma_f32_16x16x32_bf16 v[20:23], v[232:235], v[196:199], v[20:23]
	v_mfma_f32_16x16x32_bf16 v[16:19], v[240:243], v[196:199], v[16:19]
	v_mfma_f32_16x16x32_bf16 v[12:15], v[232:235], v[204:207], v[12:15]
	v_mfma_f32_16x16x32_bf16 v[8:11], v[240:243], v[204:207], v[8:11]
	v_mfma_f32_16x16x32_bf16 v[4:7], v[232:235], v[220:223], v[4:7]
	v_mfma_f32_16x16x32_bf16 v[0:3], v[240:243], v[220:223], v[0:3]
	v_mfma_f32_16x16x32_bf16 v[28:31], v[236:239], v[166:169], v[28:31]
	v_mfma_f32_16x16x32_bf16 v[24:27], v[244:247], v[166:169], v[24:27]
	v_mfma_f32_16x16x32_bf16 v[20:23], v[236:239], v[200:203], v[20:23]
	v_mfma_f32_16x16x32_bf16 v[16:19], v[244:247], v[200:203], v[16:19]
	v_mfma_f32_16x16x32_bf16 v[12:15], v[236:239], v[216:219], v[12:15]
	v_mfma_f32_16x16x32_bf16 v[8:11], v[244:247], v[216:219], v[8:11]
	v_mfma_f32_16x16x32_bf16 v[4:7], v[236:239], v[228:231], v[4:7]
	v_mfma_f32_16x16x32_bf16 v[0:3], v[244:247], v[228:231], v[0:3]
	s_barrier
	s_setprio 0
	s_add_i32 s27, 0, 0x18000
	v_add_u32_e32 v140, s27, v192
	ds_read_b128 v[128:131], v140
	ds_read_b128 v[132:135], v140 offset:1024
	ds_read_b128 v[136:139], v140 offset:2048
	ds_read_b128 v[140:143], v140 offset:3072
	s_add_u32 s52, s52, 0x40000
	s_addc_u32 s53, s53, 0
	s_mov_b32 m0, s81
	v_lshl_add_u64 v[232:233], s[52:53], 0, v[146:147]
	ds_read_b128 v[162:165], v194 offset:32768
	ds_read_b128 v[166:169], v194 offset:33792
	ds_read_b128 v[196:199], v194 offset:34816
	ds_read_b128 v[200:203], v194 offset:35840
	ds_read_b128 v[204:207], v194 offset:36864
	ds_read_b128 v[216:219], v194 offset:37888
	ds_read_b128 v[220:223], v194 offset:38912
	ds_read_b128 v[228:231], v194 offset:39936
	global_load_lds_dwordx4 v[232:233], off
	v_lshl_add_u64 v[232:233], s[52:53], 0, v[150:151]
	s_mov_b32 m0, s82
	s_nop 0
	global_load_lds_dwordx4 v[232:233], off
	s_waitcnt lgkmcnt(8)
	s_setprio 1
	s_barrier
	s_waitcnt lgkmcnt(0)
	v_mfma_f32_16x16x32_bf16 v[124:127], v[128:131], v[162:165], v[124:127]
	v_mfma_f32_16x16x32_bf16 v[120:123], v[136:139], v[162:165], v[120:123]
	v_mfma_f32_16x16x32_bf16 v[116:119], v[128:131], v[196:199], v[116:119]
	v_mfma_f32_16x16x32_bf16 v[112:115], v[136:139], v[196:199], v[112:115]
	v_mfma_f32_16x16x32_bf16 v[108:111], v[128:131], v[204:207], v[108:111]
	v_mfma_f32_16x16x32_bf16 v[104:107], v[136:139], v[204:207], v[104:107]
	v_mfma_f32_16x16x32_bf16 v[100:103], v[128:131], v[220:223], v[100:103]
	v_mfma_f32_16x16x32_bf16 v[96:99], v[136:139], v[220:223], v[96:99]
	v_mfma_f32_16x16x32_bf16 v[124:127], v[132:135], v[166:169], v[124:127]
	v_mfma_f32_16x16x32_bf16 v[120:123], v[140:143], v[166:169], v[120:123]
	v_mfma_f32_16x16x32_bf16 v[116:119], v[132:135], v[200:203], v[116:119]
	v_mfma_f32_16x16x32_bf16 v[112:115], v[140:143], v[200:203], v[112:115]
	v_mfma_f32_16x16x32_bf16 v[108:111], v[132:135], v[216:219], v[108:111]
	v_mfma_f32_16x16x32_bf16 v[104:107], v[140:143], v[216:219], v[104:107]
	v_mfma_f32_16x16x32_bf16 v[100:103], v[132:135], v[228:231], v[100:103]
	v_mfma_f32_16x16x32_bf16 v[96:99], v[140:143], v[228:231], v[96:99]
	s_barrier
	s_setprio 0
	s_add_i32 s37, 0, 0x1c000
	s_add_i32 s27, s27, s76
	v_add_u32_e32 v161, s37, v192
	v_lshl_add_u64 v[176:177], v[176:177], 0, s[18:19]
	s_mov_b32 m0, s27
	ds_read_b128 v[232:235], v161
	ds_read_b128 v[236:239], v161 offset:1024
	ds_read_b128 v[240:243], v161 offset:2048
	ds_read_b128 v[244:247], v161 offset:3072
	global_load_lds_dwordx4 v[176:177], off
	v_lshl_add_u64 v[176:177], v[188:189], 0, s[18:19]
	s_add_i32 m0, s27, 0x2000
	s_nop 0
	global_load_lds_dwordx4 v[176:177], off
	s_setprio 1
	s_barrier
	s_waitcnt lgkmcnt(0)
	v_mfma_f32_16x16x32_bf16 v[92:95], v[232:235], v[162:165], v[92:95]
	v_mfma_f32_16x16x32_bf16 v[88:91], v[240:243], v[162:165], v[88:91]
	v_mfma_f32_16x16x32_bf16 v[84:87], v[232:235], v[196:199], v[84:87]
	v_mfma_f32_16x16x32_bf16 v[80:83], v[240:243], v[196:199], v[80:83]
	v_mfma_f32_16x16x32_bf16 v[76:79], v[232:235], v[204:207], v[76:79]
	v_mfma_f32_16x16x32_bf16 v[72:75], v[240:243], v[204:207], v[72:75]
	v_mfma_f32_16x16x32_bf16 v[68:71], v[232:235], v[220:223], v[68:71]
	v_mfma_f32_16x16x32_bf16 v[64:67], v[240:243], v[220:223], v[64:67]
	v_mfma_f32_16x16x32_bf16 v[92:95], v[236:239], v[166:169], v[92:95]
	v_mfma_f32_16x16x32_bf16 v[88:91], v[244:247], v[166:169], v[88:91]
	v_mfma_f32_16x16x32_bf16 v[84:87], v[236:239], v[200:203], v[84:87]
	v_mfma_f32_16x16x32_bf16 v[80:83], v[244:247], v[200:203], v[80:83]
	v_mfma_f32_16x16x32_bf16 v[76:79], v[236:239], v[216:219], v[76:79]
	v_mfma_f32_16x16x32_bf16 v[72:75], v[244:247], v[216:219], v[72:75]
	v_mfma_f32_16x16x32_bf16 v[68:71], v[236:239], v[228:231], v[68:71]
	v_mfma_f32_16x16x32_bf16 v[64:67], v[244:247], v[228:231], v[64:67]
	s_barrier
	s_setprio 0
	s_mov_b32 m0, s80
	v_lshl_add_u64 v[176:177], v[224:225], 0, s[18:19]
	ds_read_b128 v[162:165], v194 offset:49152
	ds_read_b128 v[166:169], v194 offset:50176
	ds_read_b128 v[196:199], v194 offset:51200
	ds_read_b128 v[200:203], v194 offset:52224
	ds_read_b128 v[204:207], v194 offset:53248
	ds_read_b128 v[216:219], v194 offset:54272
	ds_read_b128 v[220:223], v194 offset:55296
	ds_read_b128 v[228:231], v194 offset:56320
	global_load_lds_dwordx4 v[176:177], off
	v_lshl_add_u64 v[176:177], v[248:249], 0, s[18:19]
	s_mov_b32 m0, s83
	s_nop 0
	global_load_lds_dwordx4 v[176:177], off
	s_setprio 1
	s_barrier
	s_waitcnt lgkmcnt(0)
	v_mfma_f32_16x16x32_bf16 v[60:63], v[128:131], v[162:165], v[60:63]
	v_mfma_f32_16x16x32_bf16 v[56:59], v[136:139], v[162:165], v[56:59]
	v_mfma_f32_16x16x32_bf16 v[52:55], v[128:131], v[196:199], v[52:55]
	v_mfma_f32_16x16x32_bf16 v[48:51], v[136:139], v[196:199], v[48:51]
	v_mfma_f32_16x16x32_bf16 v[44:47], v[128:131], v[204:207], v[44:47]
	v_mfma_f32_16x16x32_bf16 v[40:43], v[136:139], v[204:207], v[40:43]
	v_mfma_f32_16x16x32_bf16 v[36:39], v[128:131], v[220:223], v[36:39]
	v_mfma_f32_16x16x32_bf16 v[32:35], v[136:139], v[220:223], v[32:35]
	v_mfma_f32_16x16x32_bf16 v[60:63], v[132:135], v[166:169], v[60:63]
	v_mfma_f32_16x16x32_bf16 v[56:59], v[140:143], v[166:169], v[56:59]
	v_mfma_f32_16x16x32_bf16 v[52:55], v[132:135], v[200:203], v[52:55]
	v_mfma_f32_16x16x32_bf16 v[48:51], v[140:143], v[200:203], v[48:51]
	v_mfma_f32_16x16x32_bf16 v[44:47], v[132:135], v[216:219], v[44:47]
	v_mfma_f32_16x16x32_bf16 v[40:43], v[140:143], v[216:219], v[40:43]
	v_mfma_f32_16x16x32_bf16 v[36:39], v[132:135], v[228:231], v[36:39]
	v_mfma_f32_16x16x32_bf16 v[32:35], v[140:143], v[228:231], v[32:35]
	s_barrier
	s_setprio 0
	s_add_u32 s50, s50, 0x40080
	s_addc_u32 s51, s51, 0
	s_add_i32 s27, s37, s76
	v_lshl_add_u64 v[128:129], s[50:51], 0, v[148:149]
	s_mov_b32 m0, s27
	s_nop 0
	global_load_lds_dwordx4 v[128:129], off
	v_lshl_add_u64 v[128:129], s[50:51], 0, v[152:153]
	s_add_i32 m0, s27, 0x2000
	s_nop 0
	global_load_lds_dwordx4 v[128:129], off
	s_waitcnt vmcnt(6)
	s_setprio 1
	s_barrier
	v_mfma_f32_16x16x32_bf16 v[28:31], v[232:235], v[162:165], v[28:31]
	v_mfma_f32_16x16x32_bf16 v[24:27], v[240:243], v[162:165], v[24:27]
	v_mfma_f32_16x16x32_bf16 v[20:23], v[232:235], v[196:199], v[20:23]
	v_mfma_f32_16x16x32_bf16 v[16:19], v[240:243], v[196:199], v[16:19]
	v_mfma_f32_16x16x32_bf16 v[12:15], v[232:235], v[204:207], v[12:15]
	v_mfma_f32_16x16x32_bf16 v[8:11], v[240:243], v[204:207], v[8:11]
	v_mfma_f32_16x16x32_bf16 v[4:7], v[232:235], v[220:223], v[4:7]
	v_mfma_f32_16x16x32_bf16 v[0:3], v[240:243], v[220:223], v[0:3]
	v_mfma_f32_16x16x32_bf16 v[28:31], v[236:239], v[166:169], v[28:31]
	v_mfma_f32_16x16x32_bf16 v[24:27], v[244:247], v[166:169], v[24:27]
	v_mfma_f32_16x16x32_bf16 v[20:23], v[236:239], v[200:203], v[20:23]
	v_mfma_f32_16x16x32_bf16 v[16:19], v[244:247], v[200:203], v[16:19]
	v_mfma_f32_16x16x32_bf16 v[12:15], v[236:239], v[216:219], v[12:15]
	v_mfma_f32_16x16x32_bf16 v[8:11], v[244:247], v[216:219], v[8:11]
	v_mfma_f32_16x16x32_bf16 v[4:7], v[236:239], v[228:231], v[4:7]
	v_mfma_f32_16x16x32_bf16 v[0:3], v[244:247], v[228:231], v[0:3]
	s_barrier
	s_setprio 0
	s_add_i32 s36, s36, 2
	s_add_u32 s0, s0, 0x100
	s_addc_u32 s1, s1, 0
	s_add_u32 s34, s34, 0x100
	s_addc_u32 s35, s35, 0
	s_cmp_gt_u32 s36, 13
	s_cbranch_scc0 .LBB0_351
	s_lshl_b32 s0, s11, 8
	s_or_b32 s50, s0, s79
	s_ashr_i32 s51, s50, 31
	v_lshl_add_u64 v[140:141], s[50:51], 3, v[154:155]
	global_load_dwordx4 v[128:131], v[140:141], off offset:48
	global_load_dwordx4 v[132:135], v[140:141], off offset:32
	global_load_dwordx4 v[136:139], v[140:141], off offset:16
	global_load_dwordx4 v[162:165], v[140:141], off
	s_mov_b32 s34, 0x35800000
	s_mov_b32 s0, 0x358637bd
	v_mov_b64_e32 v[168:169], s[0:1]
	s_mov_b32 s30, 0x45800000
	s_cmp_lt_u32 s10, 2
	s_waitcnt vmcnt(0)
	v_ffbh_u32_e32 v142, v165
	v_min_u32_e32 v161, 32, v142
	v_lshlrev_b64 v[142:143], v161, v[164:165]
	v_min_u32_e32 v142, 1, v142
	v_or_b32_e32 v142, v143, v142
	v_cvt_f32_u32_e32 v142, v142
	v_sub_u32_e32 v143, 32, v161
	v_ldexp_f32 v143, v142, v143
	v_ffbh_u32_e32 v142, v163
	v_min_u32_e32 v142, 32, v142
	v_lshlrev_b64 v[162:163], v142, v[162:163]
	v_min_u32_e32 v161, 1, v162
	v_or_b32_e32 v161, v163, v161
	v_cvt_f32_u32_e32 v161, v161
	v_sub_u32_e32 v142, 32, v142
	v_ldexp_f32 v142, v161, v142
	v_pk_mul_f32 v[142:143], v[142:143], s[34:35] op_sel_hi:[1,0]
	s_nop 0
	v_pk_fma_f32 v[142:143], v[142:143], s[2:3], v[168:169] op_sel_hi:[1,0,0]
	s_nop 0
	v_mul_f32_e32 v161, 0x4b800000, v142
	v_cmp_gt_f32_e64 s[0:1], s89, v142
	v_cmp_gt_f32_e32 vcc, s89, v143
	s_nop 0
	v_cndmask_b32_e64 v142, v142, v161, s[0:1]
	v_mul_f32_e32 v161, 0x4b800000, v143
	v_cndmask_b32_e32 v143, v143, v161, vcc
	v_rsq_f32_e32 v142, v142
	v_rsq_f32_e32 v143, v143
	s_nop 0
	v_pk_mul_f32 v[162:163], v[142:143], s[30:31] op_sel_hi:[1,0]
	s_nop 0
	v_cndmask_b32_e64 v166, v142, v162, s[0:1]
	v_ffbh_u32_e32 v142, v139
	v_min_u32_e32 v142, 32, v142
	v_lshlrev_b64 v[138:139], v142, v[138:139]
	v_min_u32_e32 v138, 1, v138
	v_or_b32_e32 v138, v139, v138
	v_cvt_f32_u32_e32 v138, v138
	v_sub_u32_e32 v139, 32, v142
	v_cndmask_b32_e32 v167, v143, v163, vcc
	v_pk_mul_f32 v[60:61], v[60:61], v[166:167]
	v_ldexp_f32 v139, v138, v139
	v_ffbh_u32_e32 v138, v137
	v_min_u32_e32 v138, 32, v138
	v_lshlrev_b64 v[136:137], v138, v[136:137]
	v_min_u32_e32 v136, 1, v136
	v_or_b32_e32 v136, v137, v136
	v_cvt_f32_u32_e32 v136, v136
	v_sub_u32_e32 v137, 32, v138
	v_pk_mul_f32 v[52:53], v[52:53], v[166:167]
	v_pk_mul_f32 v[44:45], v[44:45], v[166:167]
	v_ldexp_f32 v138, v136, v137
	v_pk_mul_f32 v[136:137], v[138:139], s[34:35] op_sel_hi:[1,0]
	v_pk_mul_f32 v[36:37], v[36:37], v[166:167]
	v_pk_fma_f32 v[136:137], v[136:137], s[2:3], v[168:169] op_sel_hi:[1,0,0]
	s_nop 0
	v_mul_f32_e32 v138, 0x4b800000, v136
	v_cmp_gt_f32_e64 s[0:1], s89, v136
	v_cmp_gt_f32_e32 vcc, s89, v137
	s_nop 0
	v_cndmask_b32_e64 v136, v136, v138, s[0:1]
	v_mul_f32_e32 v138, 0x4b800000, v137
	v_cndmask_b32_e32 v137, v137, v138, vcc
	v_rsq_f32_e32 v136, v136
	v_rsq_f32_e32 v137, v137
	s_nop 0
	v_pk_mul_f32 v[138:139], v[136:137], s[30:31] op_sel_hi:[1,0]
	s_nop 0
	v_cndmask_b32_e64 v162, v136, v138, s[0:1]
	v_ffbh_u32_e32 v136, v135
	v_min_u32_e32 v136, 32, v136
	v_lshlrev_b64 v[134:135], v136, v[134:135]
	v_min_u32_e32 v134, 1, v134
	v_or_b32_e32 v134, v135, v134
	v_cvt_f32_u32_e32 v134, v134
	v_sub_u32_e32 v135, 32, v136
	v_cndmask_b32_e32 v163, v137, v139, vcc
	v_ldexp_f32 v135, v134, v135
	v_ffbh_u32_e32 v134, v133
	v_min_u32_e32 v134, 32, v134
	v_lshlrev_b64 v[132:133], v134, v[132:133]
	v_min_u32_e32 v132, 1, v132
	v_or_b32_e32 v132, v133, v132
	v_cvt_f32_u32_e32 v132, v132
	v_sub_u32_e32 v133, 32, v134
	v_ldexp_f32 v134, v132, v133
	v_pk_mul_f32 v[132:133], v[134:135], s[34:35] op_sel_hi:[1,0]
	s_nop 0
	v_pk_fma_f32 v[132:133], v[132:133], s[2:3], v[168:169] op_sel_hi:[1,0,0]
	s_nop 0
	v_mul_f32_e32 v134, 0x4b800000, v132
	v_cmp_gt_f32_e64 s[0:1], s89, v132
	v_cmp_gt_f32_e32 vcc, s89, v133
	s_nop 0
	v_cndmask_b32_e64 v132, v132, v134, s[0:1]
	v_mul_f32_e32 v134, 0x4b800000, v133
	v_cndmask_b32_e32 v133, v133, v134, vcc
	v_rsq_f32_e32 v132, v132
	v_rsq_f32_e32 v133, v133
	s_nop 0
	v_pk_mul_f32 v[134:135], v[132:133], s[30:31] op_sel_hi:[1,0]
	s_nop 0
	v_cndmask_b32_e64 v188, v132, v134, s[0:1]
	v_ffbh_u32_e32 v132, v131
	v_min_u32_e32 v132, 32, v132
	v_lshlrev_b64 v[130:131], v132, v[130:131]
	v_min_u32_e32 v130, 1, v130
	v_or_b32_e32 v130, v131, v130
	v_cvt_f32_u32_e32 v130, v130
	v_sub_u32_e32 v131, 32, v132
	v_cndmask_b32_e32 v189, v133, v135, vcc
	v_pk_mul_f32 v[56:57], v[56:57], v[188:189]
	v_ldexp_f32 v131, v130, v131
	v_ffbh_u32_e32 v130, v129
	v_min_u32_e32 v130, 32, v130
	v_lshlrev_b64 v[128:129], v130, v[128:129]
	v_min_u32_e32 v128, 1, v128
	v_or_b32_e32 v128, v129, v128
	v_cvt_f32_u32_e32 v128, v128
	v_sub_u32_e32 v129, 32, v130
	v_pk_mul_f32 v[48:49], v[48:49], v[188:189]
	v_pk_mul_f32 v[40:41], v[40:41], v[188:189]
	v_ldexp_f32 v130, v128, v129
	v_pk_mul_f32 v[128:129], v[130:131], s[34:35] op_sel_hi:[1,0]
	v_pk_mul_f32 v[32:33], v[32:33], v[188:189]
	v_pk_fma_f32 v[128:129], v[128:129], s[2:3], v[168:169] op_sel_hi:[1,0,0]
	s_nop 0
	v_mul_f32_e32 v130, 0x4b800000, v128
	v_cmp_gt_f32_e64 s[0:1], s89, v128
	v_cmp_gt_f32_e32 vcc, s89, v129
	s_nop 0
	v_cndmask_b32_e64 v128, v128, v130, s[0:1]
	v_mul_f32_e32 v130, 0x4b800000, v129
	v_cndmask_b32_e32 v129, v129, v130, vcc
	v_rsq_f32_e32 v128, v128
	v_rsq_f32_e32 v129, v129
	s_nop 0
	v_pk_mul_f32 v[130:131], v[128:129], s[30:31] op_sel_hi:[1,0]
	s_nop 0
	v_cndmask_b32_e32 v165, v129, v131, vcc
	v_cndmask_b32_e64 v164, v128, v130, s[0:1]
	global_load_dwordx4 v[128:131], v[140:141], off offset:1072
	global_load_dwordx4 v[132:135], v[140:141], off offset:1056
	global_load_dwordx4 v[136:139], v[140:141], off offset:1040
	s_nop 0
	global_load_dwordx4 v[140:143], v[140:141], off offset:1024
	s_waitcnt vmcnt(0)
	v_ffbh_u32_e32 v161, v143
	v_min_u32_e32 v161, 32, v161
	v_lshlrev_b64 v[142:143], v161, v[142:143]
	v_min_u32_e32 v142, 1, v142
	v_or_b32_e32 v142, v143, v142
	v_cvt_f32_u32_e32 v142, v142
	v_sub_u32_e32 v143, 32, v161
	v_ldexp_f32 v143, v142, v143
	v_ffbh_u32_e32 v142, v141
	v_min_u32_e32 v142, 32, v142
	v_lshlrev_b64 v[140:141], v142, v[140:141]
	v_min_u32_e32 v140, 1, v140
	v_or_b32_e32 v140, v141, v140
	v_cvt_f32_u32_e32 v140, v140
	v_sub_u32_e32 v141, 32, v142
	v_ldexp_f32 v142, v140, v141
	v_pk_mul_f32 v[140:141], v[142:143], s[34:35] op_sel_hi:[1,0]
	s_nop 0
	v_pk_fma_f32 v[140:141], v[140:141], s[2:3], v[168:169] op_sel_hi:[1,0,0]
	s_nop 0
	v_mul_f32_e32 v142, 0x4b800000, v140
	v_cmp_gt_f32_e64 s[0:1], s89, v140
	v_cmp_gt_f32_e32 vcc, s89, v141
	s_nop 0
	v_cndmask_b32_e64 v140, v140, v142, s[0:1]
	v_mul_f32_e32 v142, 0x4b800000, v141
	v_cndmask_b32_e32 v141, v141, v142, vcc
	v_rsq_f32_e32 v140, v140
	v_rsq_f32_e32 v141, v141
	s_nop 0
	v_pk_mul_f32 v[142:143], v[140:141], s[30:31] op_sel_hi:[1,0]
	s_nop 0
	v_cndmask_b32_e64 v142, v140, v142, s[0:1]
	v_ffbh_u32_e32 v140, v139
	v_min_u32_e32 v140, 32, v140
	v_lshlrev_b64 v[138:139], v140, v[138:139]
	v_min_u32_e32 v138, 1, v138
	v_or_b32_e32 v138, v139, v138
	v_cvt_f32_u32_e32 v138, v138
	v_sub_u32_e32 v139, 32, v140
	v_cndmask_b32_e32 v143, v141, v143, vcc
	v_pk_mul_f32 v[140:141], v[124:125], v[166:167]
	v_ldexp_f32 v139, v138, v139
	v_ffbh_u32_e32 v138, v137
	v_min_u32_e32 v138, 32, v138
	v_lshlrev_b64 v[136:137], v138, v[136:137]
	v_min_u32_e32 v136, 1, v136
	v_or_b32_e32 v136, v137, v136
	v_cvt_f32_u32_e32 v136, v136
	v_sub_u32_e32 v137, 32, v138
	v_pk_mul_f32 v[28:29], v[28:29], v[142:143]
	v_pk_mul_f32 v[20:21], v[20:21], v[142:143]
	v_ldexp_f32 v138, v136, v137
	v_pk_mul_f32 v[136:137], v[138:139], s[34:35] op_sel_hi:[1,0]
	v_pk_mul_f32 v[12:13], v[12:13], v[142:143]
	v_pk_fma_f32 v[136:137], v[136:137], s[2:3], v[168:169] op_sel_hi:[1,0,0]
	v_pk_mul_f32 v[4:5], v[4:5], v[142:143]
	v_mul_f32_e32 v138, 0x4b800000, v136
	v_cmp_gt_f32_e64 s[0:1], s89, v136
	v_cmp_gt_f32_e32 vcc, s89, v137
	s_nop 0
	v_cndmask_b32_e64 v136, v136, v138, s[0:1]
	v_mul_f32_e32 v138, 0x4b800000, v137
	v_cndmask_b32_e32 v137, v137, v138, vcc
	v_rsq_f32_e32 v136, v136
	v_rsq_f32_e32 v137, v137
	s_nop 0
	v_pk_mul_f32 v[138:139], v[136:137], s[30:31] op_sel_hi:[1,0]
	s_nop 0
	v_cndmask_b32_e64 v136, v136, v138, s[0:1]
	v_ffbh_u32_e32 v138, v135
	v_min_u32_e32 v138, 32, v138
	v_lshlrev_b64 v[134:135], v138, v[134:135]
	v_min_u32_e32 v134, 1, v134
	v_or_b32_e32 v134, v135, v134
	v_cvt_f32_u32_e32 v134, v134
	v_sub_u32_e32 v135, 32, v138
	v_cndmask_b32_e32 v137, v137, v139, vcc
	v_pk_mul_f32 v[138:139], v[120:121], v[188:189]
	v_ldexp_f32 v135, v134, v135
	v_ffbh_u32_e32 v134, v133
	v_min_u32_e32 v134, 32, v134
	v_lshlrev_b64 v[132:133], v134, v[132:133]
	v_min_u32_e32 v132, 1, v132
	v_or_b32_e32 v132, v133, v132
	v_cvt_f32_u32_e32 v132, v132
	v_sub_u32_e32 v133, 32, v134
	v_pk_mul_f32 v[120:121], v[84:85], v[142:143]
	v_ldexp_f32 v134, v132, v133
	v_pk_mul_f32 v[132:133], v[134:135], s[34:35] op_sel_hi:[1,0]
	s_nop 0
	v_pk_fma_f32 v[132:133], v[132:133], s[2:3], v[168:169] op_sel_hi:[1,0,0]
	s_nop 0
	v_mul_f32_e32 v134, 0x4b800000, v132
	v_cmp_gt_f32_e64 s[0:1], s89, v132
	v_cmp_gt_f32_e32 vcc, s89, v133
	s_nop 0
	v_cndmask_b32_e64 v132, v132, v134, s[0:1]
	v_mul_f32_e32 v134, 0x4b800000, v133
	v_cndmask_b32_e32 v133, v133, v134, vcc
	v_rsq_f32_e32 v132, v132
	v_rsq_f32_e32 v133, v133
	s_nop 0
	v_pk_mul_f32 v[134:135], v[132:133], s[30:31] op_sel_hi:[1,0]
	s_nop 0
	v_cndmask_b32_e64 v176, v132, v134, s[0:1]
	v_ffbh_u32_e32 v132, v131
	v_min_u32_e32 v132, 32, v132
	v_lshlrev_b64 v[130:131], v132, v[130:131]
	v_min_u32_e32 v130, 1, v130
	v_or_b32_e32 v130, v131, v130
	v_cvt_f32_u32_e32 v130, v130
	v_sub_u32_e32 v131, 32, v132
	v_cndmask_b32_e32 v177, v133, v135, vcc
	v_pk_mul_f32 v[124:125], v[88:89], v[176:177]
	v_ldexp_f32 v131, v130, v131
	v_ffbh_u32_e32 v130, v129
	v_min_u32_e32 v130, 32, v130
	v_lshlrev_b64 v[128:129], v130, v[128:129]
	v_min_u32_e32 v128, 1, v128
	v_or_b32_e32 v128, v129, v128
	v_cvt_f32_u32_e32 v128, v128
	v_sub_u32_e32 v129, 32, v130
	v_pk_mul_f32 v[134:135], v[116:117], v[166:167]
	v_pk_mul_f32 v[132:133], v[112:113], v[188:189]
	v_ldexp_f32 v130, v128, v129
	v_pk_mul_f32 v[128:129], v[130:131], s[34:35] op_sel_hi:[1,0]
	v_pk_mul_f32 v[116:117], v[80:81], v[176:177]
	v_pk_fma_f32 v[128:129], v[128:129], s[2:3], v[168:169] op_sel_hi:[1,0,0]
	v_pk_mul_f32 v[88:89], v[104:105], v[188:189]
	v_mul_f32_e32 v130, 0x4b800000, v128
	v_cmp_gt_f32_e64 s[0:1], s89, v128
	v_cmp_gt_f32_e32 vcc, s89, v129
	v_pk_mul_f32 v[112:113], v[76:77], v[142:143]
	v_cndmask_b32_e64 v128, v128, v130, s[0:1]
	v_mul_f32_e32 v130, 0x4b800000, v129
	v_cndmask_b32_e32 v129, v129, v130, vcc
	v_rsq_f32_e32 v128, v128
	v_rsq_f32_e32 v129, v129
	v_pk_mul_f32 v[76:77], v[100:101], v[166:167]
	v_pk_mul_f32 v[104:105], v[68:69], v[142:143]
	v_pk_mul_f32 v[24:25], v[24:25], v[176:177]
	v_pk_mul_f32 v[130:131], v[128:129], s[30:31] op_sel_hi:[1,0]
	v_pk_mul_f32 v[16:17], v[16:17], v[176:177]
	v_cndmask_b32_e32 v129, v129, v131, vcc
	v_cndmask_b32_e64 v128, v128, v130, s[0:1]
	s_mov_b64 s[0:1], -1
	v_pk_mul_f32 v[130:131], v[92:93], v[142:143]
	v_pk_mul_f32 v[92:93], v[108:109], v[166:167]
	v_pk_mul_f32 v[108:109], v[72:73], v[176:177]
	v_pk_mul_f32 v[72:73], v[96:97], v[188:189]
	v_pk_mul_f32 v[96:97], v[64:65], v[176:177]
	v_pk_mul_f32 v[8:9], v[8:9], v[176:177]
	v_pk_mul_f32 v[0:1], v[0:1], v[176:177]
	s_cbranch_scc1 .LBB0_354
	v_lshl_add_u32 v68, s10, 8, v193
	v_ashrrev_i32_e32 v69, 31, v68
	v_pk_mul_f32 v[64:65], v[126:127], v[162:163]
	v_cvt_pk_bf16_f32 v80, v140, v141
	s_lshl_b64 s[0:1], s[50:51], 1
	v_cvt_pk_bf16_f32 v81, v64, v65
	v_lshlrev_b64 v[64:65], 13, v[68:69]
	v_lshl_add_u64 v[64:65], s[44:45], 0, v[64:65]
	v_lshl_add_u64 v[64:65], v[64:65], 0, s[0:1]
	v_lshl_add_u64 v[64:65], v[64:65], 0, v[144:145]
	v_mov_b32_e32 v161, v145
	v_lshl_add_u64 v[64:65], v[64:65], 0, v[160:161]
	global_store_dwordx2 v[64:65], v[80:81], off
	v_pk_mul_f32 v[80:81], v[122:123], v[164:165]
	v_cvt_pk_bf16_f32 v84, v138, v139
	s_nop 0
	v_cvt_pk_bf16_f32 v85, v80, v81
	v_pk_mul_f32 v[80:81], v[94:95], v[136:137]
	global_store_dwordx2 v[64:65], v[84:85], off offset:16
	v_cvt_pk_bf16_f32 v84, v130, v131
	v_cvt_pk_bf16_f32 v85, v80, v81
	v_pk_mul_f32 v[80:81], v[90:91], v[128:129]
	global_store_dwordx2 v[64:65], v[84:85], off offset:256
	v_cvt_pk_bf16_f32 v84, v124, v125
	v_cvt_pk_bf16_f32 v85, v80, v81
	v_or_b32_e32 v80, 16, v68
	v_ashrrev_i32_e32 v81, 31, v80
	v_lshlrev_b64 v[80:81], 13, v[80:81]
	v_lshl_add_u64 v[80:81], s[44:45], 0, v[80:81]
	v_lshl_add_u64 v[80:81], v[80:81], 0, s[0:1]
	v_lshl_add_u64 v[80:81], v[80:81], 0, v[144:145]
	global_store_dwordx2 v[64:65], v[84:85], off offset:272
	v_pk_mul_f32 v[84:85], v[118:119], v[162:163]
	v_cvt_pk_bf16_f32 v100, v134, v135
	v_lshl_add_u64 v[80:81], v[80:81], 0, v[160:161]
	v_cvt_pk_bf16_f32 v101, v84, v85
	global_store_dwordx2 v[80:81], v[100:101], off
	v_pk_mul_f32 v[84:85], v[114:115], v[164:165]
	v_cvt_pk_bf16_f32 v100, v132, v133
	s_nop 0
	v_cvt_pk_bf16_f32 v101, v84, v85
	global_store_dwordx2 v[80:81], v[100:101], off offset:16
	v_pk_mul_f32 v[84:85], v[86:87], v[136:137]
	v_cvt_pk_bf16_f32 v100, v120, v121
	s_nop 0
	v_cvt_pk_bf16_f32 v101, v84, v85
	global_store_dwordx2 v[80:81], v[100:101], off offset:256
	v_pk_mul_f32 v[84:85], v[82:83], v[128:129]
	v_cvt_pk_bf16_f32 v100, v116, v117
	s_nop 0
	v_cvt_pk_bf16_f32 v101, v84, v85
	global_store_dwordx2 v[80:81], v[100:101], off offset:272
	v_or_b32_e32 v80, 32, v68
	v_ashrrev_i32_e32 v81, 31, v80
	v_lshlrev_b64 v[80:81], 13, v[80:81]
	v_lshl_add_u64 v[80:81], s[44:45], 0, v[80:81]
	v_or_b32_e32 v68, 48, v68
	v_lshl_add_u64 v[80:81], v[80:81], 0, s[0:1]
	v_ashrrev_i32_e32 v69, 31, v68
	v_pk_mul_f32 v[84:85], v[110:111], v[162:163]
	v_lshl_add_u64 v[80:81], v[80:81], 0, v[144:145]
	v_lshlrev_b64 v[68:69], 13, v[68:69]
	v_cvt_pk_bf16_f32 v100, v92, v93
	v_cvt_pk_bf16_f32 v101, v84, v85
	v_lshl_add_u64 v[80:81], v[80:81], 0, v[160:161]
	v_pk_mul_f32 v[84:85], v[106:107], v[164:165]
	v_lshl_add_u64 v[68:69], s[44:45], 0, v[68:69]
	global_store_dwordx2 v[80:81], v[100:101], off
	v_cvt_pk_bf16_f32 v100, v88, v89
	v_cvt_pk_bf16_f32 v101, v84, v85
	v_pk_mul_f32 v[84:85], v[78:79], v[136:137]
	v_lshl_add_u64 v[68:69], v[68:69], 0, s[0:1]
	global_store_dwordx2 v[80:81], v[100:101], off offset:16
	v_cvt_pk_bf16_f32 v100, v112, v113
	v_cvt_pk_bf16_f32 v101, v84, v85
	v_pk_mul_f32 v[84:85], v[74:75], v[128:129]
	v_lshl_add_u64 v[68:69], v[68:69], 0, v[144:145]
	global_store_dwordx2 v[80:81], v[100:101], off offset:256
	v_cvt_pk_bf16_f32 v100, v108, v109
	v_cvt_pk_bf16_f32 v101, v84, v85
	global_store_dwordx2 v[80:81], v[100:101], off offset:272
	v_cvt_pk_bf16_f32 v84, v76, v77
	v_lshl_add_u64 v[68:69], v[68:69], 0, v[160:161]
	v_pk_mul_f32 v[80:81], v[102:103], v[162:163]
	s_mov_b64 s[0:1], 0x100000
	v_cvt_pk_bf16_f32 v85, v80, v81
	global_store_dwordx2 v[68:69], v[84:85], off
	v_cvt_pk_bf16_f32 v84, v72, v73
	v_pk_mul_f32 v[80:81], v[98:99], v[164:165]
	s_nop 0
	v_cvt_pk_bf16_f32 v85, v80, v81
	global_store_dwordx2 v[68:69], v[84:85], off offset:16
	v_cvt_pk_bf16_f32 v84, v104, v105
	v_pk_mul_f32 v[80:81], v[70:71], v[136:137]
	s_nop 0
	v_cvt_pk_bf16_f32 v85, v80, v81
	global_store_dwordx2 v[68:69], v[84:85], off offset:256
	v_cvt_pk_bf16_f32 v84, v96, v97
	v_pk_mul_f32 v[80:81], v[66:67], v[128:129]
	s_nop 0
	v_cvt_pk_bf16_f32 v85, v80, v81
	global_store_dwordx2 v[68:69], v[84:85], off offset:272
	v_add_co_u32_e32 v84, vcc, s29, v64
	v_pk_mul_f32 v[68:69], v[62:63], v[162:163]
	s_nop 0
	v_addc_co_u32_e32 v85, vcc, 0, v65, vcc
	v_cvt_pk_bf16_f32 v80, v60, v61
	v_cvt_pk_bf16_f32 v81, v68, v69
	v_lshl_add_u64 v[68:69], v[64:65], 0, s[0:1]
	global_store_dwordx2 v[84:85], v[80:81], off
	v_cvt_pk_bf16_f32 v84, v56, v57
	v_pk_mul_f32 v[80:81], v[58:59], v[164:165]
	s_mov_b64 s[0:1], 0x120000
	v_cvt_pk_bf16_f32 v85, v80, v81
	global_store_dwordx2 v[68:69], v[84:85], off offset:16
	v_cvt_pk_bf16_f32 v84, v28, v29
	v_pk_mul_f32 v[80:81], v[30:31], v[136:137]
	s_nop 0
	v_cvt_pk_bf16_f32 v85, v80, v81
	global_store_dwordx2 v[68:69], v[84:85], off offset:256
	v_cvt_pk_bf16_f32 v84, v24, v25
	v_pk_mul_f32 v[80:81], v[26:27], v[128:129]
	s_nop 0
	v_cvt_pk_bf16_f32 v85, v80, v81
	global_store_dwordx2 v[68:69], v[84:85], off offset:272
	v_add_co_u32_e32 v84, vcc, s49, v64
	v_pk_mul_f32 v[68:69], v[54:55], v[162:163]
	v_cvt_pk_bf16_f32 v80, v52, v53
	s_nop 0
	v_addc_co_u32_e32 v85, vcc, 0, v65, vcc
	v_cvt_pk_bf16_f32 v81, v68, v69
	v_lshl_add_u64 v[68:69], v[64:65], 0, s[0:1]
	global_store_dwordx2 v[84:85], v[80:81], off
	v_pk_mul_f32 v[80:81], v[50:51], v[164:165]
	v_cvt_pk_bf16_f32 v84, v48, v49
	s_mov_b64 s[0:1], 0x140000
	v_cvt_pk_bf16_f32 v85, v80, v81
	global_store_dwordx2 v[68:69], v[84:85], off offset:16
	v_pk_mul_f32 v[80:81], v[22:23], v[136:137]
	v_cvt_pk_bf16_f32 v84, v20, v21
	s_nop 0
	v_cvt_pk_bf16_f32 v85, v80, v81
	global_store_dwordx2 v[68:69], v[84:85], off offset:256
	v_pk_mul_f32 v[80:81], v[18:19], v[128:129]
	v_cvt_pk_bf16_f32 v84, v16, v17
	s_nop 0
	v_cvt_pk_bf16_f32 v85, v80, v81
	global_store_dwordx2 v[68:69], v[84:85], off offset:272
	v_pk_mul_f32 v[68:69], v[46:47], v[162:163]
	v_cvt_pk_bf16_f32 v80, v44, v45
	s_nop 0
	v_cvt_pk_bf16_f32 v81, v68, v69
	v_lshl_add_u64 v[68:69], v[64:65], 0, s[0:1]
	s_mov_b32 s0, 0x140000
	v_add_co_u32_e32 v84, vcc, s0, v64
	s_mov_b64 s[0:1], 0x160000
	s_nop 0
	v_addc_co_u32_e32 v85, vcc, 0, v65, vcc
	global_store_dwordx2 v[84:85], v[80:81], off
	v_pk_mul_f32 v[80:81], v[42:43], v[164:165]
	v_cvt_pk_bf16_f32 v84, v40, v41
	s_nop 0
	v_cvt_pk_bf16_f32 v85, v80, v81
	global_store_dwordx2 v[68:69], v[84:85], off offset:16
	v_pk_mul_f32 v[80:81], v[14:15], v[136:137]
	v_cvt_pk_bf16_f32 v84, v12, v13
	s_nop 0
	v_cvt_pk_bf16_f32 v85, v80, v81
	global_store_dwordx2 v[68:69], v[84:85], off offset:256
	v_pk_mul_f32 v[80:81], v[10:11], v[128:129]
	v_cvt_pk_bf16_f32 v84, v8, v9
	s_nop 0
	v_cvt_pk_bf16_f32 v85, v80, v81
	global_store_dwordx2 v[68:69], v[84:85], off offset:272
	v_pk_mul_f32 v[68:69], v[38:39], v[162:163]
	v_cvt_pk_bf16_f32 v80, v36, v37
	s_nop 0
	v_cvt_pk_bf16_f32 v81, v68, v69
	v_lshl_add_u64 v[68:69], v[64:65], 0, s[0:1]
	s_mov_b32 s0, 0x160000
	v_add_co_u32_e32 v64, vcc, s0, v64
	s_mov_b64 s[0:1], 0
	s_nop 0
	v_addc_co_u32_e32 v65, vcc, 0, v65, vcc
	global_store_dwordx2 v[64:65], v[80:81], off
	v_pk_mul_f32 v[64:65], v[34:35], v[164:165]
	v_cvt_pk_bf16_f32 v80, v32, v33
	s_nop 0
	v_cvt_pk_bf16_f32 v81, v64, v65
	global_store_dwordx2 v[68:69], v[80:81], off offset:16
	v_pk_mul_f32 v[64:65], v[6:7], v[136:137]
	v_cvt_pk_bf16_f32 v80, v4, v5
	s_nop 0
	v_cvt_pk_bf16_f32 v81, v64, v65
	global_store_dwordx2 v[68:69], v[80:81], off offset:256
	v_pk_mul_f32 v[64:65], v[2:3], v[128:129]
	v_cvt_pk_bf16_f32 v80, v0, v1
	s_nop 0
	v_cvt_pk_bf16_f32 v81, v64, v65
	s_nop 1
	global_store_dwordx2 v[68:69], v[80:81], off offset:272
